# setprio polarity swapped: loader segments at prio 1, MFMA segments at prio 0
# baseline (speedup 1.0000x reference)
; #define PG8_STAGE(bufoff, gbase, voff) do { _Pragma("unroll") for (int _i = 0; _i < 2; ++_i) \
;         __builtin_amdgcn_global_load_lds((const unsigned*)((const char*)(gbase) + (voff)[_i]), (LAS unsigned*)(lds + (bufoff) + ldsw + _i * 8192), 16, 0, 0); } while (0)
; #define PG8_LDA(dst, b, h) do { _Pragma("unroll") for (int m = 0; m < 4; ++m) _Pragma("unroll") for (int k = 0; k < 2; ++k) dst[m][k] = *(const LAS h8*)(lds + PG8_SA(b, h) + aoff + m * 2048 + k * 1024); } while (0)
; #define PG8_LDB(dst, b, h) do { _Pragma("unroll") for (int n = 0; n < 2; ++n) _Pragma("unroll") for (int k = 0; k < 2; ++k) dst[n][k] = *(const LAS h8*)(lds + PG8_SB(b, h) + boff + n * 2048 + k * 1024); } while (0)
; #define PG8_WAIT_L(n) asm volatile("s_waitcnt lgkmcnt(" #n ")" ::: "memory")
; #define PG8_BAR __builtin_amdgcn_s_barrier()
; #define PG8_SCHED __builtin_amdgcn_sched_barrier(0)
; template <class Epi>
; __device__ __forceinline__ void gemm_phase(LAS unsigned char* lds, const Gemm g, const StaticOrder& S, const Epi& E, const int tid) {
;     ...
;         for (int t = 0; t < nt; t += 2) {
;             const bool last = (t == nt - 2);
;             const char* a1 = cA + (size_t)(t + 1) * kstep;
;             const char* a2 = last ? nA : cA + (size_t)(t + 2) * kstep; const char* b2 = last ? nB : cB + (size_t)(t + 2) * kstep;
;             const char* a3 = a2 + kstep; const char* b3 = b2 + kstep;
;             if constexpr (Epi::HAS_MID) { if (t == (nt >> 1)) E.mid(acc, cur, wr, wc, fr, fq); }
;             PG8_LDB(B0, 0, 0); PG8_SCHED; PG8_LDA(At, 0, 0); PG8_STAGE(PG8_SA(1, 1), a1 + hstep, voffA);
;             PG8_WAIT_L(8); PG8_BAR; PG8_WAIT_L(0); PG8_MMA(0, 0, At, B0); PG8_BAR; PG8_SCHED;
;             PG8_LDB(B1, 0, 1); PG8_STAGE(PG8_SB(0, 0), b2, voffB);
;             PG8_BAR; PG8_WAIT_L(0); PG8_MMA(0, 1, At, B1); PG8_BAR;
.LBB0_332:
	s_add_u32 s18, s14, 0xfff80080
	s_addc_u32 s19, s15, -1
	s_add_i32 s55, 0, 0x10000
	v_add_u32_e32 v157, s55, v140
	ds_read_b128 v[144:147], v157
	ds_read_b128 v[162:165], v157 offset:1024
	ds_read_b128 v[166:169], v157 offset:2048
	ds_read_b128 v[170:173], v157 offset:3072
	s_cmp_eq_u32 s54, 28
	s_cselect_b32 s23, s9, s19
	s_cselect_b32 s22, s50, s18
	s_cselect_b32 s19, s1, s53
	s_cselect_b32 s18, s51, s52
	v_lshl_add_u64 v[178:179], s[14:15], 0, v[136:137]
	s_add_i32 m0, s39, 0xc000
	ds_read_b128 v[174:177], v143
	ds_read_b128 v[190:193], v143 offset:1024
	ds_read_b128 v[194:197], v143 offset:2048
	ds_read_b128 v[198:201], v143 offset:3072
	ds_read_b128 v[202:205], v143 offset:4096
	ds_read_b128 v[206:209], v143 offset:5120
	ds_read_b128 v[210:213], v143 offset:6144
	ds_read_b128 v[214:217], v143 offset:7168
	global_load_lds_dwordx4 v[178:179], off
	v_lshl_add_u64 v[178:179], s[14:15], 0, v[138:139]
	s_add_i32 m0, s39, 0xe000
	s_nop 0
	global_load_lds_dwordx4 v[178:179], off
	s_waitcnt lgkmcnt(8)
	s_barrier
	s_waitcnt lgkmcnt(0)
	s_setprio 0
	s_waitcnt lgkmcnt(0)
	v_mfma_f32_16x16x32_bf16 v[124:127], v[144:147], v[174:177], v[124:127]
	v_mfma_f32_16x16x32_bf16 v[128:131], v[166:169], v[174:177], v[128:131]
	v_mfma_f32_16x16x32_bf16 v[108:111], v[144:147], v[194:197], v[108:111]
	v_mfma_f32_16x16x32_bf16 v[112:115], v[166:169], v[194:197], v[112:115]
	v_mfma_f32_16x16x32_bf16 v[92:95], v[144:147], v[202:205], v[92:95]
	v_mfma_f32_16x16x32_bf16 v[96:99], v[166:169], v[202:205], v[96:99]
	v_mfma_f32_16x16x32_bf16 v[76:79], v[144:147], v[210:213], v[76:79]
	v_mfma_f32_16x16x32_bf16 v[80:83], v[166:169], v[210:213], v[80:83]
	v_mfma_f32_16x16x32_bf16 v[124:127], v[162:165], v[190:193], v[124:127]
	v_mfma_f32_16x16x32_bf16 v[128:131], v[170:173], v[190:193], v[128:131]
	v_mfma_f32_16x16x32_bf16 v[108:111], v[162:165], v[198:201], v[108:111]
	v_mfma_f32_16x16x32_bf16 v[112:115], v[170:173], v[198:201], v[112:115]
	v_mfma_f32_16x16x32_bf16 v[92:95], v[162:165], v[206:209], v[92:95]
	v_mfma_f32_16x16x32_bf16 v[96:99], v[170:173], v[206:209], v[96:99]
	v_mfma_f32_16x16x32_bf16 v[76:79], v[162:165], v[214:217], v[76:79]
	v_mfma_f32_16x16x32_bf16 v[80:83], v[170:173], v[214:217], v[80:83]
	s_setprio 1
	s_barrier
	s_add_i32 s58, 0, 0x14000
	s_add_i32 s55, s55, s38
	v_add_u32_e32 v157, s58, v140
	v_lshl_add_u64 v[178:179], s[18:19], 0, v[2:3]
	s_mov_b32 m0, s55
	ds_read_b128 v[218:221], v157
	ds_read_b128 v[222:225], v157 offset:1024
	ds_read_b128 v[226:229], v157 offset:2048
	ds_read_b128 v[230:233], v157 offset:3072
	global_load_lds_dwordx4 v[178:179], off
	v_lshl_add_u64 v[234:235], s[18:19], 0, v[0:1]
	s_add_i32 m0, s55, 0x2000
	s_nop 0
	global_load_lds_dwordx4 v[234:235], off
	s_barrier
	s_waitcnt lgkmcnt(0)
	s_setprio 0
	s_waitcnt lgkmcnt(0)
	v_mfma_f32_16x16x32_bf16 v[116:119], v[218:221], v[174:177], v[116:119]
	v_mfma_f32_16x16x32_bf16 v[120:123], v[226:229], v[174:177], v[120:123]
	v_mfma_f32_16x16x32_bf16 v[100:103], v[218:221], v[194:197], v[100:103]
	v_mfma_f32_16x16x32_bf16 v[104:107], v[226:229], v[194:197], v[104:107]
	v_mfma_f32_16x16x32_bf16 v[84:87], v[218:221], v[202:205], v[84:87]
	v_mfma_f32_16x16x32_bf16 v[88:91], v[226:229], v[202:205], v[88:91]
	v_mfma_f32_16x16x32_bf16 v[68:71], v[218:221], v[210:213], v[68:71]
	v_mfma_f32_16x16x32_bf16 v[72:75], v[226:229], v[210:213], v[72:75]
	v_mfma_f32_16x16x32_bf16 v[116:119], v[222:225], v[190:193], v[116:119]
	v_mfma_f32_16x16x32_bf16 v[120:123], v[230:233], v[190:193], v[120:123]
	v_mfma_f32_16x16x32_bf16 v[100:103], v[222:225], v[198:201], v[100:103]
	v_mfma_f32_16x16x32_bf16 v[104:107], v[230:233], v[198:201], v[104:107]
	v_mfma_f32_16x16x32_bf16 v[84:87], v[222:225], v[206:209], v[84:87]
	v_mfma_f32_16x16x32_bf16 v[88:91], v[230:233], v[206:209], v[88:91]
	v_mfma_f32_16x16x32_bf16 v[68:71], v[222:225], v[214:217], v[68:71]
	v_mfma_f32_16x16x32_bf16 v[72:75], v[230:233], v[214:217], v[72:75]
	s_setprio 1
	s_mov_b32 m0, s39
	v_lshl_add_u64 v[236:237], s[22:23], 0, v[134:135]
	s_barrier
	ds_read_b128 v[174:177], v143 offset:16384
	ds_read_b128 v[190:193], v143 offset:17408
	ds_read_b128 v[194:197], v143 offset:18432
	ds_read_b128 v[198:201], v143 offset:19456
	ds_read_b128 v[202:205], v143 offset:20480
	ds_read_b128 v[206:209], v143 offset:21504
	ds_read_b128 v[210:213], v143 offset:22528
	ds_read_b128 v[214:217], v143 offset:23552
	global_load_lds_dwordx4 v[236:237], off
	v_lshl_add_u64 v[238:239], s[22:23], 0, v[132:133]
	s_mov_b32 m0, s40
	s_nop 0
	global_load_lds_dwordx4 v[238:239], off
	s_barrier
	s_waitcnt lgkmcnt(0)
	s_setprio 0
	s_waitcnt lgkmcnt(0)
	v_mfma_f32_16x16x32_bf16 v[60:63], v[144:147], v[174:177], v[60:63]
	v_mfma_f32_16x16x32_bf16 v[64:67], v[166:169], v[174:177], v[64:67]
	v_mfma_f32_16x16x32_bf16 v[44:47], v[144:147], v[194:197], v[44:47]
	v_mfma_f32_16x16x32_bf16 v[48:51], v[166:169], v[194:197], v[48:51]
	v_mfma_f32_16x16x32_bf16 v[28:31], v[144:147], v[202:205], v[28:31]
	v_mfma_f32_16x16x32_bf16 v[32:35], v[166:169], v[202:205], v[32:35]
	v_mfma_f32_16x16x32_bf16 v[12:15], v[144:147], v[210:213], v[12:15]
	v_mfma_f32_16x16x32_bf16 v[16:19], v[166:169], v[210:213], v[16:19]
	v_mfma_f32_16x16x32_bf16 v[60:63], v[162:165], v[190:193], v[60:63]
	v_mfma_f32_16x16x32_bf16 v[64:67], v[170:173], v[190:193], v[64:67]
	v_mfma_f32_16x16x32_bf16 v[44:47], v[162:165], v[198:201], v[44:47]
	v_mfma_f32_16x16x32_bf16 v[48:51], v[170:173], v[198:201], v[48:51]
	v_mfma_f32_16x16x32_bf16 v[28:31], v[162:165], v[206:209], v[28:31]
	v_mfma_f32_16x16x32_bf16 v[32:35], v[170:173], v[206:209], v[32:35]
	v_mfma_f32_16x16x32_bf16 v[12:15], v[162:165], v[214:217], v[12:15]
	v_mfma_f32_16x16x32_bf16 v[16:19], v[170:173], v[214:217], v[16:19]
	s_setprio 1
	s_barrier
; #define PG8_STAGE(bufoff, gbase, voff) do { _Pragma("unroll") for (int _i = 0; _i < 2; ++_i) \
;         __builtin_amdgcn_global_load_lds((const unsigned*)((const char*)(gbase) + (voff)[_i]), (LAS unsigned*)(lds + (bufoff) + ldsw + _i * 8192), 16, 0, 0); } while (0)
; #define PG8_LDA(dst, b, h) do { _Pragma("unroll") for (int m = 0; m < 4; ++m) _Pragma("unroll") for (int k = 0; k < 2; ++k) dst[m][k] = *(const LAS h8*)(lds + PG8_SA(b, h) + aoff + m * 2048 + k * 1024); } while (0)
; #define PG8_LDB(dst, b, h) do { _Pragma("unroll") for (int n = 0; n < 2; ++n) _Pragma("unroll") for (int k = 0; k < 2; ++k) dst[n][k] = *(const LAS h8*)(lds + PG8_SB(b, h) + boff + n * 2048 + k * 1024); } while (0)
; #define PG8_WAIT_V(n) asm volatile("s_waitcnt vmcnt(" #n ")" ::: "memory")
; #define PG8_WAIT_L(n) asm volatile("s_waitcnt lgkmcnt(" #n ")" ::: "memory")
; #define PG8_BAR __builtin_amdgcn_s_barrier()
; #define PG8_SCHED __builtin_amdgcn_sched_barrier(0)
; template <class Epi>
; __device__ __forceinline__ void gemm_phase(LAS unsigned char* lds, const Gemm g, const StaticOrder& S, const Epi& E, const int tid) {
;     ...
;             PG8_STAGE(PG8_SB(0, 1), b2 + hstepB, voffB);
;             PG8_WAIT_V(6); PG8_BAR; PG8_MMA(1, 1, At, B1); PG8_BAR;
;             PG8_LDB(B0, 1, 0); PG8_SCHED; PG8_LDA(At, 1, 0); PG8_STAGE(PG8_SA(0, 1), a2 + hstep, voffA);
;             PG8_WAIT_L(8); PG8_BAR; PG8_WAIT_L(0); PG8_MMA(0, 0, At, B0); PG8_BAR; PG8_SCHED;
;             PG8_LDB(B1, 1, 1); PG8_STAGE(PG8_SB(1, 0), b3, voffB);
;             PG8_BAR; PG8_WAIT_L(0); PG8_MMA(0, 1, At, B1); PG8_BAR;
;             PG8_LDA(At, 1, 1); PG8_STAGE(PG8_SA(1, 0), a3, voffA);
;             PG8_BAR; PG8_WAIT_L(0); PG8_MMA(1, 0, At, B0); PG8_BAR; PG8_SCHED;
;             PG8_STAGE(PG8_SB(1, 1), b3 + hstepB, voffB);
	s_add_u32 s56, s18, 0x20000
	s_addc_u32 s57, s19, 0
	s_add_i32 s55, s58, s38
	v_lshl_add_u64 v[144:145], s[56:57], 0, v[2:3]
	s_mov_b32 m0, s55
	s_nop 0
	global_load_lds_dwordx4 v[144:145], off
	v_lshl_add_u64 v[144:145], s[56:57], 0, v[0:1]
	s_add_i32 m0, s55, 0x2000
	s_nop 0
	global_load_lds_dwordx4 v[144:145], off
	s_waitcnt vmcnt(6)
	s_barrier
	s_setprio 0
	v_mfma_f32_16x16x32_bf16 v[52:55], v[218:221], v[174:177], v[52:55]
	v_mfma_f32_16x16x32_bf16 v[56:59], v[226:229], v[174:177], v[56:59]
	v_mfma_f32_16x16x32_bf16 v[36:39], v[218:221], v[194:197], v[36:39]
	v_mfma_f32_16x16x32_bf16 v[40:43], v[226:229], v[194:197], v[40:43]
	v_mfma_f32_16x16x32_bf16 v[20:23], v[218:221], v[202:205], v[20:23]
	v_mfma_f32_16x16x32_bf16 v[24:27], v[226:229], v[202:205], v[24:27]
	v_mfma_f32_16x16x32_bf16 v[8:11], v[218:221], v[210:213], v[8:11]
	v_mfma_f32_16x16x32_bf16 v[4:7], v[226:229], v[210:213], v[4:7]
	v_mfma_f32_16x16x32_bf16 v[52:55], v[222:225], v[190:193], v[52:55]
	v_mfma_f32_16x16x32_bf16 v[56:59], v[230:233], v[190:193], v[56:59]
	v_mfma_f32_16x16x32_bf16 v[36:39], v[222:225], v[198:201], v[36:39]
	v_mfma_f32_16x16x32_bf16 v[40:43], v[230:233], v[198:201], v[40:43]
	v_mfma_f32_16x16x32_bf16 v[20:23], v[222:225], v[206:209], v[20:23]
	v_mfma_f32_16x16x32_bf16 v[24:27], v[230:233], v[206:209], v[24:27]
	v_mfma_f32_16x16x32_bf16 v[8:11], v[222:225], v[214:217], v[8:11]
	v_mfma_f32_16x16x32_bf16 v[4:7], v[230:233], v[214:217], v[4:7]
	s_setprio 1
	s_add_i32 s55, 0, 0x18000
	v_add_u32_e32 v157, s55, v140
	s_barrier
	ds_read_b128 v[144:147], v157
	ds_read_b128 v[162:165], v157 offset:1024
	ds_read_b128 v[166:169], v157 offset:2048
	ds_read_b128 v[170:173], v157 offset:3072
	s_add_u32 s22, s22, 0x80000
	s_addc_u32 s23, s23, 0
	s_mov_b32 m0, s41
	v_lshl_add_u64 v[218:219], s[22:23], 0, v[134:135]
	ds_read_b128 v[174:177], v143 offset:32768
	ds_read_b128 v[190:193], v143 offset:33792
	ds_read_b128 v[194:197], v143 offset:34816
	ds_read_b128 v[198:201], v143 offset:35840
	ds_read_b128 v[202:205], v143 offset:36864
	ds_read_b128 v[206:209], v143 offset:37888
	ds_read_b128 v[210:213], v143 offset:38912
	ds_read_b128 v[214:217], v143 offset:39936
	global_load_lds_dwordx4 v[218:219], off
	v_lshl_add_u64 v[218:219], s[22:23], 0, v[132:133]
	s_mov_b32 m0, s42
	s_nop 0
	global_load_lds_dwordx4 v[218:219], off
	s_waitcnt lgkmcnt(8)
	s_barrier
	s_waitcnt lgkmcnt(0)
	s_setprio 0
	s_waitcnt lgkmcnt(0)
	v_mfma_f32_16x16x32_bf16 v[124:127], v[144:147], v[174:177], v[124:127]
	v_mfma_f32_16x16x32_bf16 v[128:131], v[166:169], v[174:177], v[128:131]
	v_mfma_f32_16x16x32_bf16 v[108:111], v[144:147], v[194:197], v[108:111]
	v_mfma_f32_16x16x32_bf16 v[112:115], v[166:169], v[194:197], v[112:115]
	v_mfma_f32_16x16x32_bf16 v[92:95], v[144:147], v[202:205], v[92:95]
	v_mfma_f32_16x16x32_bf16 v[96:99], v[166:169], v[202:205], v[96:99]
	v_mfma_f32_16x16x32_bf16 v[76:79], v[144:147], v[210:213], v[76:79]
	v_mfma_f32_16x16x32_bf16 v[80:83], v[166:169], v[210:213], v[80:83]
	v_mfma_f32_16x16x32_bf16 v[124:127], v[162:165], v[190:193], v[124:127]
	v_mfma_f32_16x16x32_bf16 v[128:131], v[170:173], v[190:193], v[128:131]
	v_mfma_f32_16x16x32_bf16 v[108:111], v[162:165], v[198:201], v[108:111]
	v_mfma_f32_16x16x32_bf16 v[112:115], v[170:173], v[198:201], v[112:115]
	v_mfma_f32_16x16x32_bf16 v[92:95], v[162:165], v[206:209], v[92:95]
	v_mfma_f32_16x16x32_bf16 v[96:99], v[170:173], v[206:209], v[96:99]
	v_mfma_f32_16x16x32_bf16 v[76:79], v[162:165], v[214:217], v[76:79]
	v_mfma_f32_16x16x32_bf16 v[80:83], v[170:173], v[214:217], v[80:83]
	s_setprio 1
	s_barrier
	s_add_i32 s22, 0, 0x1c000
	s_add_i32 s23, s55, s38
	v_add_u32_e32 v157, s22, v140
	v_lshl_add_u64 v[178:179], v[178:179], 0, s[30:31]
	s_mov_b32 m0, s23
	ds_read_b128 v[218:221], v157
	ds_read_b128 v[222:225], v157 offset:1024
	ds_read_b128 v[226:229], v157 offset:2048
	ds_read_b128 v[230:233], v157 offset:3072
	global_load_lds_dwordx4 v[178:179], off
	v_lshl_add_u64 v[178:179], v[234:235], 0, s[30:31]
	s_add_i32 m0, s23, 0x2000
	s_nop 0
	global_load_lds_dwordx4 v[178:179], off
	s_barrier
	s_waitcnt lgkmcnt(0)
	s_setprio 0
	s_waitcnt lgkmcnt(0)
	v_mfma_f32_16x16x32_bf16 v[116:119], v[218:221], v[174:177], v[116:119]
	v_mfma_f32_16x16x32_bf16 v[120:123], v[226:229], v[174:177], v[120:123]
	v_mfma_f32_16x16x32_bf16 v[100:103], v[218:221], v[194:197], v[100:103]
	v_mfma_f32_16x16x32_bf16 v[104:107], v[226:229], v[194:197], v[104:107]
	v_mfma_f32_16x16x32_bf16 v[84:87], v[218:221], v[202:205], v[84:87]
	v_mfma_f32_16x16x32_bf16 v[88:91], v[226:229], v[202:205], v[88:91]
	v_mfma_f32_16x16x32_bf16 v[68:71], v[218:221], v[210:213], v[68:71]
	v_mfma_f32_16x16x32_bf16 v[72:75], v[226:229], v[210:213], v[72:75]
	v_mfma_f32_16x16x32_bf16 v[116:119], v[222:225], v[190:193], v[116:119]
	v_mfma_f32_16x16x32_bf16 v[120:123], v[230:233], v[190:193], v[120:123]
	v_mfma_f32_16x16x32_bf16 v[100:103], v[222:225], v[198:201], v[100:103]
	v_mfma_f32_16x16x32_bf16 v[104:107], v[230:233], v[198:201], v[104:107]
	v_mfma_f32_16x16x32_bf16 v[84:87], v[222:225], v[206:209], v[84:87]
	v_mfma_f32_16x16x32_bf16 v[88:91], v[230:233], v[206:209], v[88:91]
	v_mfma_f32_16x16x32_bf16 v[68:71], v[222:225], v[214:217], v[68:71]
	v_mfma_f32_16x16x32_bf16 v[72:75], v[230:233], v[214:217], v[72:75]
	s_setprio 1
	s_mov_b32 m0, s43
	v_lshl_add_u64 v[178:179], v[236:237], 0, s[30:31]
	s_barrier
	ds_read_b128 v[174:177], v143 offset:49152
	ds_read_b128 v[190:193], v143 offset:50176
	ds_read_b128 v[194:197], v143 offset:51200
	ds_read_b128 v[198:201], v143 offset:52224
	ds_read_b128 v[202:205], v143 offset:53248
	ds_read_b128 v[206:209], v143 offset:54272
	ds_read_b128 v[210:213], v143 offset:55296
	ds_read_b128 v[214:217], v143 offset:56320
	global_load_lds_dwordx4 v[178:179], off
	v_lshl_add_u64 v[178:179], v[238:239], 0, s[30:31]
	s_mov_b32 m0, s46
	s_nop 0
	global_load_lds_dwordx4 v[178:179], off
	s_barrier
; #define PG8_STAGE(bufoff, gbase, voff) do { _Pragma("unroll") for (int _i = 0; _i < 2; ++_i) \
;         __builtin_amdgcn_global_load_lds((const unsigned*)((const char*)(gbase) + (voff)[_i]), (LAS unsigned*)(lds + (bufoff) + ldsw + _i * 8192), 16, 0, 0); } while (0)
; #define PG8_LDA(dst, b, h) do { _Pragma("unroll") for (int m = 0; m < 4; ++m) _Pragma("unroll") for (int k = 0; k < 2; ++k) dst[m][k] = *(const LAS h8*)(lds + PG8_SA(b, h) + aoff + m * 2048 + k * 1024); } while (0)
; #define PG8_WAIT_V(n) asm volatile("s_waitcnt vmcnt(" #n ")" ::: "memory")
; #define PG8_WAIT_L(n) asm volatile("s_waitcnt lgkmcnt(" #n ")" ::: "memory")
; #define PG8_BAR __builtin_amdgcn_s_barrier()
; template <class Epi>
; __device__ __forceinline__ void gemm_phase(LAS unsigned char* lds, const Gemm g, const StaticOrder& S, const Epi& E, const int tid) {
;     ...
;             PG8_BAR; PG8_WAIT_L(0); PG8_MMA(0, 1, At, B1); PG8_BAR;
;             PG8_LDA(At, 1, 1); PG8_STAGE(PG8_SA(1, 0), a3, voffA);
;             PG8_BAR; PG8_WAIT_L(0); PG8_MMA(1, 0, At, B0); PG8_BAR; PG8_SCHED;
;             PG8_STAGE(PG8_SB(1, 1), b3 + hstepB, voffB);
;             PG8_WAIT_V(6); PG8_BAR; PG8_MMA(1, 1, At, B1); PG8_BAR;
;     __device__ __forceinline__ void operator()(f32x4 (&acc)[2][2][4][2], const pg8::Unit& u, int wr, int wc, int fr, int fq) const {
;         const bool hi = fr >= 8;
;         const int row0 = u.pm * 256 + wr * 64 + (fr & 7), col = u.pn * 256 + wc * 64 + fq * 8 + (hi ? 32 : 0);
; #pragma unroll
;         for (int ai = 0; ai < 2; ++ai)
; #pragma unroll
;             for (int m = 0; m < 4; ++m) {
;                 const h8 x0 = pack8(acc[ai][0][m][0], acc[ai][0][m][1]), x1 = pack8(acc[ai][1][m][0], acc[ai][1][m][1]);
;                 const i32x4 snd = hi ? __builtin_bit_cast(i32x4, x0) : __builtin_bit_cast(i32x4, x1);
;                 i32x4 rcv;
; #pragma unroll
;                 for (int d = 0; d < 4; ++d) rcv[d] = __builtin_amdgcn_update_dpp(0, snd[d], 0x128  , 0xF, 0xF, false);
;                 const h8 rv = __builtin_bit_cast(h8, rcv);
;                 const h8 vA = hi ? rv : x0;
;                 const h8 vB = hi ? x1 : rv;
;                 half_t* rowp = O + (size_t)(row0 + ai * 128 + m * 16) * NIN + col;
;                 __builtin_nontemporal_store(vA, (h8*)rowp); __builtin_nontemporal_store(vB, (h8*)(rowp + (size_t)8 * NIN)); }
	s_waitcnt lgkmcnt(0)
	s_setprio 0
	s_waitcnt lgkmcnt(0)
	v_mfma_f32_16x16x32_bf16 v[60:63], v[144:147], v[174:177], v[60:63]
	v_mfma_f32_16x16x32_bf16 v[64:67], v[166:169], v[174:177], v[64:67]
	v_mfma_f32_16x16x32_bf16 v[44:47], v[144:147], v[194:197], v[44:47]
	v_mfma_f32_16x16x32_bf16 v[48:51], v[166:169], v[194:197], v[48:51]
	v_mfma_f32_16x16x32_bf16 v[28:31], v[144:147], v[202:205], v[28:31]
	v_mfma_f32_16x16x32_bf16 v[32:35], v[166:169], v[202:205], v[32:35]
	v_mfma_f32_16x16x32_bf16 v[12:15], v[144:147], v[210:213], v[12:15]
	v_mfma_f32_16x16x32_bf16 v[16:19], v[166:169], v[210:213], v[16:19]
	v_mfma_f32_16x16x32_bf16 v[60:63], v[162:165], v[190:193], v[60:63]
	v_mfma_f32_16x16x32_bf16 v[64:67], v[170:173], v[190:193], v[64:67]
	v_mfma_f32_16x16x32_bf16 v[44:47], v[162:165], v[198:201], v[44:47]
	v_mfma_f32_16x16x32_bf16 v[48:51], v[170:173], v[198:201], v[48:51]
	v_mfma_f32_16x16x32_bf16 v[28:31], v[162:165], v[206:209], v[28:31]
	v_mfma_f32_16x16x32_bf16 v[32:35], v[170:173], v[206:209], v[32:35]
	v_mfma_f32_16x16x32_bf16 v[12:15], v[162:165], v[214:217], v[12:15]
	v_mfma_f32_16x16x32_bf16 v[16:19], v[170:173], v[214:217], v[16:19]
	s_setprio 1
	s_barrier
	s_add_u32 s18, s18, 0x20080
	s_addc_u32 s19, s19, 0
	s_add_i32 s22, s22, s38
	v_lshl_add_u64 v[144:145], s[18:19], 0, v[2:3]
	s_mov_b32 m0, s22
	s_nop 0
	global_load_lds_dwordx4 v[144:145], off
	v_lshl_add_u64 v[144:145], s[18:19], 0, v[0:1]
	s_add_i32 m0, s22, 0x2000
	s_nop 0
	global_load_lds_dwordx4 v[144:145], off
	s_waitcnt vmcnt(6)
	s_barrier
	s_setprio 0
	v_mfma_f32_16x16x32_bf16 v[52:55], v[218:221], v[174:177], v[52:55]
	v_mfma_f32_16x16x32_bf16 v[56:59], v[226:229], v[174:177], v[56:59]
	v_mfma_f32_16x16x32_bf16 v[36:39], v[218:221], v[194:197], v[36:39]
	v_mfma_f32_16x16x32_bf16 v[40:43], v[226:229], v[194:197], v[40:43]
	v_mfma_f32_16x16x32_bf16 v[20:23], v[218:221], v[202:205], v[20:23]
	v_mfma_f32_16x16x32_bf16 v[24:27], v[226:229], v[202:205], v[24:27]
	v_mfma_f32_16x16x32_bf16 v[8:11], v[218:221], v[210:213], v[8:11]
	v_mfma_f32_16x16x32_bf16 v[4:7], v[226:229], v[210:213], v[4:7]
	v_mfma_f32_16x16x32_bf16 v[52:55], v[222:225], v[190:193], v[52:55]
	v_mfma_f32_16x16x32_bf16 v[56:59], v[230:233], v[190:193], v[56:59]
	v_mfma_f32_16x16x32_bf16 v[36:39], v[222:225], v[198:201], v[36:39]
	v_mfma_f32_16x16x32_bf16 v[40:43], v[230:233], v[198:201], v[40:43]
	v_mfma_f32_16x16x32_bf16 v[20:23], v[222:225], v[206:209], v[20:23]
	v_mfma_f32_16x16x32_bf16 v[24:27], v[230:233], v[206:209], v[24:27]
	v_mfma_f32_16x16x32_bf16 v[8:11], v[222:225], v[214:217], v[8:11]
	v_mfma_f32_16x16x32_bf16 v[4:7], v[230:233], v[214:217], v[4:7]
	s_setprio 1
	s_add_i32 s54, s54, 2
	s_add_u32 s14, s14, 0x100
	s_addc_u32 s15, s15, 0
	s_add_u32 s52, s52, 0x100
	s_addc_u32 s53, s53, 0
	s_cmp_gt_u32 s54, 29
	s_barrier
	s_cbranch_scc0 .LBB0_332
	v_cvt_pk_f16_f32 v124, v124, v125
	v_cvt_pk_f16_f32 v116, v116, v117
	v_cvt_pk_f16_f32 v130, v130, v131
	v_cvt_pk_f16_f32 v131, v122, v123
	v_cvt_pk_f16_f32 v128, v128, v129
	v_cvt_pk_f16_f32 v129, v120, v121
	v_cvt_pk_f16_f32 v121, v126, v127
	v_cvt_pk_f16_f32 v118, v118, v119
	v_cndmask_b32_e64 v117, v116, v124, s[4:5]
	v_mov_b32_e32 v147, v3
	v_cndmask_b32_e64 v122, v131, v130, s[4:5]
	v_cndmask_b32_e64 v119, v118, v121, s[4:5]
	v_mov_b32_dpp v147, v117 row_ror:8 row_mask:0xf bank_mask:0xf
	v_mov_b32_e32 v117, v3
	v_mov_b32_e32 v125, v3
	v_lshl_or_b32 v144, s48, 8, v142
	v_cndmask_b32_e64 v120, v129, v128, s[4:5]
	v_mov_b32_dpp v117, v119 row_ror:8 row_mask:0xf bank_mask:0xf
	v_mov_b32_e32 v119, v3
	v_mov_b32_dpp v125, v122 row_ror:8 row_mask:0xf bank_mask:0xf
	v_lshl_add_u32 v146, s49, 8, v141
	v_ashrrev_i32_e32 v145, 31, v144
	v_mov_b32_dpp v119, v120 row_ror:8 row_mask:0xf bank_mask:0xf
	v_cndmask_b32_e64 v123, v130, v125, s[4:5]
	v_cndmask_b32_e64 v121, v121, v117, s[4:5]
	v_cndmask_b32_e64 v120, v124, v147, s[4:5]
	v_cndmask_b32_e64 v127, v125, v131, s[4:5]
	v_cndmask_b32_e64 v125, v117, v118, s[4:5]
	v_cndmask_b32_e64 v124, v147, v116, s[4:5]
	v_mov_b64_e32 v[116:117], s[36:37]
	v_cndmask_b32_e64 v122, v128, v119, s[4:5]
	v_cndmask_b32_e64 v126, v119, v129, s[4:5]
	v_mad_i64_i32 v[128:129], s[14:15], v146, s35, v[116:117]
	v_lshlrev_b64 v[118:119], 1, v[144:145]
	v_lshl_add_u64 v[128:129], v[128:129], 0, v[118:119]
	s_mov_b32 s1, 0x3c000
	global_store_dwordx4 v[128:129], v[120:123], off nt
	v_cvt_pk_f16_f32 v112, v112, v113
	v_cvt_pk_f16_f32 v104, v104, v105
	v_add_co_u32_e32 v120, vcc, s1, v128
	v_cvt_pk_f16_f32 v108, v108, v109
	s_nop 0
	v_addc_co_u32_e32 v121, vcc, 0, v129, vcc
	v_cvt_pk_f16_f32 v109, v100, v101
	global_store_dwordx4 v[120:121], v[124:127], off nt
	v_cvt_pk_f16_f32 v114, v114, v115
	v_cvt_pk_f16_f32 v106, v106, v107
	v_cndmask_b32_e64 v105, v104, v112, s[4:5]
	v_cndmask_b32_e64 v100, v109, v108, s[4:5]
	v_mov_b32_e32 v113, v3
	v_mov_b32_e32 v120, v3
	v_cndmask_b32_e64 v107, v106, v114, s[4:5]
	v_cvt_pk_f16_f32 v110, v110, v111
	v_cvt_pk_f16_f32 v111, v102, v103
	v_mov_b32_dpp v113, v100 row_ror:8 row_mask:0xf bank_mask:0xf
	v_mov_b32_dpp v120, v105 row_ror:8 row_mask:0xf bank_mask:0xf
	v_mov_b32_e32 v105, v3
	v_cndmask_b32_e64 v102, v111, v110, s[4:5]
	v_mov_b32_e32 v115, v3
	v_mov_b32_dpp v105, v107 row_ror:8 row_mask:0xf bank_mask:0xf
	v_cndmask_b32_e64 v100, v108, v113, s[4:5]
	v_or_b32_e32 v108, 16, v146
	v_mov_b32_dpp v115, v102 row_ror:8 row_mask:0xf bank_mask:0xf
	v_cndmask_b32_e64 v107, v105, v106, s[4:5]
	v_cndmask_b32_e64 v106, v120, v104, s[4:5]
	v_cndmask_b32_e64 v104, v113, v109, s[4:5]
	v_mad_i64_i32 v[108:109], s[14:15], v108, s35, v[116:117]
	v_cndmask_b32_e64 v103, v114, v105, s[4:5]
;     __device__ __forceinline__ void operator()(f32x4 (&acc)[2][2][4][2], const pg8::Unit& u, int wr, int wc, int fr, int fq) const {
;     ...
;         for (int ai = 0; ai < 2; ++ai)
; #pragma unroll
;             for (int m = 0; m < 4; ++m) {
;                 const h8 x0 = pack8(acc[ai][0][m][0], acc[ai][0][m][1]), x1 = pack8(acc[ai][1][m][0], acc[ai][1][m][1]);
;                 const i32x4 snd = hi ? __builtin_bit_cast(i32x4, x0) : __builtin_bit_cast(i32x4, x1);
;                 i32x4 rcv;
; #pragma unroll
;                 for (int d = 0; d < 4; ++d) rcv[d] = __builtin_amdgcn_update_dpp(0, snd[d], 0x128  , 0xF, 0xF, false);
;                 const h8 rv = __builtin_bit_cast(h8, rcv);
;                 const h8 vA = hi ? rv : x0;
;                 const h8 vB = hi ? x1 : rv;
;                 half_t* rowp = O + (size_t)(row0 + ai * 128 + m * 16) * NIN + col;
;                 __builtin_nontemporal_store(vA, (h8*)rowp); __builtin_nontemporal_store(vB, (h8*)(rowp + (size_t)8 * NIN)); }
	v_cndmask_b32_e64 v102, v112, v120, s[4:5]
	v_cndmask_b32_e64 v101, v110, v115, s[4:5]
	v_lshl_add_u64 v[108:109], v[108:109], 0, v[118:119]
	global_store_dwordx4 v[108:109], v[100:103], off nt
	v_cndmask_b32_e64 v105, v115, v111, s[4:5]
	v_cvt_pk_f16_f32 v96, v96, v97
	v_add_co_u32_e32 v100, vcc, s1, v108
	v_cvt_pk_f16_f32 v88, v88, v89
	s_nop 0
	v_addc_co_u32_e32 v101, vcc, 0, v109, vcc
	v_cvt_pk_f16_f32 v92, v92, v93
	v_cvt_pk_f16_f32 v93, v84, v85
	global_store_dwordx4 v[100:101], v[104:107], off nt
	v_cvt_pk_f16_f32 v98, v98, v99
	v_cvt_pk_f16_f32 v90, v90, v91
	v_cndmask_b32_e64 v89, v88, v96, s[4:5]
	v_cndmask_b32_e64 v84, v93, v92, s[4:5]
	v_mov_b32_e32 v97, v3
	v_mov_b32_e32 v100, v3
	v_cndmask_b32_e64 v91, v90, v98, s[4:5]
	v_cvt_pk_f16_f32 v94, v94, v95
	v_cvt_pk_f16_f32 v95, v86, v87
	v_mov_b32_dpp v97, v84 row_ror:8 row_mask:0xf bank_mask:0xf
	v_mov_b32_dpp v100, v89 row_ror:8 row_mask:0xf bank_mask:0xf
	v_mov_b32_e32 v89, v3
	v_cndmask_b32_e64 v86, v95, v94, s[4:5]
	v_mov_b32_e32 v99, v3
	v_mov_b32_dpp v89, v91 row_ror:8 row_mask:0xf bank_mask:0xf
	v_cndmask_b32_e64 v84, v92, v97, s[4:5]
	v_or_b32_e32 v92, 32, v146
	v_mov_b32_dpp v99, v86 row_ror:8 row_mask:0xf bank_mask:0xf
	v_cndmask_b32_e64 v91, v89, v90, s[4:5]
	v_cndmask_b32_e64 v90, v100, v88, s[4:5]
	v_cndmask_b32_e64 v88, v97, v93, s[4:5]
	v_mad_i64_i32 v[92:93], s[14:15], v92, s35, v[116:117]
	v_cndmask_b32_e64 v87, v98, v89, s[4:5]
	v_cndmask_b32_e64 v86, v96, v100, s[4:5]
	v_cndmask_b32_e64 v85, v94, v99, s[4:5]
	v_lshl_add_u64 v[92:93], v[92:93], 0, v[118:119]
	global_store_dwordx4 v[92:93], v[84:87], off nt
	v_cndmask_b32_e64 v89, v99, v95, s[4:5]
	v_cvt_pk_f16_f32 v80, v80, v81
	v_add_co_u32_e32 v84, vcc, s1, v92
	v_cvt_pk_f16_f32 v72, v72, v73
	s_nop 0
	v_addc_co_u32_e32 v85, vcc, 0, v93, vcc
	v_cvt_pk_f16_f32 v76, v76, v77
	v_cvt_pk_f16_f32 v77, v68, v69
	global_store_dwordx4 v[84:85], v[88:91], off nt
	v_cvt_pk_f16_f32 v82, v82, v83
	v_cvt_pk_f16_f32 v74, v74, v75
	v_cndmask_b32_e64 v73, v72, v80, s[4:5]
	v_cndmask_b32_e64 v68, v77, v76, s[4:5]
	v_mov_b32_e32 v81, v3
	v_mov_b32_e32 v84, v3
	v_cndmask_b32_e64 v75, v74, v82, s[4:5]
	v_cvt_pk_f16_f32 v78, v78, v79
	v_cvt_pk_f16_f32 v79, v70, v71
	v_mov_b32_dpp v81, v68 row_ror:8 row_mask:0xf bank_mask:0xf
	v_mov_b32_dpp v84, v73 row_ror:8 row_mask:0xf bank_mask:0xf
	v_mov_b32_e32 v73, v3
	v_cndmask_b32_e64 v70, v79, v78, s[4:5]
	v_mov_b32_e32 v83, v3
	v_mov_b32_dpp v73, v75 row_ror:8 row_mask:0xf bank_mask:0xf
	v_cndmask_b32_e64 v68, v76, v81, s[4:5]
	v_or_b32_e32 v76, 48, v146
	v_mov_b32_dpp v83, v70 row_ror:8 row_mask:0xf bank_mask:0xf
	v_cndmask_b32_e64 v75, v73, v74, s[4:5]
	v_cndmask_b32_e64 v74, v84, v72, s[4:5]
	v_cndmask_b32_e64 v72, v81, v77, s[4:5]
	v_mad_i64_i32 v[76:77], s[14:15], v76, s35, v[116:117]
	v_cndmask_b32_e64 v71, v82, v73, s[4:5]
	v_cndmask_b32_e64 v70, v80, v84, s[4:5]
	v_cndmask_b32_e64 v69, v78, v83, s[4:5]
	v_lshl_add_u64 v[76:77], v[76:77], 0, v[118:119]
	global_store_dwordx4 v[76:77], v[68:71], off nt
	v_cndmask_b32_e64 v73, v83, v79, s[4:5]
	v_cvt_pk_f16_f32 v64, v64, v65
	v_add_co_u32_e32 v68, vcc, s1, v76
	v_cvt_pk_f16_f32 v56, v56, v57
	s_nop 0
	v_addc_co_u32_e32 v69, vcc, 0, v77, vcc
	global_store_dwordx4 v[68:69], v[72:75], off nt
	v_cvt_pk_f16_f32 v66, v66, v67
	v_cvt_pk_f16_f32 v58, v58, v59
	v_cndmask_b32_e64 v57, v56, v64, s[4:5]
	v_cvt_pk_f16_f32 v60, v60, v61
	v_cvt_pk_f16_f32 v61, v52, v53
	v_mov_b32_e32 v69, v3
	v_cndmask_b32_e64 v59, v58, v66, s[4:5]
	v_cvt_pk_f16_f32 v62, v62, v63
	v_cvt_pk_f16_f32 v63, v54, v55
	v_cndmask_b32_e64 v52, v61, v60, s[4:5]
	v_mov_b32_e32 v65, v3
	v_mov_b32_dpp v69, v57 row_ror:8 row_mask:0xf bank_mask:0xf
	v_mov_b32_e32 v57, v3
	v_add_u32_e32 v68, 0x80, v146
	v_cndmask_b32_e64 v54, v63, v62, s[4:5]
	v_mov_b32_dpp v65, v52 row_ror:8 row_mask:0xf bank_mask:0xf
	v_mov_b32_e32 v67, v3
	v_mov_b32_dpp v57, v59 row_ror:8 row_mask:0xf bank_mask:0xf
	v_cndmask_b32_e64 v52, v60, v65, s[4:5]
	v_mov_b32_dpp v67, v54 row_ror:8 row_mask:0xf bank_mask:0xf
	v_cndmask_b32_e64 v59, v57, v58, s[4:5]
	v_cndmask_b32_e64 v58, v69, v56, s[4:5]
	v_cndmask_b32_e64 v56, v65, v61, s[4:5]
	v_mad_i64_i32 v[60:61], s[14:15], v68, s35, v[116:117]
	v_cndmask_b32_e64 v55, v66, v57, s[4:5]
	v_cndmask_b32_e64 v54, v64, v69, s[4:5]
	v_cndmask_b32_e64 v53, v62, v67, s[4:5]
	v_lshl_add_u64 v[60:61], v[60:61], 0, v[118:119]
	global_store_dwordx4 v[60:61], v[52:55], off nt
	v_cndmask_b32_e64 v57, v67, v63, s[4:5]
	v_cvt_pk_f16_f32 v48, v48, v49
	v_add_co_u32_e32 v52, vcc, s1, v60
	v_cvt_pk_f16_f32 v40, v40, v41
	s_nop 0
	v_addc_co_u32_e32 v53, vcc, 0, v61, vcc
; #define PG8_WAIT_V(n) asm volatile("s_waitcnt vmcnt(" #n ")" ::: "memory")
; #define PG8_BAR __builtin_amdgcn_s_barrier()
; template <class Epi>
; __device__ __forceinline__ void gemm_phase(LAS unsigned char* lds, const Gemm g, const StaticOrder& S, const Epi& E, const int tid) {
;     ...
;         if (!has_next) break;
; #pragma unroll
;         for (int a = 0; a < 2; ++a)
; #pragma unroll
;             for (int b = 0; b < 2; ++b)
; #pragma unroll
;                 for (int m = 0; m < 4; ++m)
; #pragma unroll
;                     for (int n = 0; n < 2; ++n) acc[a][b][m][n] = (f32x4){0.f, 0.f, 0.f, 0.f};
;         cur = nxt; cA = nA; cB = nB; ++ui;
;     }
;     PG8_WAIT_V(0);
;     if (wr == 0) PG8_BAR;
;     PG8_BAR;
;     __device__ __forceinline__ void operator()(f32x4 (&acc)[2][2][4][2], const pg8::Unit& u, int wr, int wc, int fr, int fq) const {
;     ...
;         for (int ai = 0; ai < 2; ++ai)
; #pragma unroll
;             for (int m = 0; m < 4; ++m) {
;                 const h8 x0 = pack8(acc[ai][0][m][0], acc[ai][0][m][1]), x1 = pack8(acc[ai][1][m][0], acc[ai][1][m][1]);
;                 const i32x4 snd = hi ? __builtin_bit_cast(i32x4, x0) : __builtin_bit_cast(i32x4, x1);
;                 i32x4 rcv;
; #pragma unroll
;                 for (int d = 0; d < 4; ++d) rcv[d] = __builtin_amdgcn_update_dpp(0, snd[d], 0x128  , 0xF, 0xF, false);
;                 const h8 rv = __builtin_bit_cast(h8, rcv);
;                 const h8 vA = hi ? rv : x0;
;                 const h8 vB = hi ? x1 : rv;
;                 half_t* rowp = O + (size_t)(row0 + ai * 128 + m * 16) * NIN + col;
;                 __builtin_nontemporal_store(vA, (h8*)rowp); __builtin_nontemporal_store(vB, (h8*)(rowp + (size_t)8 * NIN)); }
	v_cvt_pk_f16_f32 v44, v44, v45
	v_cvt_pk_f16_f32 v45, v36, v37
	global_store_dwordx4 v[52:53], v[56:59], off nt
	v_cvt_pk_f16_f32 v50, v50, v51
	v_cvt_pk_f16_f32 v42, v42, v43
	v_cndmask_b32_e64 v41, v40, v48, s[4:5]
	v_cndmask_b32_e64 v36, v45, v44, s[4:5]
	v_mov_b32_e32 v49, v3
	v_mov_b32_e32 v52, v3
	v_cndmask_b32_e64 v43, v42, v50, s[4:5]
	v_cvt_pk_f16_f32 v46, v46, v47
	v_cvt_pk_f16_f32 v47, v38, v39
	v_mov_b32_dpp v49, v36 row_ror:8 row_mask:0xf bank_mask:0xf
	v_mov_b32_dpp v52, v41 row_ror:8 row_mask:0xf bank_mask:0xf
	v_mov_b32_e32 v41, v3
	v_cndmask_b32_e64 v38, v47, v46, s[4:5]
	v_mov_b32_e32 v51, v3
	v_mov_b32_dpp v41, v43 row_ror:8 row_mask:0xf bank_mask:0xf
	v_cndmask_b32_e64 v36, v44, v49, s[4:5]
	v_add_u32_e32 v44, 0x90, v146
	v_mov_b32_dpp v51, v38 row_ror:8 row_mask:0xf bank_mask:0xf
	v_cndmask_b32_e64 v43, v41, v42, s[4:5]
	v_cndmask_b32_e64 v42, v52, v40, s[4:5]
	v_cndmask_b32_e64 v40, v49, v45, s[4:5]
	v_mad_i64_i32 v[44:45], s[14:15], v44, s35, v[116:117]
	v_cndmask_b32_e64 v39, v50, v41, s[4:5]
	v_cndmask_b32_e64 v38, v48, v52, s[4:5]
	v_cndmask_b32_e64 v37, v46, v51, s[4:5]
	v_lshl_add_u64 v[44:45], v[44:45], 0, v[118:119]
	global_store_dwordx4 v[44:45], v[36:39], off nt
	v_cndmask_b32_e64 v41, v51, v47, s[4:5]
	v_cvt_pk_f16_f32 v32, v32, v33
	v_add_co_u32_e32 v36, vcc, s1, v44
	v_cvt_pk_f16_f32 v24, v24, v25
	s_nop 0
	v_addc_co_u32_e32 v37, vcc, 0, v45, vcc
	v_cvt_pk_f16_f32 v28, v28, v29
	v_cvt_pk_f16_f32 v29, v20, v21
	global_store_dwordx4 v[36:37], v[40:43], off nt
	v_cvt_pk_f16_f32 v34, v34, v35
	v_cvt_pk_f16_f32 v26, v26, v27
	v_cndmask_b32_e64 v25, v24, v32, s[4:5]
	v_cndmask_b32_e64 v20, v29, v28, s[4:5]
	v_mov_b32_e32 v33, v3
	v_mov_b32_e32 v36, v3
	v_cndmask_b32_e64 v27, v26, v34, s[4:5]
	v_cvt_pk_f16_f32 v30, v30, v31
	v_cvt_pk_f16_f32 v31, v22, v23
	v_mov_b32_dpp v33, v20 row_ror:8 row_mask:0xf bank_mask:0xf
	v_mov_b32_dpp v36, v25 row_ror:8 row_mask:0xf bank_mask:0xf
	v_mov_b32_e32 v25, v3
	v_cvt_pk_f16_f32 v16, v16, v17
	v_cvt_pk_f16_f32 v17, v4, v5
	v_cvt_pk_f16_f32 v5, v14, v15
	v_cvt_pk_f16_f32 v14, v10, v11
	v_cvt_pk_f16_f32 v10, v12, v13
	v_cvt_pk_f16_f32 v8, v8, v9
	v_cndmask_b32_e64 v22, v31, v30, s[4:5]
	v_mov_b32_e32 v35, v3
	v_mov_b32_dpp v25, v27 row_ror:8 row_mask:0xf bank_mask:0xf
	v_cndmask_b32_e64 v20, v28, v33, s[4:5]
	v_add_u32_e32 v28, 0xa0, v146
	v_cndmask_b32_e64 v9, v8, v10, s[4:5]
	v_mov_b32_e32 v12, v3
	v_mov_b32_dpp v35, v22 row_ror:8 row_mask:0xf bank_mask:0xf
	v_cndmask_b32_e64 v27, v25, v26, s[4:5]
	v_cndmask_b32_e64 v26, v36, v24, s[4:5]
	v_cndmask_b32_e64 v24, v33, v29, s[4:5]
	v_mad_i64_i32 v[28:29], s[14:15], v28, s35, v[116:117]
	v_cvt_pk_f16_f32 v18, v18, v19
	v_cvt_pk_f16_f32 v19, v6, v7
	v_cndmask_b32_e64 v4, v17, v16, s[4:5]
	v_mov_b32_dpp v12, v9 row_ror:8 row_mask:0xf bank_mask:0xf
	v_mov_b32_e32 v13, v3
	v_cndmask_b32_e64 v23, v34, v25, s[4:5]
	v_cndmask_b32_e64 v22, v32, v36, s[4:5]
	v_cndmask_b32_e64 v21, v30, v35, s[4:5]
	v_lshl_add_u64 v[28:29], v[28:29], 0, v[118:119]
	v_cndmask_b32_e64 v6, v19, v18, s[4:5]
	v_cndmask_b32_e64 v7, v14, v5, s[4:5]
	v_mov_b32_e32 v9, v3
	v_mov_b32_dpp v13, v4 row_ror:8 row_mask:0xf bank_mask:0xf
	v_mov_b32_e32 v11, v3
	v_cndmask_b32_e64 v4, v10, v12, s[4:5]
	v_cndmask_b32_e64 v8, v12, v8, s[4:5]
	v_add_u32_e32 v12, 0xb0, v146
	global_store_dwordx4 v[28:29], v[20:23], off nt
	v_mov_b32_dpp v9, v7 row_ror:8 row_mask:0xf bank_mask:0xf
	v_mov_b32_dpp v11, v6 row_ror:8 row_mask:0xf bank_mask:0xf
	v_add_co_u32_e32 v20, vcc, s1, v28
	v_cndmask_b32_e64 v6, v16, v13, s[4:5]
	v_cndmask_b32_e64 v10, v13, v17, s[4:5]
	v_mad_i64_i32 v[12:13], s[14:15], v12, s35, v[116:117]
	v_addc_co_u32_e32 v21, vcc, 0, v29, vcc
	v_cndmask_b32_e64 v7, v18, v11, s[4:5]
	v_cndmask_b32_e64 v5, v5, v9, s[4:5]
	v_lshl_add_u64 v[12:13], v[12:13], 0, v[118:119]
	global_store_dwordx4 v[12:13], v[4:7], off nt
	v_cndmask_b32_e64 v25, v35, v31, s[4:5]
	v_cndmask_b32_e64 v11, v11, v19, s[4:5]
	v_add_co_u32_e32 v4, vcc, 0x3c000, v12
	v_cndmask_b32_e64 v9, v9, v14, s[4:5]
	s_nop 0
	v_addc_co_u32_e32 v5, vcc, 0, v13, vcc
	s_and_b64 vcc, exec, s[6:7]
	s_mov_b32 s48, s0
	s_mov_b32 s49, s8
	s_mov_b64 s[18:19], s[12:13]
	s_mov_b64 s[14:15], s[10:11]
	global_store_dwordx4 v[20:21], v[24:27], off nt
	global_store_dwordx4 v[4:5], v[8:11], off nt
	s_cbranch_vccz .LBB0_329
	s_waitcnt vmcnt(0)
	v_readlane_b32 s42, v251, 7
	v_readlane_b32 s46, v251, 9
	v_readlane_b32 s48, v251, 13
	s_cmpk_gt_u32 s20, 0xff
	v_readlane_b32 s43, v251, 8
	v_readlane_b32 s47, v251, 10
	v_readlane_b32 s49, v251, 14
	s_cbranch_scc1 .LBB0_336
	s_barrier

; #define PG8_STAGE(bufoff, gbase, voff) do { _Pragma("unroll") for (int _i = 0; _i < 2; ++_i) \
;         __builtin_amdgcn_global_load_lds((const unsigned*)((const char*)(gbase) + (voff)[_i]), (LAS unsigned*)(lds + (bufoff) + ldsw + _i * 8192), 16, 0, 0); } while (0)
; #define PG8_LDA(dst, b, h) do { _Pragma("unroll") for (int m = 0; m < 4; ++m) _Pragma("unroll") for (int k = 0; k < 2; ++k) dst[m][k] = *(const LAS h8*)(lds + PG8_SA(b, h) + aoff + m * 2048 + k * 1024); } while (0)
; #define PG8_LDB(dst, b, h) do { _Pragma("unroll") for (int n = 0; n < 2; ++n) _Pragma("unroll") for (int k = 0; k < 2; ++k) dst[n][k] = *(const LAS h8*)(lds + PG8_SB(b, h) + boff + n * 2048 + k * 1024); } while (0)
; #define PG8_WAIT_L(n) asm volatile("s_waitcnt lgkmcnt(" #n ")" ::: "memory")
; #define PG8_BAR __builtin_amdgcn_s_barrier()
; #define PG8_SCHED __builtin_amdgcn_sched_barrier(0)
; template <class Epi>
; __device__ __forceinline__ void gemm_phase(LAS unsigned char* lds, const Gemm g, const StaticOrder& S, const Epi& E, const int tid) {
;     ...
;         for (int t = 0; t < nt; t += 2) {
;             const bool last = (t == nt - 2);
;             const char* a1 = cA + (size_t)(t + 1) * kstep;
;             const char* a2 = last ? nA : cA + (size_t)(t + 2) * kstep; const char* b2 = last ? nB : cB + (size_t)(t + 2) * kstep;
;             const char* a3 = a2 + kstep; const char* b3 = b2 + kstep;
;             if constexpr (Epi::HAS_MID) { if (t == (nt >> 1)) E.mid(acc, cur, wr, wc, fr, fq); }
;             PG8_LDB(B0, 0, 0); PG8_SCHED; PG8_LDA(At, 0, 0); PG8_STAGE(PG8_SA(1, 1), a1 + hstep, voffA);
;             PG8_WAIT_L(8); PG8_BAR; PG8_WAIT_L(0); PG8_MMA(0, 0, At, B0); PG8_BAR; PG8_SCHED;
;             PG8_LDB(B1, 0, 1); PG8_STAGE(PG8_SB(0, 0), b2, voffB);
;             PG8_BAR; PG8_WAIT_L(0); PG8_MMA(0, 1, At, B1); PG8_BAR;
.LBB0_594:
	s_add_u32 s14, s10, s12
	s_addc_u32 s15, s11, s13
	s_add_u32 s14, s14, 0x100
	s_addc_u32 s15, s15, 0
	s_add_u32 s55, s52, s12
	s_addc_u32 s56, s53, s13
	s_cmpk_eq_i32 s12, 0x1f00
	s_cselect_b32 s19, s5, s15
	s_cselect_b32 s18, s50, s14
	s_cselect_b32 s15, s1, s56
	s_cselect_b32 s14, s51, s55
	s_add_i32 s55, 0, 0x10000
	v_add_u32_e32 v0, s55, v189
	ds_read_b128 v[132:135], v0
	ds_read_b128 v[136:139], v0 offset:1024
	ds_read_b128 v[176:179], v0 offset:2048
	ds_read_b128 v[192:195], v0 offset:3072
	v_lshl_add_u64 v[0:1], v[172:173], 0, s[12:13]
	s_add_i32 m0, s25, 0xc000
	ds_read_b128 v[196:199], v191
	ds_read_b128 v[200:203], v191 offset:1024
	ds_read_b128 v[204:207], v191 offset:2048
	ds_read_b128 v[208:211], v191 offset:3072
	ds_read_b128 v[212:215], v191 offset:4096
	ds_read_b128 v[216:219], v191 offset:5120
	ds_read_b128 v[220:223], v191 offset:6144
	ds_read_b128 v[224:227], v191 offset:7168
	global_load_lds_dwordx4 v[0:1], off
	v_lshl_add_u64 v[0:1], v[174:175], 0, s[12:13]
	s_add_i32 m0, s25, 0xe000
	s_nop 0
	global_load_lds_dwordx4 v[0:1], off
	s_waitcnt lgkmcnt(8)
	s_barrier
	s_waitcnt lgkmcnt(0)
	s_setprio 0
	s_waitcnt lgkmcnt(0)
	v_mfma_f32_16x16x32_bf16 v[128:131], v[132:135], v[196:199], v[128:131]
	v_mfma_f32_16x16x32_bf16 v[124:127], v[176:179], v[196:199], v[124:127]
	v_mfma_f32_16x16x32_bf16 v[112:115], v[132:135], v[204:207], v[112:115]
	v_mfma_f32_16x16x32_bf16 v[108:111], v[176:179], v[204:207], v[108:111]
	v_mfma_f32_16x16x32_bf16 v[96:99], v[132:135], v[212:215], v[96:99]
	v_mfma_f32_16x16x32_bf16 v[92:95], v[176:179], v[212:215], v[92:95]
	v_mfma_f32_16x16x32_bf16 v[80:83], v[132:135], v[220:223], v[80:83]
	v_mfma_f32_16x16x32_bf16 v[76:79], v[176:179], v[220:223], v[76:79]
	v_mfma_f32_16x16x32_bf16 v[128:131], v[136:139], v[200:203], v[128:131]
	v_mfma_f32_16x16x32_bf16 v[124:127], v[192:195], v[200:203], v[124:127]
	v_mfma_f32_16x16x32_bf16 v[112:115], v[136:139], v[208:211], v[112:115]
	v_mfma_f32_16x16x32_bf16 v[108:111], v[192:195], v[208:211], v[108:111]
	v_mfma_f32_16x16x32_bf16 v[96:99], v[136:139], v[216:219], v[96:99]
	v_mfma_f32_16x16x32_bf16 v[92:95], v[192:195], v[216:219], v[92:95]
	v_mfma_f32_16x16x32_bf16 v[80:83], v[136:139], v[224:227], v[80:83]
	v_mfma_f32_16x16x32_bf16 v[76:79], v[192:195], v[224:227], v[76:79]
	s_setprio 1
	s_barrier
	s_add_i32 s58, 0, 0x14000
	v_add_u32_e32 v0, s58, v189
	s_add_i32 s55, s55, s24
	ds_read_b128 v[228:231], v0
	ds_read_b128 v[232:235], v0 offset:1024
	ds_read_b128 v[236:239], v0 offset:2048
	ds_read_b128 v[240:243], v0 offset:3072
	v_lshl_add_u64 v[0:1], s[14:15], 0, v[144:145]
	s_mov_b32 m0, s55
	v_lshl_add_u64 v[244:245], s[14:15], 0, v[140:141]
	global_load_lds_dwordx4 v[0:1], off
	s_add_i32 m0, s55, 0x2000
	s_nop 0
	global_load_lds_dwordx4 v[244:245], off
	s_barrier
	s_waitcnt lgkmcnt(0)
	s_setprio 0
	s_waitcnt lgkmcnt(0)
	v_mfma_f32_16x16x32_bf16 v[120:123], v[228:231], v[196:199], v[120:123]
	v_mfma_f32_16x16x32_bf16 v[116:119], v[236:239], v[196:199], v[116:119]
	v_mfma_f32_16x16x32_bf16 v[104:107], v[228:231], v[204:207], v[104:107]
	v_mfma_f32_16x16x32_bf16 v[100:103], v[236:239], v[204:207], v[100:103]
	v_mfma_f32_16x16x32_bf16 v[88:91], v[228:231], v[212:215], v[88:91]
	v_mfma_f32_16x16x32_bf16 v[84:87], v[236:239], v[212:215], v[84:87]
	v_mfma_f32_16x16x32_bf16 v[72:75], v[228:231], v[220:223], v[72:75]
	v_mfma_f32_16x16x32_bf16 v[68:71], v[236:239], v[220:223], v[68:71]
	v_mfma_f32_16x16x32_bf16 v[120:123], v[232:235], v[200:203], v[120:123]
	v_mfma_f32_16x16x32_bf16 v[116:119], v[240:243], v[200:203], v[116:119]
	v_mfma_f32_16x16x32_bf16 v[104:107], v[232:235], v[208:211], v[104:107]
	v_mfma_f32_16x16x32_bf16 v[100:103], v[240:243], v[208:211], v[100:103]
	v_mfma_f32_16x16x32_bf16 v[88:91], v[232:235], v[216:219], v[88:91]
	v_mfma_f32_16x16x32_bf16 v[84:87], v[240:243], v[216:219], v[84:87]
	v_mfma_f32_16x16x32_bf16 v[72:75], v[232:235], v[224:227], v[72:75]
	v_mfma_f32_16x16x32_bf16 v[68:71], v[240:243], v[224:227], v[68:71]
	s_setprio 1
	s_mov_b32 m0, s25
	v_lshl_add_u64 v[246:247], s[18:19], 0, v[146:147]
	s_barrier
	ds_read_b128 v[196:199], v191 offset:16384
	ds_read_b128 v[200:203], v191 offset:17408
	ds_read_b128 v[204:207], v191 offset:18432
	ds_read_b128 v[208:211], v191 offset:19456
	ds_read_b128 v[212:215], v191 offset:20480
	ds_read_b128 v[216:219], v191 offset:21504
	ds_read_b128 v[220:223], v191 offset:22528
	ds_read_b128 v[224:227], v191 offset:23552
	global_load_lds_dwordx4 v[246:247], off
	v_lshl_add_u64 v[248:249], s[18:19], 0, v[142:143]
	s_mov_b32 m0, s42
	s_nop 0
	global_load_lds_dwordx4 v[248:249], off
	s_barrier
	s_waitcnt lgkmcnt(0)
	s_setprio 0
	s_waitcnt lgkmcnt(0)
	v_mfma_f32_16x16x32_bf16 v[64:67], v[132:135], v[196:199], v[64:67]
	v_mfma_f32_16x16x32_bf16 v[60:63], v[176:179], v[196:199], v[60:63]
	v_mfma_f32_16x16x32_bf16 v[48:51], v[132:135], v[204:207], v[48:51]
	v_mfma_f32_16x16x32_bf16 v[44:47], v[176:179], v[204:207], v[44:47]
	v_mfma_f32_16x16x32_bf16 v[32:35], v[132:135], v[212:215], v[32:35]
	v_mfma_f32_16x16x32_bf16 v[28:31], v[176:179], v[212:215], v[28:31]
	v_mfma_f32_16x16x32_bf16 v[16:19], v[132:135], v[220:223], v[16:19]
	v_mfma_f32_16x16x32_bf16 v[12:15], v[176:179], v[220:223], v[12:15]
	v_mfma_f32_16x16x32_bf16 v[64:67], v[136:139], v[200:203], v[64:67]
	v_mfma_f32_16x16x32_bf16 v[60:63], v[192:195], v[200:203], v[60:63]
	v_mfma_f32_16x16x32_bf16 v[48:51], v[136:139], v[208:211], v[48:51]
	v_mfma_f32_16x16x32_bf16 v[44:47], v[192:195], v[208:211], v[44:47]
	v_mfma_f32_16x16x32_bf16 v[32:35], v[136:139], v[216:219], v[32:35]
	v_mfma_f32_16x16x32_bf16 v[28:31], v[192:195], v[216:219], v[28:31]
	v_mfma_f32_16x16x32_bf16 v[16:19], v[136:139], v[224:227], v[16:19]
	v_mfma_f32_16x16x32_bf16 v[12:15], v[192:195], v[224:227], v[12:15]
	s_setprio 1
	s_barrier
; #define PG8_STAGE(bufoff, gbase, voff) do { _Pragma("unroll") for (int _i = 0; _i < 2; ++_i) \
;         __builtin_amdgcn_global_load_lds((const unsigned*)((const char*)(gbase) + (voff)[_i]), (LAS unsigned*)(lds + (bufoff) + ldsw + _i * 8192), 16, 0, 0); } while (0)
; #define PG8_LDA(dst, b, h) do { _Pragma("unroll") for (int m = 0; m < 4; ++m) _Pragma("unroll") for (int k = 0; k < 2; ++k) dst[m][k] = *(const LAS h8*)(lds + PG8_SA(b, h) + aoff + m * 2048 + k * 1024); } while (0)
; #define PG8_LDB(dst, b, h) do { _Pragma("unroll") for (int n = 0; n < 2; ++n) _Pragma("unroll") for (int k = 0; k < 2; ++k) dst[n][k] = *(const LAS h8*)(lds + PG8_SB(b, h) + boff + n * 2048 + k * 1024); } while (0)
; #define PG8_WAIT_V(n) asm volatile("s_waitcnt vmcnt(" #n ")" ::: "memory")
; #define PG8_WAIT_L(n) asm volatile("s_waitcnt lgkmcnt(" #n ")" ::: "memory")
; #define PG8_BAR __builtin_amdgcn_s_barrier()
; #define PG8_SCHED __builtin_amdgcn_sched_barrier(0)
; template <class Epi>
; __device__ __forceinline__ void gemm_phase(LAS unsigned char* lds, const Gemm g, const StaticOrder& S, const Epi& E, const int tid) {
;     ...
;             PG8_STAGE(PG8_SB(0, 1), b2 + hstepB, voffB);
;             PG8_WAIT_V(6); PG8_BAR; PG8_MMA(1, 1, At, B1); PG8_BAR;
;             PG8_LDB(B0, 1, 0); PG8_SCHED; PG8_LDA(At, 1, 0); PG8_STAGE(PG8_SA(0, 1), a2 + hstep, voffA);
;             PG8_WAIT_L(8); PG8_BAR; PG8_WAIT_L(0); PG8_MMA(0, 0, At, B0); PG8_BAR; PG8_SCHED;
;             PG8_LDB(B1, 1, 1); PG8_STAGE(PG8_SB(1, 0), b3, voffB);
;             PG8_BAR; PG8_WAIT_L(0); PG8_MMA(0, 1, At, B1); PG8_BAR;
	s_add_u32 s56, s14, 0x100000
	s_addc_u32 s57, s15, 0
	s_add_i32 s55, s58, s24
	v_lshl_add_u64 v[132:133], s[56:57], 0, v[144:145]
	s_mov_b32 m0, s55
	s_nop 0
	global_load_lds_dwordx4 v[132:133], off
	v_lshl_add_u64 v[132:133], s[56:57], 0, v[140:141]
	s_add_i32 m0, s55, 0x2000
	s_nop 0
	global_load_lds_dwordx4 v[132:133], off
	s_waitcnt vmcnt(6)
	s_barrier
	s_setprio 0
	v_mfma_f32_16x16x32_bf16 v[56:59], v[228:231], v[196:199], v[56:59]
	v_mfma_f32_16x16x32_bf16 v[52:55], v[236:239], v[196:199], v[52:55]
	v_mfma_f32_16x16x32_bf16 v[40:43], v[228:231], v[204:207], v[40:43]
	v_mfma_f32_16x16x32_bf16 v[36:39], v[236:239], v[204:207], v[36:39]
	v_mfma_f32_16x16x32_bf16 v[24:27], v[228:231], v[212:215], v[24:27]
	v_mfma_f32_16x16x32_bf16 v[20:23], v[236:239], v[212:215], v[20:23]
	v_mfma_f32_16x16x32_bf16 v[8:11], v[228:231], v[220:223], v[8:11]
	v_mfma_f32_16x16x32_bf16 v[4:7], v[236:239], v[220:223], v[4:7]
	v_mfma_f32_16x16x32_bf16 v[56:59], v[232:235], v[200:203], v[56:59]
	v_mfma_f32_16x16x32_bf16 v[52:55], v[240:243], v[200:203], v[52:55]
	v_mfma_f32_16x16x32_bf16 v[40:43], v[232:235], v[208:211], v[40:43]
	v_mfma_f32_16x16x32_bf16 v[36:39], v[240:243], v[208:211], v[36:39]
	v_mfma_f32_16x16x32_bf16 v[24:27], v[232:235], v[216:219], v[24:27]
	v_mfma_f32_16x16x32_bf16 v[20:23], v[240:243], v[216:219], v[20:23]
	v_mfma_f32_16x16x32_bf16 v[8:11], v[232:235], v[224:227], v[8:11]
	v_mfma_f32_16x16x32_bf16 v[4:7], v[240:243], v[224:227], v[4:7]
	s_setprio 1
	s_add_i32 s55, 0, 0x18000
	v_add_u32_e32 v2, s55, v189
	s_barrier
	ds_read_b128 v[132:135], v2
	ds_read_b128 v[136:139], v2 offset:1024
	ds_read_b128 v[176:179], v2 offset:2048
	ds_read_b128 v[192:195], v2 offset:3072
	s_add_u32 s18, s18, 0x100000
	s_addc_u32 s19, s19, 0
	s_mov_b32 m0, s43
	v_lshl_add_u64 v[228:229], s[18:19], 0, v[146:147]
	ds_read_b128 v[196:199], v191 offset:32768
	ds_read_b128 v[200:203], v191 offset:33792
	ds_read_b128 v[204:207], v191 offset:34816
	ds_read_b128 v[208:211], v191 offset:35840
	ds_read_b128 v[212:215], v191 offset:36864
	ds_read_b128 v[216:219], v191 offset:37888
	ds_read_b128 v[220:223], v191 offset:38912
	ds_read_b128 v[224:227], v191 offset:39936
	global_load_lds_dwordx4 v[228:229], off
	v_lshl_add_u64 v[228:229], s[18:19], 0, v[142:143]
	s_mov_b32 m0, s46
	s_nop 0
	global_load_lds_dwordx4 v[228:229], off
	s_waitcnt lgkmcnt(8)
	s_barrier
	s_waitcnt lgkmcnt(0)
	s_setprio 0
	s_waitcnt lgkmcnt(0)
	v_mfma_f32_16x16x32_bf16 v[128:131], v[132:135], v[196:199], v[128:131]
	v_mfma_f32_16x16x32_bf16 v[124:127], v[176:179], v[196:199], v[124:127]
	v_mfma_f32_16x16x32_bf16 v[112:115], v[132:135], v[204:207], v[112:115]
	v_mfma_f32_16x16x32_bf16 v[108:111], v[176:179], v[204:207], v[108:111]
	v_mfma_f32_16x16x32_bf16 v[96:99], v[132:135], v[212:215], v[96:99]
	v_mfma_f32_16x16x32_bf16 v[92:95], v[176:179], v[212:215], v[92:95]
	v_mfma_f32_16x16x32_bf16 v[80:83], v[132:135], v[220:223], v[80:83]
	v_mfma_f32_16x16x32_bf16 v[76:79], v[176:179], v[220:223], v[76:79]
	v_mfma_f32_16x16x32_bf16 v[128:131], v[136:139], v[200:203], v[128:131]
	v_mfma_f32_16x16x32_bf16 v[124:127], v[192:195], v[200:203], v[124:127]
	v_mfma_f32_16x16x32_bf16 v[112:115], v[136:139], v[208:211], v[112:115]
	v_mfma_f32_16x16x32_bf16 v[108:111], v[192:195], v[208:211], v[108:111]
	v_mfma_f32_16x16x32_bf16 v[96:99], v[136:139], v[216:219], v[96:99]
	v_mfma_f32_16x16x32_bf16 v[92:95], v[192:195], v[216:219], v[92:95]
	v_mfma_f32_16x16x32_bf16 v[80:83], v[136:139], v[224:227], v[80:83]
	v_mfma_f32_16x16x32_bf16 v[76:79], v[192:195], v[224:227], v[76:79]
	s_setprio 1
	s_barrier
	s_add_i32 s18, 0, 0x1c000
	s_add_i32 s19, s55, s24
	v_add_u32_e32 v2, s18, v189
	v_lshl_add_u64 v[0:1], v[0:1], 0, s[30:31]
	s_mov_b32 m0, s19
	ds_read_b128 v[228:231], v2
	ds_read_b128 v[232:235], v2 offset:1024
	ds_read_b128 v[236:239], v2 offset:2048
	ds_read_b128 v[240:243], v2 offset:3072
	global_load_lds_dwordx4 v[0:1], off
	v_lshl_add_u64 v[0:1], v[244:245], 0, s[30:31]
	s_add_i32 m0, s19, 0x2000
	s_nop 0
	global_load_lds_dwordx4 v[0:1], off
	s_barrier
; #define PG8_STAGE(bufoff, gbase, voff) do { _Pragma("unroll") for (int _i = 0; _i < 2; ++_i) \
;         __builtin_amdgcn_global_load_lds((const unsigned*)((const char*)(gbase) + (voff)[_i]), (LAS unsigned*)(lds + (bufoff) + ldsw + _i * 8192), 16, 0, 0); } while (0)
; #define PG8_LDA(dst, b, h) do { _Pragma("unroll") for (int m = 0; m < 4; ++m) _Pragma("unroll") for (int k = 0; k < 2; ++k) dst[m][k] = *(const LAS h8*)(lds + PG8_SA(b, h) + aoff + m * 2048 + k * 1024); } while (0)
; #define PG8_WAIT_V(n) asm volatile("s_waitcnt vmcnt(" #n ")" ::: "memory")
; #define PG8_WAIT_L(n) asm volatile("s_waitcnt lgkmcnt(" #n ")" ::: "memory")
; #define PG8_BAR __builtin_amdgcn_s_barrier()
; #define PG8_SCHED __builtin_amdgcn_sched_barrier(0)
; template <class Epi>
; __device__ __forceinline__ void gemm_phase(LAS unsigned char* lds, const Gemm g, const StaticOrder& S, const Epi& E, const int tid) {
;     ...
;             PG8_BAR; PG8_WAIT_L(0); PG8_MMA(0, 1, At, B1); PG8_BAR;
;             PG8_LDA(At, 1, 1); PG8_STAGE(PG8_SA(1, 0), a3, voffA);
;             PG8_BAR; PG8_WAIT_L(0); PG8_MMA(1, 0, At, B0); PG8_BAR; PG8_SCHED;
;             PG8_STAGE(PG8_SB(1, 1), b3 + hstepB, voffB);
;             PG8_WAIT_V(6); PG8_BAR; PG8_MMA(1, 1, At, B1); PG8_BAR;
	s_waitcnt lgkmcnt(0)
	s_setprio 0
	s_waitcnt lgkmcnt(0)
	v_mfma_f32_16x16x32_bf16 v[120:123], v[228:231], v[196:199], v[120:123]
	v_mfma_f32_16x16x32_bf16 v[116:119], v[236:239], v[196:199], v[116:119]
	v_mfma_f32_16x16x32_bf16 v[104:107], v[228:231], v[204:207], v[104:107]
	v_mfma_f32_16x16x32_bf16 v[100:103], v[236:239], v[204:207], v[100:103]
	v_mfma_f32_16x16x32_bf16 v[88:91], v[228:231], v[212:215], v[88:91]
	v_mfma_f32_16x16x32_bf16 v[84:87], v[236:239], v[212:215], v[84:87]
	v_mfma_f32_16x16x32_bf16 v[72:75], v[228:231], v[220:223], v[72:75]
	v_mfma_f32_16x16x32_bf16 v[68:71], v[236:239], v[220:223], v[68:71]
	v_mfma_f32_16x16x32_bf16 v[120:123], v[232:235], v[200:203], v[120:123]
	v_mfma_f32_16x16x32_bf16 v[116:119], v[240:243], v[200:203], v[116:119]
	v_mfma_f32_16x16x32_bf16 v[104:107], v[232:235], v[208:211], v[104:107]
	v_mfma_f32_16x16x32_bf16 v[100:103], v[240:243], v[208:211], v[100:103]
	v_mfma_f32_16x16x32_bf16 v[88:91], v[232:235], v[216:219], v[88:91]
	v_mfma_f32_16x16x32_bf16 v[84:87], v[240:243], v[216:219], v[84:87]
	v_mfma_f32_16x16x32_bf16 v[72:75], v[232:235], v[224:227], v[72:75]
	v_mfma_f32_16x16x32_bf16 v[68:71], v[240:243], v[224:227], v[68:71]
	s_setprio 1
	s_mov_b32 m0, s47
	v_lshl_add_u64 v[0:1], v[246:247], 0, s[30:31]
	s_barrier
	ds_read_b128 v[196:199], v191 offset:49152
	ds_read_b128 v[200:203], v191 offset:50176
	ds_read_b128 v[204:207], v191 offset:51200
	ds_read_b128 v[208:211], v191 offset:52224
	ds_read_b128 v[212:215], v191 offset:53248
	ds_read_b128 v[216:219], v191 offset:54272
	ds_read_b128 v[220:223], v191 offset:55296
	ds_read_b128 v[224:227], v191 offset:56320
	global_load_lds_dwordx4 v[0:1], off
	v_lshl_add_u64 v[0:1], v[248:249], 0, s[30:31]
	s_mov_b32 m0, s48
	s_nop 0
	global_load_lds_dwordx4 v[0:1], off
	s_barrier
	s_waitcnt lgkmcnt(0)
	s_setprio 0
	s_waitcnt lgkmcnt(0)
	v_mfma_f32_16x16x32_bf16 v[64:67], v[132:135], v[196:199], v[64:67]
	v_mfma_f32_16x16x32_bf16 v[60:63], v[176:179], v[196:199], v[60:63]
	v_mfma_f32_16x16x32_bf16 v[48:51], v[132:135], v[204:207], v[48:51]
	v_mfma_f32_16x16x32_bf16 v[44:47], v[176:179], v[204:207], v[44:47]
	v_mfma_f32_16x16x32_bf16 v[32:35], v[132:135], v[212:215], v[32:35]
	v_mfma_f32_16x16x32_bf16 v[28:31], v[176:179], v[212:215], v[28:31]
	v_mfma_f32_16x16x32_bf16 v[16:19], v[132:135], v[220:223], v[16:19]
	v_mfma_f32_16x16x32_bf16 v[12:15], v[176:179], v[220:223], v[12:15]
	v_mfma_f32_16x16x32_bf16 v[64:67], v[136:139], v[200:203], v[64:67]
	v_mfma_f32_16x16x32_bf16 v[60:63], v[192:195], v[200:203], v[60:63]
	v_mfma_f32_16x16x32_bf16 v[48:51], v[136:139], v[208:211], v[48:51]
	v_mfma_f32_16x16x32_bf16 v[44:47], v[192:195], v[208:211], v[44:47]
	v_mfma_f32_16x16x32_bf16 v[32:35], v[136:139], v[216:219], v[32:35]
	v_mfma_f32_16x16x32_bf16 v[28:31], v[192:195], v[216:219], v[28:31]
	v_mfma_f32_16x16x32_bf16 v[16:19], v[136:139], v[224:227], v[16:19]
	v_mfma_f32_16x16x32_bf16 v[12:15], v[192:195], v[224:227], v[12:15]
	s_setprio 1
	s_barrier
	s_add_u32 s14, s14, 0x100080
	s_addc_u32 s15, s15, 0
	s_add_i32 s18, s18, s24
	v_lshl_add_u64 v[0:1], s[14:15], 0, v[144:145]
	s_mov_b32 m0, s18
	s_nop 0
	global_load_lds_dwordx4 v[0:1], off
	v_lshl_add_u64 v[0:1], s[14:15], 0, v[140:141]
	s_add_i32 m0, s18, 0x2000
	s_nop 0
	global_load_lds_dwordx4 v[0:1], off
	s_waitcnt vmcnt(6)
	s_barrier
	s_setprio 0
	v_mfma_f32_16x16x32_bf16 v[56:59], v[228:231], v[196:199], v[56:59]
	v_mfma_f32_16x16x32_bf16 v[52:55], v[236:239], v[196:199], v[52:55]
	v_mfma_f32_16x16x32_bf16 v[40:43], v[228:231], v[204:207], v[40:43]
	v_mfma_f32_16x16x32_bf16 v[36:39], v[236:239], v[204:207], v[36:39]
	v_mfma_f32_16x16x32_bf16 v[24:27], v[228:231], v[212:215], v[24:27]
	v_mfma_f32_16x16x32_bf16 v[20:23], v[236:239], v[212:215], v[20:23]
	v_mfma_f32_16x16x32_bf16 v[8:11], v[228:231], v[220:223], v[8:11]
	v_mfma_f32_16x16x32_bf16 v[4:7], v[236:239], v[220:223], v[4:7]
	v_mfma_f32_16x16x32_bf16 v[56:59], v[232:235], v[200:203], v[56:59]
	v_mfma_f32_16x16x32_bf16 v[52:55], v[240:243], v[200:203], v[52:55]
	v_mfma_f32_16x16x32_bf16 v[40:43], v[232:235], v[208:211], v[40:43]
	v_mfma_f32_16x16x32_bf16 v[36:39], v[240:243], v[208:211], v[36:39]
	v_mfma_f32_16x16x32_bf16 v[24:27], v[232:235], v[216:219], v[24:27]
	v_mfma_f32_16x16x32_bf16 v[20:23], v[240:243], v[216:219], v[20:23]
	v_mfma_f32_16x16x32_bf16 v[8:11], v[232:235], v[224:227], v[8:11]
	v_mfma_f32_16x16x32_bf16 v[4:7], v[240:243], v[224:227], v[4:7]
	s_setprio 1
	s_add_i32 s54, s54, 2
	s_add_u32 s12, s12, 0x100
	s_addc_u32 s13, s13, 0
	s_cmp_gt_u32 s54, 61
	s_barrier
	s_cbranch_scc1 .LBB0_586

; #define PG8_STAGE(bufoff, gbase, voff) do { _Pragma("unroll") for (int _i = 0; _i < 2; ++_i) \
;         __builtin_amdgcn_global_load_lds((const unsigned*)((const char*)(gbase) + (voff)[_i]), (LAS unsigned*)(lds + (bufoff) + ldsw + _i * 8192), 16, 0, 0); } while (0)
; #define PG8_LDA(dst, b, h) do { _Pragma("unroll") for (int m = 0; m < 4; ++m) _Pragma("unroll") for (int k = 0; k < 2; ++k) dst[m][k] = *(const LAS h8*)(lds + PG8_SA(b, h) + aoff + m * 2048 + k * 1024); } while (0)
; #define PG8_LDB(dst, b, h) do { _Pragma("unroll") for (int n = 0; n < 2; ++n) _Pragma("unroll") for (int k = 0; k < 2; ++k) dst[n][k] = *(const LAS h8*)(lds + PG8_SB(b, h) + boff + n * 2048 + k * 1024); } while (0)
; #define PG8_WAIT_L(n) asm volatile("s_waitcnt lgkmcnt(" #n ")" ::: "memory")
; #define PG8_BAR __builtin_amdgcn_s_barrier()
; #define PG8_SCHED __builtin_amdgcn_sched_barrier(0)
; template <class Epi>
; __device__ __forceinline__ void gemm_phase(LAS unsigned char* lds, const Gemm g, const StaticOrder& S, const Epi& E, const int tid) {
;     ...
;         for (int t = 0; t < nt; t += 2) {
;             const bool last = (t == nt - 2);
;             const char* a1 = cA + (size_t)(t + 1) * kstep;
;             const char* a2 = last ? nA : cA + (size_t)(t + 2) * kstep; const char* b2 = last ? nB : cB + (size_t)(t + 2) * kstep;
;             const char* a3 = a2 + kstep; const char* b3 = b2 + kstep;
;             if constexpr (Epi::HAS_MID) { if (t == (nt >> 1)) E.mid(acc, cur, wr, wc, fr, fq); }
;             PG8_LDB(B0, 0, 0); PG8_SCHED; PG8_LDA(At, 0, 0); PG8_STAGE(PG8_SA(1, 1), a1 + hstep, voffA);
;             PG8_WAIT_L(8); PG8_BAR; PG8_WAIT_L(0); PG8_MMA(0, 0, At, B0); PG8_BAR; PG8_SCHED;
;             PG8_LDB(B1, 0, 1); PG8_STAGE(PG8_SB(0, 0), b2, voffB);
;             PG8_BAR; PG8_WAIT_L(0); PG8_MMA(0, 1, At, B1); PG8_BAR;
.LBB0_660:
	s_add_u32 s14, s12, 0xfff80080
	s_addc_u32 s15, s13, -1
	s_add_i32 s57, 0, 0x10000
	v_add_u32_e32 v64, s57, v190
	ds_read_b128 v[28:31], v64
	ds_read_b128 v[32:35], v64 offset:1024
	ds_read_b128 v[60:63], v64 offset:2048
	ds_read_b128 v[64:67], v64 offset:3072
	s_cmp_eq_u32 s56, 28
	s_cselect_b32 s19, s7, s15
	s_cselect_b32 s18, s52, s14
	s_cselect_b32 s15, s1, s55
	s_cselect_b32 s14, s53, s54
	v_lshl_add_u64 v[174:175], s[12:13], 0, v[166:167]
	s_add_i32 m0, s41, 0xc000
	ds_read_b128 v[170:173], v192
	ds_read_b128 v[194:197], v192 offset:1024
	ds_read_b128 v[198:201], v192 offset:2048
	ds_read_b128 v[202:205], v192 offset:3072
	ds_read_b128 v[206:209], v192 offset:4096
	ds_read_b128 v[210:213], v192 offset:5120
	ds_read_b128 v[214:217], v192 offset:6144
	ds_read_b128 v[218:221], v192 offset:7168
	global_load_lds_dwordx4 v[174:175], off
	v_lshl_add_u64 v[174:175], s[12:13], 0, v[168:169]
	s_add_i32 m0, s41, 0xe000
	s_nop 0
	global_load_lds_dwordx4 v[174:175], off
	s_waitcnt lgkmcnt(8)
	s_barrier
	s_waitcnt lgkmcnt(0)
	s_setprio 0
	s_waitcnt lgkmcnt(0)
	v_mfma_f32_16x16x32_bf16 v[144:147], v[28:31], v[170:173], v[144:147]
	v_mfma_f32_16x16x32_bf16 v[140:143], v[60:63], v[170:173], v[140:143]
	v_mfma_f32_16x16x32_bf16 v[128:131], v[28:31], v[198:201], v[128:131]
	v_mfma_f32_16x16x32_bf16 v[124:127], v[60:63], v[198:201], v[124:127]
	v_mfma_f32_16x16x32_bf16 v[112:115], v[28:31], v[206:209], v[112:115]
	v_mfma_f32_16x16x32_bf16 v[108:111], v[60:63], v[206:209], v[108:111]
	v_mfma_f32_16x16x32_bf16 v[96:99], v[28:31], v[214:217], v[96:99]
	v_mfma_f32_16x16x32_bf16 v[92:95], v[60:63], v[214:217], v[92:95]
	v_mfma_f32_16x16x32_bf16 v[144:147], v[32:35], v[194:197], v[144:147]
	v_mfma_f32_16x16x32_bf16 v[140:143], v[64:67], v[194:197], v[140:143]
	v_mfma_f32_16x16x32_bf16 v[128:131], v[32:35], v[202:205], v[128:131]
	v_mfma_f32_16x16x32_bf16 v[124:127], v[64:67], v[202:205], v[124:127]
	v_mfma_f32_16x16x32_bf16 v[112:115], v[32:35], v[210:213], v[112:115]
	v_mfma_f32_16x16x32_bf16 v[108:111], v[64:67], v[210:213], v[108:111]
	v_mfma_f32_16x16x32_bf16 v[96:99], v[32:35], v[218:221], v[96:99]
	v_mfma_f32_16x16x32_bf16 v[92:95], v[64:67], v[218:221], v[92:95]
	s_setprio 1
	s_barrier
	s_add_i32 s60, 0, 0x14000
	v_add_u32_e32 v174, s60, v190
	s_add_i32 s57, s57, s40
	ds_read_b128 v[222:225], v174
	ds_read_b128 v[226:229], v174 offset:1024
	ds_read_b128 v[230:233], v174 offset:2048
	ds_read_b128 v[234:237], v174 offset:3072
	v_lshl_add_u64 v[174:175], s[14:15], 0, v[2:3]
	s_mov_b32 m0, s57
	v_lshl_add_u64 v[238:239], s[14:15], 0, v[0:1]
	global_load_lds_dwordx4 v[174:175], off
	s_add_i32 m0, s57, 0x2000
	s_nop 0
	global_load_lds_dwordx4 v[238:239], off
	s_barrier
	s_waitcnt lgkmcnt(0)
	s_setprio 0
	s_waitcnt lgkmcnt(0)
	v_mfma_f32_16x16x32_bf16 v[136:139], v[222:225], v[170:173], v[136:139]
	v_mfma_f32_16x16x32_bf16 v[132:135], v[230:233], v[170:173], v[132:135]
	v_mfma_f32_16x16x32_bf16 v[120:123], v[222:225], v[198:201], v[120:123]
	v_mfma_f32_16x16x32_bf16 v[116:119], v[230:233], v[198:201], v[116:119]
	v_mfma_f32_16x16x32_bf16 v[104:107], v[222:225], v[206:209], v[104:107]
	v_mfma_f32_16x16x32_bf16 v[100:103], v[230:233], v[206:209], v[100:103]
	v_mfma_f32_16x16x32_bf16 v[88:91], v[222:225], v[214:217], v[88:91]
	v_mfma_f32_16x16x32_bf16 v[84:87], v[230:233], v[214:217], v[84:87]
	v_mfma_f32_16x16x32_bf16 v[136:139], v[226:229], v[194:197], v[136:139]
	v_mfma_f32_16x16x32_bf16 v[132:135], v[234:237], v[194:197], v[132:135]
	v_mfma_f32_16x16x32_bf16 v[120:123], v[226:229], v[202:205], v[120:123]
	v_mfma_f32_16x16x32_bf16 v[116:119], v[234:237], v[202:205], v[116:119]
	v_mfma_f32_16x16x32_bf16 v[104:107], v[226:229], v[210:213], v[104:107]
	v_mfma_f32_16x16x32_bf16 v[100:103], v[234:237], v[210:213], v[100:103]
	v_mfma_f32_16x16x32_bf16 v[88:91], v[226:229], v[218:221], v[88:91]
	v_mfma_f32_16x16x32_bf16 v[84:87], v[234:237], v[218:221], v[84:87]
	s_setprio 1
	s_mov_b32 m0, s41
	v_lshl_add_u64 v[240:241], s[18:19], 0, v[164:165]
	s_barrier
	ds_read_b128 v[170:173], v192 offset:16384
	ds_read_b128 v[194:197], v192 offset:17408
	ds_read_b128 v[198:201], v192 offset:18432
	ds_read_b128 v[202:205], v192 offset:19456
	ds_read_b128 v[206:209], v192 offset:20480
	ds_read_b128 v[210:213], v192 offset:21504
	ds_read_b128 v[214:217], v192 offset:22528
	ds_read_b128 v[218:221], v192 offset:23552
	global_load_lds_dwordx4 v[240:241], off
	v_lshl_add_u64 v[242:243], s[18:19], 0, v[162:163]
	s_mov_b32 m0, s42
	s_nop 0
	global_load_lds_dwordx4 v[242:243], off
	s_barrier
	s_waitcnt lgkmcnt(0)
	s_setprio 0
	s_waitcnt lgkmcnt(0)
	v_mfma_f32_16x16x32_bf16 v[80:83], v[28:31], v[170:173], v[80:83]
	v_mfma_f32_16x16x32_bf16 v[76:79], v[60:63], v[170:173], v[76:79]
	v_mfma_f32_16x16x32_bf16 v[56:59], v[28:31], v[198:201], v[56:59]
	v_mfma_f32_16x16x32_bf16 v[52:55], v[60:63], v[198:201], v[52:55]
	v_mfma_f32_16x16x32_bf16 v[40:43], v[28:31], v[206:209], v[40:43]
	v_mfma_f32_16x16x32_bf16 v[36:39], v[60:63], v[206:209], v[36:39]
	v_mfma_f32_16x16x32_bf16 v[16:19], v[28:31], v[214:217], v[16:19]
	v_mfma_f32_16x16x32_bf16 v[12:15], v[60:63], v[214:217], v[12:15]
	v_mfma_f32_16x16x32_bf16 v[80:83], v[32:35], v[194:197], v[80:83]
	v_mfma_f32_16x16x32_bf16 v[76:79], v[64:67], v[194:197], v[76:79]
	v_mfma_f32_16x16x32_bf16 v[56:59], v[32:35], v[202:205], v[56:59]
	v_mfma_f32_16x16x32_bf16 v[52:55], v[64:67], v[202:205], v[52:55]
	v_mfma_f32_16x16x32_bf16 v[40:43], v[32:35], v[210:213], v[40:43]
	v_mfma_f32_16x16x32_bf16 v[36:39], v[64:67], v[210:213], v[36:39]
	v_mfma_f32_16x16x32_bf16 v[16:19], v[32:35], v[218:221], v[16:19]
	v_mfma_f32_16x16x32_bf16 v[12:15], v[64:67], v[218:221], v[12:15]
	s_setprio 1
	s_barrier
; #define PG8_STAGE(bufoff, gbase, voff) do { _Pragma("unroll") for (int _i = 0; _i < 2; ++_i) \
;         __builtin_amdgcn_global_load_lds((const unsigned*)((const char*)(gbase) + (voff)[_i]), (LAS unsigned*)(lds + (bufoff) + ldsw + _i * 8192), 16, 0, 0); } while (0)
; #define PG8_LDA(dst, b, h) do { _Pragma("unroll") for (int m = 0; m < 4; ++m) _Pragma("unroll") for (int k = 0; k < 2; ++k) dst[m][k] = *(const LAS h8*)(lds + PG8_SA(b, h) + aoff + m * 2048 + k * 1024); } while (0)
; #define PG8_LDB(dst, b, h) do { _Pragma("unroll") for (int n = 0; n < 2; ++n) _Pragma("unroll") for (int k = 0; k < 2; ++k) dst[n][k] = *(const LAS h8*)(lds + PG8_SB(b, h) + boff + n * 2048 + k * 1024); } while (0)
; #define PG8_WAIT_V(n) asm volatile("s_waitcnt vmcnt(" #n ")" ::: "memory")
; #define PG8_WAIT_L(n) asm volatile("s_waitcnt lgkmcnt(" #n ")" ::: "memory")
; #define PG8_BAR __builtin_amdgcn_s_barrier()
; #define PG8_SCHED __builtin_amdgcn_sched_barrier(0)
; template <class Epi>
; __device__ __forceinline__ void gemm_phase(LAS unsigned char* lds, const Gemm g, const StaticOrder& S, const Epi& E, const int tid) {
;     ...
;             PG8_STAGE(PG8_SB(0, 1), b2 + hstepB, voffB);
;             PG8_WAIT_V(6); PG8_BAR; PG8_MMA(1, 1, At, B1); PG8_BAR;
;             PG8_LDB(B0, 1, 0); PG8_SCHED; PG8_LDA(At, 1, 0); PG8_STAGE(PG8_SA(0, 1), a2 + hstep, voffA);
;             PG8_WAIT_L(8); PG8_BAR; PG8_WAIT_L(0); PG8_MMA(0, 0, At, B0); PG8_BAR; PG8_SCHED;
;             PG8_LDB(B1, 1, 1); PG8_STAGE(PG8_SB(1, 0), b3, voffB);
;             PG8_BAR; PG8_WAIT_L(0); PG8_MMA(0, 1, At, B1); PG8_BAR;
;             PG8_LDA(At, 1, 1); PG8_STAGE(PG8_SA(1, 0), a3, voffA);
;             PG8_BAR; PG8_WAIT_L(0); PG8_MMA(1, 0, At, B0); PG8_BAR; PG8_SCHED;
;             PG8_STAGE(PG8_SB(1, 1), b3 + hstepB, voffB);
	s_add_u32 s58, s14, 0x80000
	s_addc_u32 s59, s15, 0
	s_add_i32 s57, s60, s40
	v_lshl_add_u64 v[28:29], s[58:59], 0, v[2:3]
	s_mov_b32 m0, s57
	s_nop 0
	global_load_lds_dwordx4 v[28:29], off
	v_lshl_add_u64 v[28:29], s[58:59], 0, v[0:1]
	s_add_i32 m0, s57, 0x2000
	s_nop 0
	global_load_lds_dwordx4 v[28:29], off
	s_waitcnt vmcnt(6)
	s_barrier
	s_setprio 0
	v_mfma_f32_16x16x32_bf16 v[48:51], v[222:225], v[198:201], v[48:51]
	v_mfma_f32_16x16x32_bf16 v[44:47], v[230:233], v[198:201], v[44:47]
	v_mfma_f32_16x16x32_bf16 v[24:27], v[222:225], v[206:209], v[24:27]
	v_mfma_f32_16x16x32_bf16 v[20:23], v[230:233], v[206:209], v[20:23]
	v_mfma_f32_16x16x32_bf16 v[8:11], v[222:225], v[214:217], v[8:11]
	v_mfma_f32_16x16x32_bf16 v[4:7], v[230:233], v[214:217], v[4:7]
	v_mfma_f32_16x16x32_bf16 v[28:31], v[222:225], v[170:173], v[72:75]
	v_mfma_f32_16x16x32_bf16 v[32:35], v[230:233], v[170:173], v[68:71]
	v_mfma_f32_16x16x32_bf16 v[48:51], v[226:229], v[202:205], v[48:51]
	v_mfma_f32_16x16x32_bf16 v[44:47], v[234:237], v[202:205], v[44:47]
	v_mfma_f32_16x16x32_bf16 v[24:27], v[226:229], v[210:213], v[24:27]
	v_mfma_f32_16x16x32_bf16 v[20:23], v[234:237], v[210:213], v[20:23]
	v_mfma_f32_16x16x32_bf16 v[8:11], v[226:229], v[218:221], v[8:11]
	v_mfma_f32_16x16x32_bf16 v[4:7], v[234:237], v[218:221], v[4:7]
	v_mfma_f32_16x16x32_bf16 v[28:31], v[226:229], v[194:197], v[28:31]
	v_mfma_f32_16x16x32_bf16 v[32:35], v[234:237], v[194:197], v[32:35]
	s_setprio 1
	s_add_i32 s57, 0, 0x18000
	v_add_u32_e32 v72, s57, v190
	s_barrier
	ds_read_b128 v[60:63], v72
	ds_read_b128 v[64:67], v72 offset:1024
	ds_read_b128 v[68:71], v72 offset:2048
	ds_read_b128 v[72:75], v72 offset:3072
	s_add_u32 s18, s18, 0x80000
	s_addc_u32 s19, s19, 0
	s_mov_b32 m0, s43
	v_lshl_add_u64 v[222:223], s[18:19], 0, v[164:165]
	ds_read_b128 v[170:173], v192 offset:32768
	ds_read_b128 v[194:197], v192 offset:33792
	ds_read_b128 v[198:201], v192 offset:34816
	ds_read_b128 v[202:205], v192 offset:35840
	ds_read_b128 v[206:209], v192 offset:36864
	ds_read_b128 v[210:213], v192 offset:37888
	ds_read_b128 v[214:217], v192 offset:38912
	ds_read_b128 v[218:221], v192 offset:39936
	global_load_lds_dwordx4 v[222:223], off
	v_lshl_add_u64 v[222:223], s[18:19], 0, v[162:163]
	s_mov_b32 m0, s46
	s_nop 0
	global_load_lds_dwordx4 v[222:223], off
	s_waitcnt lgkmcnt(8)
	s_barrier
	s_waitcnt lgkmcnt(0)
	s_setprio 0
	s_waitcnt lgkmcnt(0)
	v_mfma_f32_16x16x32_bf16 v[144:147], v[60:63], v[170:173], v[144:147]
	v_mfma_f32_16x16x32_bf16 v[140:143], v[68:71], v[170:173], v[140:143]
	v_mfma_f32_16x16x32_bf16 v[128:131], v[60:63], v[198:201], v[128:131]
	v_mfma_f32_16x16x32_bf16 v[124:127], v[68:71], v[198:201], v[124:127]
	v_mfma_f32_16x16x32_bf16 v[112:115], v[60:63], v[206:209], v[112:115]
	v_mfma_f32_16x16x32_bf16 v[108:111], v[68:71], v[206:209], v[108:111]
	v_mfma_f32_16x16x32_bf16 v[96:99], v[60:63], v[214:217], v[96:99]
	v_mfma_f32_16x16x32_bf16 v[92:95], v[68:71], v[214:217], v[92:95]
	v_mfma_f32_16x16x32_bf16 v[144:147], v[64:67], v[194:197], v[144:147]
	v_mfma_f32_16x16x32_bf16 v[140:143], v[72:75], v[194:197], v[140:143]
	v_mfma_f32_16x16x32_bf16 v[128:131], v[64:67], v[202:205], v[128:131]
	v_mfma_f32_16x16x32_bf16 v[124:127], v[72:75], v[202:205], v[124:127]
	v_mfma_f32_16x16x32_bf16 v[112:115], v[64:67], v[210:213], v[112:115]
	v_mfma_f32_16x16x32_bf16 v[108:111], v[72:75], v[210:213], v[108:111]
	v_mfma_f32_16x16x32_bf16 v[96:99], v[64:67], v[218:221], v[96:99]
	v_mfma_f32_16x16x32_bf16 v[92:95], v[72:75], v[218:221], v[92:95]
	s_setprio 1
	s_barrier
	s_add_i32 s18, 0, 0x1c000
	s_add_i32 s19, s57, s40
	v_add_u32_e32 v193, s18, v190
	v_lshl_add_u64 v[174:175], v[174:175], 0, s[30:31]
	s_mov_b32 m0, s19
	ds_read_b128 v[222:225], v193
	ds_read_b128 v[226:229], v193 offset:1024
	ds_read_b128 v[230:233], v193 offset:2048
	ds_read_b128 v[234:237], v193 offset:3072
	global_load_lds_dwordx4 v[174:175], off
	v_lshl_add_u64 v[174:175], v[238:239], 0, s[30:31]
	s_add_i32 m0, s19, 0x2000
	s_nop 0
	global_load_lds_dwordx4 v[174:175], off
	s_barrier
	s_waitcnt lgkmcnt(0)
	s_setprio 0
	s_waitcnt lgkmcnt(0)
	v_mfma_f32_16x16x32_bf16 v[136:139], v[222:225], v[170:173], v[136:139]
	v_mfma_f32_16x16x32_bf16 v[132:135], v[230:233], v[170:173], v[132:135]
	v_mfma_f32_16x16x32_bf16 v[120:123], v[222:225], v[198:201], v[120:123]
	v_mfma_f32_16x16x32_bf16 v[116:119], v[230:233], v[198:201], v[116:119]
	v_mfma_f32_16x16x32_bf16 v[104:107], v[222:225], v[206:209], v[104:107]
	v_mfma_f32_16x16x32_bf16 v[100:103], v[230:233], v[206:209], v[100:103]
	v_mfma_f32_16x16x32_bf16 v[88:91], v[222:225], v[214:217], v[88:91]
	v_mfma_f32_16x16x32_bf16 v[84:87], v[230:233], v[214:217], v[84:87]
	v_mfma_f32_16x16x32_bf16 v[136:139], v[226:229], v[194:197], v[136:139]
	v_mfma_f32_16x16x32_bf16 v[132:135], v[234:237], v[194:197], v[132:135]
	v_mfma_f32_16x16x32_bf16 v[120:123], v[226:229], v[202:205], v[120:123]
	v_mfma_f32_16x16x32_bf16 v[116:119], v[234:237], v[202:205], v[116:119]
	v_mfma_f32_16x16x32_bf16 v[104:107], v[226:229], v[210:213], v[104:107]
	v_mfma_f32_16x16x32_bf16 v[100:103], v[234:237], v[210:213], v[100:103]
	v_mfma_f32_16x16x32_bf16 v[88:91], v[226:229], v[218:221], v[88:91]
	v_mfma_f32_16x16x32_bf16 v[84:87], v[234:237], v[218:221], v[84:87]
	s_setprio 1
	s_mov_b32 m0, s47
	v_lshl_add_u64 v[174:175], v[240:241], 0, s[30:31]
	s_barrier
	ds_read_b128 v[170:173], v192 offset:49152
	ds_read_b128 v[194:197], v192 offset:50176
	ds_read_b128 v[198:201], v192 offset:51200
	ds_read_b128 v[202:205], v192 offset:52224
	ds_read_b128 v[206:209], v192 offset:53248
	ds_read_b128 v[210:213], v192 offset:54272
	ds_read_b128 v[214:217], v192 offset:55296
	ds_read_b128 v[218:221], v192 offset:56320
	global_load_lds_dwordx4 v[174:175], off
	v_lshl_add_u64 v[174:175], v[242:243], 0, s[30:31]
	s_mov_b32 m0, s48
	s_nop 0
	global_load_lds_dwordx4 v[174:175], off
	s_barrier
; #define PG8_STAGE(bufoff, gbase, voff) do { _Pragma("unroll") for (int _i = 0; _i < 2; ++_i) \
;         __builtin_amdgcn_global_load_lds((const unsigned*)((const char*)(gbase) + (voff)[_i]), (LAS unsigned*)(lds + (bufoff) + ldsw + _i * 8192), 16, 0, 0); } while (0)
; #define PG8_LDA(dst, b, h) do { _Pragma("unroll") for (int m = 0; m < 4; ++m) _Pragma("unroll") for (int k = 0; k < 2; ++k) dst[m][k] = *(const LAS h8*)(lds + PG8_SA(b, h) + aoff + m * 2048 + k * 1024); } while (0)
; #define PG8_WAIT_V(n) asm volatile("s_waitcnt vmcnt(" #n ")" ::: "memory")
; #define PG8_WAIT_L(n) asm volatile("s_waitcnt lgkmcnt(" #n ")" ::: "memory")
; #define PG8_BAR __builtin_amdgcn_s_barrier()
; #define PG8_SCHED __builtin_amdgcn_sched_barrier(0)
; template <class Epi>
; __device__ __forceinline__ void gemm_phase(LAS unsigned char* lds, const Gemm g, const StaticOrder& S, const Epi& E, const int tid) {
;     ...
;             PG8_LDA(At, 1, 1); PG8_STAGE(PG8_SA(1, 0), a3, voffA);
;             PG8_BAR; PG8_WAIT_L(0); PG8_MMA(1, 0, At, B0); PG8_BAR; PG8_SCHED;
;             PG8_STAGE(PG8_SB(1, 1), b3 + hstepB, voffB);
;             PG8_WAIT_V(6); PG8_BAR; PG8_MMA(1, 1, At, B1); PG8_BAR;
;     __device__ __forceinline__ void operator()(const f32x4 (&acc)[2][2][4][2], const pg8::Unit& u, int wr, int wc, int fr, int fq) const {
;         const int row0 = u.pm * 256 + wr * 64 + fr, col0 = u.pn * 256 + wc * 32 + 8 * fq;
;         const float* gp = gate + (size_t)((u.pm * 256) >> 12) * 6144 + col0;
;         f32x4 gv[2][2];
; #pragma unroll
;         for (int bj = 0; bj < 2; ++bj)
; #pragma unroll
;             for (int n = 0; n < 2; ++n) gv[bj][n] = *(const f32x4*)(gp + bj * 128 + 4 * n);
; #pragma unroll
;         for (int ai = 0; ai < 2; ++ai)
; #pragma unroll
;             for (int m = 0; m < 4; ++m) { const size_t ro = (size_t)(row0 + ai * 128 + m * 16) * DM + col0;
; #pragma unroll
;                 for (int bj = 0; bj < 2; ++bj) {
;                     f32x4 x0, x1;
;                     if (XF32) { x0 = *(const f32x4*)(xin + ro + bj * 128); x1 = *(const f32x4*)(xin + ro + bj * 128 + 4); }
;                     else { const h8 xh = *(const h8*)(H + ro + bj * 128); x0 = (f32x4){(float)xh[0], (float)xh[1], (float)xh[2], (float)xh[3]}; x1 = (f32x4){(float)xh[4], (float)xh[5], (float)xh[6], (float)xh[7]}; }
	s_waitcnt lgkmcnt(0)
	s_setprio 0
	s_waitcnt lgkmcnt(0)
	v_mfma_f32_16x16x32_bf16 v[80:83], v[60:63], v[170:173], v[80:83]
	v_mfma_f32_16x16x32_bf16 v[76:79], v[68:71], v[170:173], v[76:79]
	v_mfma_f32_16x16x32_bf16 v[56:59], v[60:63], v[198:201], v[56:59]
	v_mfma_f32_16x16x32_bf16 v[52:55], v[68:71], v[198:201], v[52:55]
	v_mfma_f32_16x16x32_bf16 v[40:43], v[60:63], v[206:209], v[40:43]
	v_mfma_f32_16x16x32_bf16 v[36:39], v[68:71], v[206:209], v[36:39]
	v_mfma_f32_16x16x32_bf16 v[16:19], v[60:63], v[214:217], v[16:19]
	v_mfma_f32_16x16x32_bf16 v[12:15], v[68:71], v[214:217], v[12:15]
	v_mfma_f32_16x16x32_bf16 v[80:83], v[64:67], v[194:197], v[80:83]
	v_mfma_f32_16x16x32_bf16 v[76:79], v[72:75], v[194:197], v[76:79]
	v_mfma_f32_16x16x32_bf16 v[56:59], v[64:67], v[202:205], v[56:59]
	v_mfma_f32_16x16x32_bf16 v[52:55], v[72:75], v[202:205], v[52:55]
	v_mfma_f32_16x16x32_bf16 v[40:43], v[64:67], v[210:213], v[40:43]
	v_mfma_f32_16x16x32_bf16 v[36:39], v[72:75], v[210:213], v[36:39]
	v_mfma_f32_16x16x32_bf16 v[16:19], v[64:67], v[218:221], v[16:19]
	v_mfma_f32_16x16x32_bf16 v[12:15], v[72:75], v[218:221], v[12:15]
	s_setprio 1
	s_barrier
	s_add_u32 s14, s14, 0x80080
	s_addc_u32 s15, s15, 0
	s_add_i32 s18, s18, s40
	v_lshl_add_u64 v[60:61], s[14:15], 0, v[2:3]
	s_mov_b32 m0, s18
	s_nop 0
	global_load_lds_dwordx4 v[60:61], off
	v_lshl_add_u64 v[60:61], s[14:15], 0, v[0:1]
	s_add_i32 m0, s18, 0x2000
	s_nop 0
	global_load_lds_dwordx4 v[60:61], off
	s_waitcnt vmcnt(6)
	s_barrier
	s_setprio 0
	v_mfma_f32_16x16x32_bf16 v[28:31], v[222:225], v[170:173], v[28:31]
	v_mfma_f32_16x16x32_bf16 v[72:75], v[226:229], v[194:197], v[28:31]
	v_mfma_f32_16x16x32_bf16 v[28:31], v[230:233], v[170:173], v[32:35]
	v_mfma_f32_16x16x32_bf16 v[68:71], v[234:237], v[194:197], v[28:31]
	v_mfma_f32_16x16x32_bf16 v[28:31], v[222:225], v[198:201], v[48:51]
	v_mfma_f32_16x16x32_bf16 v[48:51], v[226:229], v[202:205], v[28:31]
	v_mfma_f32_16x16x32_bf16 v[28:31], v[230:233], v[198:201], v[44:47]
	v_mfma_f32_16x16x32_bf16 v[24:27], v[222:225], v[206:209], v[24:27]
	v_mfma_f32_16x16x32_bf16 v[20:23], v[230:233], v[206:209], v[20:23]
	v_mfma_f32_16x16x32_bf16 v[8:11], v[222:225], v[214:217], v[8:11]
	v_mfma_f32_16x16x32_bf16 v[4:7], v[230:233], v[214:217], v[4:7]
	v_mfma_f32_16x16x32_bf16 v[44:47], v[234:237], v[202:205], v[28:31]
	v_mfma_f32_16x16x32_bf16 v[24:27], v[226:229], v[210:213], v[24:27]
	v_mfma_f32_16x16x32_bf16 v[20:23], v[234:237], v[210:213], v[20:23]
	v_mfma_f32_16x16x32_bf16 v[8:11], v[226:229], v[218:221], v[8:11]
	v_mfma_f32_16x16x32_bf16 v[4:7], v[234:237], v[218:221], v[4:7]
	s_setprio 1
	s_add_i32 s56, s56, 2
	s_add_u32 s12, s12, 0x100
	s_addc_u32 s13, s13, 0
	s_add_u32 s54, s54, 0x100
	s_addc_u32 s55, s55, 0
	s_cmp_gt_u32 s56, 29
	s_barrier
	s_cbranch_scc0 .LBB0_660
	s_ashr_i32 s1, s50, 4
	v_lshl_add_u32 v172, s50, 8, v189
	v_lshl_or_b32 v170, s51, 8, v191
	s_mul_hi_i32 s7, s1, 0x6000
	s_mulk_i32 s1, 0x6000
	v_ashrrev_i32_e32 v173, 31, v172
	s_add_u32 s12, s23, s1
	v_ashrrev_i32_e32 v171, 31, v170
	v_lshlrev_b64 v[174:175], 12, v[172:173]
	s_addc_u32 s13, s24, s7
	v_lshl_add_u64 v[194:195], s[16:17], 0, v[174:175]
	v_lshlrev_b64 v[174:175], 1, v[170:171]
	v_lshl_add_u64 v[32:33], v[170:171], 2, s[12:13]
	v_lshl_add_u64 v[170:171], v[194:195], 0, v[174:175]
	global_load_dwordx4 v[60:63], v[32:33], off offset:16
	global_load_dwordx4 v[64:67], v[32:33], off
	global_load_dwordx4 v[28:31], v[32:33], off offset:528
	s_nop 0
	global_load_dwordx4 v[32:35], v[32:33], off offset:512
	v_add_co_u32_e32 v242, vcc, 0, v170
	s_nop 1
	v_addc_co_u32_e32 v243, vcc, 0, v171, vcc
	global_load_dwordx4 v[202:205], v[242:243], off
	v_add_co_u32_e32 v242, vcc, 0, v170
	s_nop 1
	v_addc_co_u32_e32 v243, vcc, 0, v171, vcc
	global_load_dwordx4 v[206:209], v[242:243], off offset:256
	v_add_co_u32_e32 v242, vcc, 0x10000, v170
	s_nop 1
	v_addc_co_u32_e32 v243, vcc, 0, v171, vcc
	global_load_dwordx4 v[210:213], v[242:243], off
	v_add_co_u32_e32 v242, vcc, 0x10000, v170
	s_nop 1
	v_addc_co_u32_e32 v243, vcc, 0, v171, vcc
	global_load_dwordx4 v[214:217], v[242:243], off offset:256
	v_add_co_u32_e32 v242, vcc, 0x20000, v170
	s_nop 1
	v_addc_co_u32_e32 v243, vcc, 0, v171, vcc
	global_load_dwordx4 v[218:221], v[242:243], off
	v_add_co_u32_e32 v242, vcc, 0x20000, v170
	s_nop 1
	v_addc_co_u32_e32 v243, vcc, 0, v171, vcc
	global_load_dwordx4 v[222:225], v[242:243], off offset:256
	v_add_co_u32_e32 v242, vcc, 0x30000, v170
	s_nop 1
	v_addc_co_u32_e32 v243, vcc, 0, v171, vcc
	global_load_dwordx4 v[226:229], v[242:243], off
	v_add_co_u32_e32 v242, vcc, 0x30000, v170
	s_nop 1
	v_addc_co_u32_e32 v243, vcc, 0, v171, vcc
	global_load_dwordx4 v[230:233], v[242:243], off offset:256
	v_add_co_u32_e32 v242, vcc, 0x80000, v170
	s_nop 1
	v_addc_co_u32_e32 v243, vcc, 0, v171, vcc
	global_load_dwordx4 v[234:237], v[242:243], off
	v_add_co_u32_e32 v242, vcc, 0x80000, v170
	s_nop 1
	v_addc_co_u32_e32 v243, vcc, 0, v171, vcc
	global_load_dwordx4 v[238:241], v[242:243], off offset:256
	v_add_co_u32_e32 v242, vcc, 0x90000, v170
	s_nop 1
	v_addc_co_u32_e32 v243, vcc, 0, v171, vcc
	global_load_dwordx4 v[244:247], v[242:243], off
	s_mov_b32 s1, 0x80000
	s_nop 1
	s_waitcnt vmcnt(10)
;     __device__ __forceinline__ void operator()(const f32x4 (&acc)[2][2][4][2], const pg8::Unit& u, int wr, int wc, int fr, int fq) const {
;     ...
;             for (int m = 0; m < 4; ++m) { const size_t ro = (size_t)(row0 + ai * 128 + m * 16) * DM + col0;
; #pragma unroll
;                 for (int bj = 0; bj < 2; ++bj) {
;                     f32x4 x0, x1;
;                     if (XF32) { x0 = *(const f32x4*)(xin + ro + bj * 128); x1 = *(const f32x4*)(xin + ro + bj * 128 + 4); }
;                     else { const h8 xh = *(const h8*)(H + ro + bj * 128); x0 = (f32x4){(float)xh[0], (float)xh[1], (float)xh[2], (float)xh[3]}; x1 = (f32x4){(float)xh[4], (float)xh[5], (float)xh[6], (float)xh[7]}; }
;                     const f32x4 y0 = x0 + gv[bj][0] * acc[ai][bj][m][0], y1 = x1 + gv[bj][1] * acc[ai][bj][m][1];
;                     h8 o; o[0] = (half_t)y0[0]; o[1] = (half_t)y0[1]; o[2] = (half_t)y0[2]; o[3] = (half_t)y0[3]; o[4] = (half_t)y1[0]; o[5] = (half_t)y1[1]; o[6] = (half_t)y1[2]; o[7] = (half_t)y1[3];
;                     *(h8*)(H + ro + bj * 128) = o; } }
	v_mov_b32_e32 v194, v202
	v_mov_b32_e32 v195, v203
	v_mov_b32_e32 v196, v204
	v_mov_b32_e32 v197, v205
	v_add_co_u32_e32 v242, vcc, 0x90000, v170
	s_nop 1
	v_addc_co_u32_e32 v243, vcc, 0, v171, vcc
	global_load_dwordx4 v[202:205], v[242:243], off offset:256
	s_mov_b64 s[12:13], 0x80000
	s_mov_b32 s51, s0
	s_mov_b32 s50, s6
	s_mov_b64 s[14:15], s[10:11]
	v_readlane_b32 s59, v251, 43
	s_nop 0
	v_cvt_f32_f16_e32 v198, v194
	v_cvt_f32_f16_sdwa v199, v194 dst_sel:DWORD dst_unused:UNUSED_PAD src0_sel:WORD_1
	v_cvt_f32_f16_e32 v194, v195
	v_cvt_f32_f16_sdwa v195, v195 dst_sel:DWORD dst_unused:UNUSED_PAD src0_sel:WORD_1
	v_cvt_f32_f16_e32 v200, v196
	v_cvt_f32_f16_sdwa v201, v196 dst_sel:DWORD dst_unused:UNUSED_PAD src0_sel:WORD_1
	v_cvt_f32_f16_e32 v196, v197
	v_cvt_f32_f16_sdwa v197, v197 dst_sel:DWORD dst_unused:UNUSED_PAD src0_sel:WORD_1
	v_pk_fma_f32 v[146:147], v[146:147], v[66:67], v[194:195]
	v_pk_fma_f32 v[144:145], v[144:145], v[64:65], v[198:199]
	v_pk_fma_f32 v[140:141], v[140:141], v[60:61], v[200:201]
	v_pk_fma_f32 v[142:143], v[142:143], v[62:63], v[196:197]
	s_nop 0
	v_cvt_pk_f16_f32 v143, v142, v143
	v_cvt_pk_f16_f32 v142, v140, v141
	v_cvt_pk_f16_f32 v141, v146, v147
	v_cvt_pk_f16_f32 v140, v144, v145
	global_store_dwordx4 v[170:171], v[140:143], off
	s_nop 1
	s_waitcnt vmcnt(10)
	v_mov_b32_e32 v140, v206
	v_mov_b32_e32 v141, v207
	v_mov_b32_e32 v142, v208
	v_mov_b32_e32 v143, v209
	v_add_co_u32_e32 v242, vcc, 0xa0000, v170
	s_nop 1
	v_addc_co_u32_e32 v243, vcc, 0, v171, vcc
	global_load_dwordx4 v[206:209], v[242:243], off
	s_nop 0
	v_cvt_f32_f16_e32 v144, v140
	v_cvt_f32_f16_sdwa v145, v140 dst_sel:DWORD dst_unused:UNUSED_PAD src0_sel:WORD_1
	v_cvt_f32_f16_e32 v140, v141
	v_cvt_f32_f16_sdwa v141, v141 dst_sel:DWORD dst_unused:UNUSED_PAD src0_sel:WORD_1
	v_cvt_f32_f16_e32 v146, v142
	v_cvt_f32_f16_sdwa v147, v142 dst_sel:DWORD dst_unused:UNUSED_PAD src0_sel:WORD_1
	v_cvt_f32_f16_e32 v142, v143
	v_cvt_f32_f16_sdwa v143, v143 dst_sel:DWORD dst_unused:UNUSED_PAD src0_sel:WORD_1
	v_pk_fma_f32 v[138:139], v[138:139], v[34:35], v[140:141]
	v_pk_fma_f32 v[136:137], v[136:137], v[32:33], v[144:145]
	v_pk_fma_f32 v[132:133], v[132:133], v[28:29], v[146:147]
	v_pk_fma_f32 v[134:135], v[134:135], v[30:31], v[142:143]
	s_nop 0
	v_cvt_pk_f16_f32 v135, v134, v135
	v_cvt_pk_f16_f32 v134, v132, v133
	v_cvt_pk_f16_f32 v133, v138, v139
	v_cvt_pk_f16_f32 v132, v136, v137
	global_store_dwordx4 v[170:171], v[132:135], off offset:256
	s_nop 1
	v_or_b32_e32 v132, 16, v172
	v_ashrrev_i32_e32 v133, 31, v132
	v_lshlrev_b64 v[132:133], 12, v[132:133]
	v_lshl_add_u64 v[132:133], s[16:17], 0, v[132:133]
	v_lshl_add_u64 v[136:137], v[132:133], 0, v[174:175]
	s_nop 1
	s_waitcnt vmcnt(10)
	v_mov_b32_e32 v132, v210
	v_mov_b32_e32 v133, v211
	v_mov_b32_e32 v134, v212
	v_mov_b32_e32 v135, v213
	v_add_co_u32_e32 v242, vcc, 0xa0000, v170
	s_nop 1
	v_addc_co_u32_e32 v243, vcc, 0, v171, vcc
	global_load_dwordx4 v[210:213], v[242:243], off offset:256
	s_nop 0
	v_cvt_f32_f16_e32 v138, v132
	v_cvt_f32_f16_sdwa v139, v132 dst_sel:DWORD dst_unused:UNUSED_PAD src0_sel:WORD_1
	v_cvt_f32_f16_e32 v132, v133
	v_cvt_f32_f16_sdwa v133, v133 dst_sel:DWORD dst_unused:UNUSED_PAD src0_sel:WORD_1
	v_cvt_f32_f16_e32 v140, v134
	v_cvt_f32_f16_sdwa v141, v134 dst_sel:DWORD dst_unused:UNUSED_PAD src0_sel:WORD_1
	v_cvt_f32_f16_e32 v134, v135
	v_cvt_f32_f16_sdwa v135, v135 dst_sel:DWORD dst_unused:UNUSED_PAD src0_sel:WORD_1
	v_pk_fma_f32 v[130:131], v[130:131], v[66:67], v[132:133]
	v_pk_fma_f32 v[128:129], v[128:129], v[64:65], v[138:139]
	v_pk_fma_f32 v[124:125], v[124:125], v[60:61], v[140:141]
	v_pk_fma_f32 v[126:127], v[126:127], v[62:63], v[134:135]
	s_nop 0
	v_cvt_pk_f16_f32 v127, v126, v127
	v_cvt_pk_f16_f32 v126, v124, v125
	v_cvt_pk_f16_f32 v125, v130, v131
	v_cvt_pk_f16_f32 v124, v128, v129
	global_store_dwordx4 v[136:137], v[124:127], off
	s_nop 1
	s_waitcnt vmcnt(10)
	v_mov_b32_e32 v124, v214
	v_mov_b32_e32 v125, v215
	v_mov_b32_e32 v126, v216
	v_mov_b32_e32 v127, v217
	v_add_co_u32_e32 v242, vcc, 0xb0000, v170
	s_nop 1
	v_addc_co_u32_e32 v243, vcc, 0, v171, vcc
	global_load_dwordx4 v[214:217], v[242:243], off
	s_nop 0
	v_cvt_f32_f16_e32 v128, v124
	v_cvt_f32_f16_sdwa v129, v124 dst_sel:DWORD dst_unused:UNUSED_PAD src0_sel:WORD_1
	v_cvt_f32_f16_e32 v124, v125
	v_cvt_f32_f16_sdwa v125, v125 dst_sel:DWORD dst_unused:UNUSED_PAD src0_sel:WORD_1
	v_cvt_f32_f16_e32 v130, v126
	v_cvt_f32_f16_sdwa v131, v126 dst_sel:DWORD dst_unused:UNUSED_PAD src0_sel:WORD_1
	v_cvt_f32_f16_e32 v126, v127
	v_cvt_f32_f16_sdwa v127, v127 dst_sel:DWORD dst_unused:UNUSED_PAD src0_sel:WORD_1
	v_pk_fma_f32 v[122:123], v[122:123], v[34:35], v[124:125]
	v_pk_fma_f32 v[120:121], v[120:121], v[32:33], v[128:129]
	v_pk_fma_f32 v[116:117], v[116:117], v[28:29], v[130:131]
	v_pk_fma_f32 v[118:119], v[118:119], v[30:31], v[126:127]
	s_nop 0
	v_cvt_pk_f16_f32 v119, v118, v119
	v_cvt_pk_f16_f32 v118, v116, v117
	v_cvt_pk_f16_f32 v117, v122, v123
	v_cvt_pk_f16_f32 v116, v120, v121
	global_store_dwordx4 v[136:137], v[116:119], off offset:256
	s_nop 1
	v_or_b32_e32 v116, 32, v172
	v_ashrrev_i32_e32 v117, 31, v116
	v_lshlrev_b64 v[116:117], 12, v[116:117]
	v_lshl_add_u64 v[116:117], s[16:17], 0, v[116:117]
	v_lshl_add_u64 v[120:121], v[116:117], 0, v[174:175]
	s_nop 1
	s_waitcnt vmcnt(10)
;     __device__ __forceinline__ void operator()(const f32x4 (&acc)[2][2][4][2], const pg8::Unit& u, int wr, int wc, int fr, int fq) const {
;     ...
;             for (int m = 0; m < 4; ++m) { const size_t ro = (size_t)(row0 + ai * 128 + m * 16) * DM + col0;
; #pragma unroll
;                 for (int bj = 0; bj < 2; ++bj) {
;                     f32x4 x0, x1;
;                     if (XF32) { x0 = *(const f32x4*)(xin + ro + bj * 128); x1 = *(const f32x4*)(xin + ro + bj * 128 + 4); }
;                     else { const h8 xh = *(const h8*)(H + ro + bj * 128); x0 = (f32x4){(float)xh[0], (float)xh[1], (float)xh[2], (float)xh[3]}; x1 = (f32x4){(float)xh[4], (float)xh[5], (float)xh[6], (float)xh[7]}; }
;                     const f32x4 y0 = x0 + gv[bj][0] * acc[ai][bj][m][0], y1 = x1 + gv[bj][1] * acc[ai][bj][m][1];
;                     h8 o; o[0] = (half_t)y0[0]; o[1] = (half_t)y0[1]; o[2] = (half_t)y0[2]; o[3] = (half_t)y0[3]; o[4] = (half_t)y1[0]; o[5] = (half_t)y1[1]; o[6] = (half_t)y1[2]; o[7] = (half_t)y1[3];
;                     *(h8*)(H + ro + bj * 128) = o; } }
	v_mov_b32_e32 v116, v218
	v_mov_b32_e32 v117, v219
	v_mov_b32_e32 v118, v220
	v_mov_b32_e32 v119, v221
	v_add_co_u32_e32 v242, vcc, 0xb0000, v170
	s_nop 1
	v_addc_co_u32_e32 v243, vcc, 0, v171, vcc
	global_load_dwordx4 v[218:221], v[242:243], off offset:256
	s_nop 0
	v_cvt_f32_f16_e32 v122, v116
	v_cvt_f32_f16_sdwa v123, v116 dst_sel:DWORD dst_unused:UNUSED_PAD src0_sel:WORD_1
	v_cvt_f32_f16_e32 v116, v117
	v_cvt_f32_f16_sdwa v117, v117 dst_sel:DWORD dst_unused:UNUSED_PAD src0_sel:WORD_1
	v_cvt_f32_f16_e32 v124, v118
	v_cvt_f32_f16_sdwa v125, v118 dst_sel:DWORD dst_unused:UNUSED_PAD src0_sel:WORD_1
	v_cvt_f32_f16_e32 v118, v119
	v_cvt_f32_f16_sdwa v119, v119 dst_sel:DWORD dst_unused:UNUSED_PAD src0_sel:WORD_1
	v_pk_fma_f32 v[114:115], v[114:115], v[66:67], v[116:117]
	v_pk_fma_f32 v[112:113], v[112:113], v[64:65], v[122:123]
	v_pk_fma_f32 v[108:109], v[108:109], v[60:61], v[124:125]
	v_pk_fma_f32 v[110:111], v[110:111], v[62:63], v[118:119]
	s_nop 0
	v_cvt_pk_f16_f32 v111, v110, v111
	v_cvt_pk_f16_f32 v110, v108, v109
	v_cvt_pk_f16_f32 v109, v114, v115
	v_cvt_pk_f16_f32 v108, v112, v113
	global_store_dwordx4 v[120:121], v[108:111], off
	s_nop 1
	s_waitcnt vmcnt(10)
	v_mov_b32_e32 v108, v222
	v_mov_b32_e32 v109, v223
	v_mov_b32_e32 v110, v224
	v_mov_b32_e32 v111, v225
	s_nop 0
	v_cvt_f32_f16_e32 v112, v108
	v_cvt_f32_f16_sdwa v113, v108 dst_sel:DWORD dst_unused:UNUSED_PAD src0_sel:WORD_1
	v_cvt_f32_f16_e32 v108, v109
	v_cvt_f32_f16_sdwa v109, v109 dst_sel:DWORD dst_unused:UNUSED_PAD src0_sel:WORD_1
	v_cvt_f32_f16_e32 v114, v110
	v_cvt_f32_f16_sdwa v115, v110 dst_sel:DWORD dst_unused:UNUSED_PAD src0_sel:WORD_1
	v_cvt_f32_f16_e32 v110, v111
	v_cvt_f32_f16_sdwa v111, v111 dst_sel:DWORD dst_unused:UNUSED_PAD src0_sel:WORD_1
	v_pk_fma_f32 v[106:107], v[106:107], v[34:35], v[108:109]
	v_pk_fma_f32 v[104:105], v[104:105], v[32:33], v[112:113]
	v_pk_fma_f32 v[100:101], v[100:101], v[28:29], v[114:115]
	v_pk_fma_f32 v[102:103], v[102:103], v[30:31], v[110:111]
	s_nop 0
	v_cvt_pk_f16_f32 v103, v102, v103
	v_cvt_pk_f16_f32 v102, v100, v101
	v_cvt_pk_f16_f32 v101, v106, v107
	v_cvt_pk_f16_f32 v100, v104, v105
	global_store_dwordx4 v[120:121], v[100:103], off offset:256
	s_nop 1
	v_or_b32_e32 v100, 48, v172
	v_ashrrev_i32_e32 v101, 31, v100
	v_lshlrev_b64 v[100:101], 12, v[100:101]
	v_lshl_add_u64 v[100:101], s[16:17], 0, v[100:101]
	v_lshl_add_u64 v[104:105], v[100:101], 0, v[174:175]
	s_nop 1
	s_waitcnt vmcnt(9)
	v_mov_b32_e32 v100, v226
	v_mov_b32_e32 v101, v227
	v_mov_b32_e32 v102, v228
	v_mov_b32_e32 v103, v229
	s_nop 0
	v_cvt_f32_f16_e32 v106, v100
	v_cvt_f32_f16_sdwa v107, v100 dst_sel:DWORD dst_unused:UNUSED_PAD src0_sel:WORD_1
	v_cvt_f32_f16_e32 v100, v101
	v_cvt_f32_f16_sdwa v101, v101 dst_sel:DWORD dst_unused:UNUSED_PAD src0_sel:WORD_1
	v_cvt_f32_f16_e32 v108, v102
	v_cvt_f32_f16_sdwa v109, v102 dst_sel:DWORD dst_unused:UNUSED_PAD src0_sel:WORD_1
	v_cvt_f32_f16_e32 v102, v103
	v_cvt_f32_f16_sdwa v103, v103 dst_sel:DWORD dst_unused:UNUSED_PAD src0_sel:WORD_1
	v_pk_fma_f32 v[98:99], v[98:99], v[66:67], v[100:101]
	v_pk_fma_f32 v[96:97], v[96:97], v[64:65], v[106:107]
	v_pk_fma_f32 v[92:93], v[92:93], v[60:61], v[108:109]
	v_pk_fma_f32 v[94:95], v[94:95], v[62:63], v[102:103]
	s_nop 0
	v_cvt_pk_f16_f32 v95, v94, v95
	v_cvt_pk_f16_f32 v94, v92, v93
	v_cvt_pk_f16_f32 v93, v98, v99
	v_cvt_pk_f16_f32 v92, v96, v97
	global_store_dwordx4 v[104:105], v[92:95], off
	s_nop 1
	s_waitcnt vmcnt(8)
	v_mov_b32_e32 v92, v230
	v_mov_b32_e32 v93, v231
	v_mov_b32_e32 v94, v232
	v_mov_b32_e32 v95, v233
	s_nop 0
	v_cvt_f32_f16_e32 v96, v92
	v_cvt_f32_f16_sdwa v97, v92 dst_sel:DWORD dst_unused:UNUSED_PAD src0_sel:WORD_1
	v_cvt_f32_f16_e32 v92, v93
	v_cvt_f32_f16_sdwa v93, v93 dst_sel:DWORD dst_unused:UNUSED_PAD src0_sel:WORD_1
	v_cvt_f32_f16_e32 v98, v94
	v_cvt_f32_f16_sdwa v99, v94 dst_sel:DWORD dst_unused:UNUSED_PAD src0_sel:WORD_1
	v_cvt_f32_f16_e32 v94, v95
	v_cvt_f32_f16_sdwa v95, v95 dst_sel:DWORD dst_unused:UNUSED_PAD src0_sel:WORD_1
	v_pk_fma_f32 v[90:91], v[90:91], v[34:35], v[92:93]
	v_pk_fma_f32 v[84:85], v[84:85], v[28:29], v[98:99]
	v_pk_fma_f32 v[88:89], v[88:89], v[32:33], v[96:97]
	v_pk_fma_f32 v[86:87], v[86:87], v[30:31], v[94:95]
	s_nop 0
	v_cvt_pk_f16_f32 v87, v86, v87
	v_cvt_pk_f16_f32 v86, v84, v85
	v_cvt_pk_f16_f32 v85, v90, v91
	v_add_co_u32_e32 v90, vcc, s1, v170
	v_cvt_pk_f16_f32 v84, v88, v89
	s_nop 0
	v_addc_co_u32_e32 v91, vcc, 0, v171, vcc
	global_store_dwordx4 v[104:105], v[84:87], off offset:256
	s_nop 1
	s_waitcnt vmcnt(7)
	v_mov_b32_e32 v86, v234
	v_mov_b32_e32 v87, v235
	v_mov_b32_e32 v88, v236
	v_mov_b32_e32 v89, v237
	s_mov_b32 s1, 0x90000
	v_lshl_add_u64 v[84:85], v[170:171], 0, s[12:13]
	s_mov_b64 s[12:13], 0x90000
	s_nop 0
	v_cvt_f32_f16_e32 v92, v86
	v_cvt_f32_f16_sdwa v93, v86 dst_sel:DWORD dst_unused:UNUSED_PAD src0_sel:WORD_1
	v_cvt_f32_f16_e32 v86, v87
	v_cvt_f32_f16_sdwa v87, v87 dst_sel:DWORD dst_unused:UNUSED_PAD src0_sel:WORD_1
	v_cvt_f32_f16_e32 v94, v88
	v_cvt_f32_f16_sdwa v95, v88 dst_sel:DWORD dst_unused:UNUSED_PAD src0_sel:WORD_1
	v_cvt_f32_f16_e32 v88, v89
	v_cvt_f32_f16_sdwa v89, v89 dst_sel:DWORD dst_unused:UNUSED_PAD src0_sel:WORD_1
	v_pk_fma_f32 v[82:83], v[82:83], v[66:67], v[86:87]
	v_pk_fma_f32 v[80:81], v[80:81], v[64:65], v[92:93]
	v_pk_fma_f32 v[76:77], v[76:77], v[60:61], v[94:95]
	v_pk_fma_f32 v[78:79], v[78:79], v[62:63], v[88:89]
	s_nop 0
	v_cvt_pk_f16_f32 v79, v78, v79
	v_cvt_pk_f16_f32 v78, v76, v77
	v_cvt_pk_f16_f32 v77, v82, v83
	v_cvt_pk_f16_f32 v76, v80, v81
	global_store_dwordx4 v[90:91], v[76:79], off
	s_nop 1
	s_waitcnt vmcnt(6)
;     __device__ __forceinline__ void operator()(const f32x4 (&acc)[2][2][4][2], const pg8::Unit& u, int wr, int wc, int fr, int fq) const {
;     ...
;             for (int m = 0; m < 4; ++m) { const size_t ro = (size_t)(row0 + ai * 128 + m * 16) * DM + col0;
; #pragma unroll
;                 for (int bj = 0; bj < 2; ++bj) {
;                     f32x4 x0, x1;
;                     if (XF32) { x0 = *(const f32x4*)(xin + ro + bj * 128); x1 = *(const f32x4*)(xin + ro + bj * 128 + 4); }
;                     else { const h8 xh = *(const h8*)(H + ro + bj * 128); x0 = (f32x4){(float)xh[0], (float)xh[1], (float)xh[2], (float)xh[3]}; x1 = (f32x4){(float)xh[4], (float)xh[5], (float)xh[6], (float)xh[7]}; }
;                     const f32x4 y0 = x0 + gv[bj][0] * acc[ai][bj][m][0], y1 = x1 + gv[bj][1] * acc[ai][bj][m][1];
;                     h8 o; o[0] = (half_t)y0[0]; o[1] = (half_t)y0[1]; o[2] = (half_t)y0[2]; o[3] = (half_t)y0[3]; o[4] = (half_t)y1[0]; o[5] = (half_t)y1[1]; o[6] = (half_t)y1[2]; o[7] = (half_t)y1[3];
;                     *(h8*)(H + ro + bj * 128) = o; } }
	v_mov_b32_e32 v76, v238
	v_mov_b32_e32 v77, v239
	v_mov_b32_e32 v78, v240
	v_mov_b32_e32 v79, v241
	s_nop 0
	v_cvt_f32_f16_e32 v80, v76
	v_cvt_f32_f16_sdwa v81, v76 dst_sel:DWORD dst_unused:UNUSED_PAD src0_sel:WORD_1
	v_cvt_f32_f16_e32 v76, v77
	v_cvt_f32_f16_sdwa v77, v77 dst_sel:DWORD dst_unused:UNUSED_PAD src0_sel:WORD_1
	v_cvt_f32_f16_e32 v82, v78
	v_cvt_f32_f16_sdwa v83, v78 dst_sel:DWORD dst_unused:UNUSED_PAD src0_sel:WORD_1
	v_cvt_f32_f16_e32 v78, v79
	v_cvt_f32_f16_sdwa v79, v79 dst_sel:DWORD dst_unused:UNUSED_PAD src0_sel:WORD_1
	v_pk_fma_f32 v[74:75], v[74:75], v[34:35], v[76:77]
	v_pk_fma_f32 v[68:69], v[68:69], v[28:29], v[82:83]
	v_pk_fma_f32 v[72:73], v[72:73], v[32:33], v[80:81]
	v_pk_fma_f32 v[70:71], v[70:71], v[30:31], v[78:79]
	s_nop 0
	v_cvt_pk_f16_f32 v71, v70, v71
	v_cvt_pk_f16_f32 v70, v68, v69
	v_cvt_pk_f16_f32 v69, v74, v75
	v_add_co_u32_e32 v74, vcc, s1, v170
	v_cvt_pk_f16_f32 v68, v72, v73
	s_nop 0
	v_addc_co_u32_e32 v75, vcc, 0, v171, vcc
	global_store_dwordx4 v[84:85], v[68:71], off offset:256
	s_nop 1
	s_waitcnt vmcnt(5)
	v_mov_b32_e32 v70, v244
	v_mov_b32_e32 v71, v245
	v_mov_b32_e32 v72, v246
	v_mov_b32_e32 v73, v247
	s_mov_b32 s1, 0xa0000
	v_lshl_add_u64 v[68:69], v[170:171], 0, s[12:13]
	s_mov_b64 s[12:13], 0xa0000
	s_nop 0
	v_cvt_f32_f16_e32 v76, v70
	v_cvt_f32_f16_sdwa v77, v70 dst_sel:DWORD dst_unused:UNUSED_PAD src0_sel:WORD_1
	v_cvt_f32_f16_e32 v70, v71
	v_cvt_f32_f16_sdwa v71, v71 dst_sel:DWORD dst_unused:UNUSED_PAD src0_sel:WORD_1
	v_cvt_f32_f16_e32 v78, v72
	v_cvt_f32_f16_sdwa v79, v72 dst_sel:DWORD dst_unused:UNUSED_PAD src0_sel:WORD_1
	v_cvt_f32_f16_e32 v72, v73
	v_cvt_f32_f16_sdwa v73, v73 dst_sel:DWORD dst_unused:UNUSED_PAD src0_sel:WORD_1
	v_pk_fma_f32 v[58:59], v[58:59], v[66:67], v[70:71]
	v_pk_fma_f32 v[56:57], v[56:57], v[64:65], v[76:77]
	v_pk_fma_f32 v[52:53], v[52:53], v[60:61], v[78:79]
	v_pk_fma_f32 v[54:55], v[54:55], v[62:63], v[72:73]
	s_nop 0
	v_cvt_pk_f16_f32 v55, v54, v55
	v_cvt_pk_f16_f32 v54, v52, v53
	v_cvt_pk_f16_f32 v53, v58, v59
	v_cvt_pk_f16_f32 v52, v56, v57
	global_store_dwordx4 v[74:75], v[52:55], off
	s_nop 1
	s_waitcnt vmcnt(4)
	v_mov_b32_e32 v52, v202
	v_mov_b32_e32 v53, v203
	v_mov_b32_e32 v54, v204
	v_mov_b32_e32 v55, v205
	s_nop 0
	v_cvt_f32_f16_e32 v56, v52
	v_cvt_f32_f16_sdwa v57, v52 dst_sel:DWORD dst_unused:UNUSED_PAD src0_sel:WORD_1
	v_cvt_f32_f16_e32 v52, v53
	v_cvt_f32_f16_sdwa v53, v53 dst_sel:DWORD dst_unused:UNUSED_PAD src0_sel:WORD_1
	v_cvt_f32_f16_e32 v58, v54
	v_cvt_f32_f16_sdwa v59, v54 dst_sel:DWORD dst_unused:UNUSED_PAD src0_sel:WORD_1
	v_cvt_f32_f16_e32 v54, v55
	v_cvt_f32_f16_sdwa v55, v55 dst_sel:DWORD dst_unused:UNUSED_PAD src0_sel:WORD_1
	v_pk_fma_f32 v[50:51], v[50:51], v[34:35], v[52:53]
	v_pk_fma_f32 v[44:45], v[44:45], v[28:29], v[58:59]
	v_pk_fma_f32 v[48:49], v[48:49], v[32:33], v[56:57]
	v_pk_fma_f32 v[46:47], v[46:47], v[30:31], v[54:55]
	s_nop 0
	v_cvt_pk_f16_f32 v47, v46, v47
	v_cvt_pk_f16_f32 v46, v44, v45
	v_cvt_pk_f16_f32 v45, v50, v51
	v_add_co_u32_e32 v50, vcc, s1, v170
	v_cvt_pk_f16_f32 v44, v48, v49
	s_nop 0
	v_addc_co_u32_e32 v51, vcc, 0, v171, vcc
	global_store_dwordx4 v[68:69], v[44:47], off offset:256
	s_nop 1
	s_waitcnt vmcnt(3)
	v_mov_b32_e32 v46, v206
	v_mov_b32_e32 v47, v207
	v_mov_b32_e32 v48, v208
	v_mov_b32_e32 v49, v209
	s_mov_b32 s1, 0xb0000
	v_lshl_add_u64 v[44:45], v[170:171], 0, s[12:13]
	s_mov_b64 s[12:13], 0xb0000
	s_nop 0
	v_cvt_f32_f16_e32 v52, v46
	v_cvt_f32_f16_sdwa v53, v46 dst_sel:DWORD dst_unused:UNUSED_PAD src0_sel:WORD_1
	v_cvt_f32_f16_e32 v46, v47
	v_cvt_f32_f16_sdwa v47, v47 dst_sel:DWORD dst_unused:UNUSED_PAD src0_sel:WORD_1
	v_cvt_f32_f16_e32 v54, v48
	v_cvt_f32_f16_sdwa v55, v48 dst_sel:DWORD dst_unused:UNUSED_PAD src0_sel:WORD_1
	v_cvt_f32_f16_e32 v48, v49
	v_cvt_f32_f16_sdwa v49, v49 dst_sel:DWORD dst_unused:UNUSED_PAD src0_sel:WORD_1
	v_pk_fma_f32 v[42:43], v[42:43], v[66:67], v[46:47]
	v_pk_fma_f32 v[40:41], v[40:41], v[64:65], v[52:53]
	v_pk_fma_f32 v[36:37], v[36:37], v[60:61], v[54:55]
	v_pk_fma_f32 v[38:39], v[38:39], v[62:63], v[48:49]
	s_nop 0
	v_cvt_pk_f16_f32 v39, v38, v39
	v_cvt_pk_f16_f32 v38, v36, v37
	v_cvt_pk_f16_f32 v37, v42, v43
	v_cvt_pk_f16_f32 v36, v40, v41
	global_store_dwordx4 v[50:51], v[36:39], off
	s_nop 1
	s_waitcnt vmcnt(2)
; #define PG8_WAIT_V(n) asm volatile("s_waitcnt vmcnt(" #n ")" ::: "memory")
; #define PG8_BAR __builtin_amdgcn_s_barrier()
; template <class Epi>
; __device__ __forceinline__ void gemm_phase(LAS unsigned char* lds, const Gemm g, const StaticOrder& S, const Epi& E, const int tid) {
;     ...
;     PG8_WAIT_V(0);
;     if (wr == 0) PG8_BAR;
;     PG8_BAR;
;     __device__ __forceinline__ void operator()(const f32x4 (&acc)[2][2][4][2], const pg8::Unit& u, int wr, int wc, int fr, int fq) const {
;     ...
;             for (int m = 0; m < 4; ++m) { const size_t ro = (size_t)(row0 + ai * 128 + m * 16) * DM + col0;
; #pragma unroll
;                 for (int bj = 0; bj < 2; ++bj) {
;                     f32x4 x0, x1;
;                     if (XF32) { x0 = *(const f32x4*)(xin + ro + bj * 128); x1 = *(const f32x4*)(xin + ro + bj * 128 + 4); }
;                     else { const h8 xh = *(const h8*)(H + ro + bj * 128); x0 = (f32x4){(float)xh[0], (float)xh[1], (float)xh[2], (float)xh[3]}; x1 = (f32x4){(float)xh[4], (float)xh[5], (float)xh[6], (float)xh[7]}; }
;                     const f32x4 y0 = x0 + gv[bj][0] * acc[ai][bj][m][0], y1 = x1 + gv[bj][1] * acc[ai][bj][m][1];
;                     h8 o; o[0] = (half_t)y0[0]; o[1] = (half_t)y0[1]; o[2] = (half_t)y0[2]; o[3] = (half_t)y0[3]; o[4] = (half_t)y1[0]; o[5] = (half_t)y1[1]; o[6] = (half_t)y1[2]; o[7] = (half_t)y1[3];
;                     *(h8*)(H + ro + bj * 128) = o; } }
	v_mov_b32_e32 v36, v210
	v_mov_b32_e32 v37, v211
	v_mov_b32_e32 v38, v212
	v_mov_b32_e32 v39, v213
	s_nop 0
	v_cvt_f32_f16_e32 v40, v36
	v_cvt_f32_f16_sdwa v41, v36 dst_sel:DWORD dst_unused:UNUSED_PAD src0_sel:WORD_1
	v_cvt_f32_f16_e32 v36, v37
	v_cvt_f32_f16_sdwa v37, v37 dst_sel:DWORD dst_unused:UNUSED_PAD src0_sel:WORD_1
	v_cvt_f32_f16_e32 v42, v38
	v_cvt_f32_f16_sdwa v43, v38 dst_sel:DWORD dst_unused:UNUSED_PAD src0_sel:WORD_1
	v_cvt_f32_f16_e32 v38, v39
	v_cvt_f32_f16_sdwa v39, v39 dst_sel:DWORD dst_unused:UNUSED_PAD src0_sel:WORD_1
	v_pk_fma_f32 v[26:27], v[26:27], v[34:35], v[36:37]
	v_pk_fma_f32 v[20:21], v[20:21], v[28:29], v[42:43]
	v_pk_fma_f32 v[24:25], v[24:25], v[32:33], v[40:41]
	v_pk_fma_f32 v[22:23], v[22:23], v[30:31], v[38:39]
	s_nop 0
	v_cvt_pk_f16_f32 v23, v22, v23
	v_cvt_pk_f16_f32 v22, v20, v21
	v_cvt_pk_f16_f32 v21, v26, v27
	v_add_co_u32_e32 v26, vcc, s1, v170
	v_cvt_pk_f16_f32 v20, v24, v25
	s_nop 0
	v_addc_co_u32_e32 v27, vcc, 0, v171, vcc
	global_store_dwordx4 v[44:45], v[20:23], off offset:256
	s_nop 1
	s_waitcnt vmcnt(1)
	v_mov_b32_e32 v22, v214
	v_mov_b32_e32 v23, v215
	v_mov_b32_e32 v24, v216
	v_mov_b32_e32 v25, v217
	s_and_b64 vcc, exec, s[4:5]
	v_lshl_add_u64 v[20:21], v[170:171], 0, s[12:13]
	s_mov_b64 s[12:13], s[8:9]
	s_nop 0
	v_cvt_f32_f16_e32 v36, v22
	v_cvt_f32_f16_sdwa v37, v22 dst_sel:DWORD dst_unused:UNUSED_PAD src0_sel:WORD_1
	v_cvt_f32_f16_e32 v22, v23
	v_cvt_f32_f16_sdwa v23, v23 dst_sel:DWORD dst_unused:UNUSED_PAD src0_sel:WORD_1
	v_cvt_f32_f16_e32 v38, v24
	v_cvt_f32_f16_sdwa v39, v24 dst_sel:DWORD dst_unused:UNUSED_PAD src0_sel:WORD_1
	v_cvt_f32_f16_e32 v24, v25
	v_cvt_f32_f16_sdwa v25, v25 dst_sel:DWORD dst_unused:UNUSED_PAD src0_sel:WORD_1
	v_pk_fma_f32 v[18:19], v[18:19], v[66:67], v[22:23]
	v_pk_fma_f32 v[16:17], v[16:17], v[64:65], v[36:37]
	v_pk_fma_f32 v[12:13], v[12:13], v[60:61], v[38:39]
	v_pk_fma_f32 v[14:15], v[14:15], v[62:63], v[24:25]
	s_nop 0
	v_cvt_pk_f16_f32 v15, v14, v15
	v_cvt_pk_f16_f32 v14, v12, v13
	v_cvt_pk_f16_f32 v13, v18, v19
	v_cvt_pk_f16_f32 v12, v16, v17
	global_store_dwordx4 v[26:27], v[12:15], off
	s_nop 1
	s_waitcnt vmcnt(0)
	v_mov_b32_e32 v12, v218
	v_mov_b32_e32 v13, v219
	v_mov_b32_e32 v14, v220
	v_mov_b32_e32 v15, v221
	s_nop 0
	v_cvt_f32_f16_e32 v16, v12
	v_cvt_f32_f16_sdwa v17, v12 dst_sel:DWORD dst_unused:UNUSED_PAD src0_sel:WORD_1
	v_cvt_f32_f16_e32 v12, v13
	v_cvt_f32_f16_sdwa v13, v13 dst_sel:DWORD dst_unused:UNUSED_PAD src0_sel:WORD_1
	v_cvt_f32_f16_e32 v18, v14
	v_cvt_f32_f16_sdwa v19, v14 dst_sel:DWORD dst_unused:UNUSED_PAD src0_sel:WORD_1
	v_cvt_f32_f16_e32 v14, v15
	v_cvt_f32_f16_sdwa v15, v15 dst_sel:DWORD dst_unused:UNUSED_PAD src0_sel:WORD_1
	v_pk_fma_f32 v[10:11], v[10:11], v[34:35], v[12:13]
	v_pk_fma_f32 v[8:9], v[8:9], v[32:33], v[16:17]
	v_pk_fma_f32 v[4:5], v[4:5], v[28:29], v[18:19]
	v_pk_fma_f32 v[6:7], v[6:7], v[30:31], v[14:15]
	s_nop 0
	v_cvt_pk_f16_f32 v7, v6, v7
	v_cvt_pk_f16_f32 v6, v4, v5
	v_cvt_pk_f16_f32 v5, v10, v11
	v_cvt_pk_f16_f32 v4, v8, v9
	global_store_dwordx4 v[20:21], v[4:7], off offset:256
	s_cbranch_vccz .LBB0_653
	s_waitcnt vmcnt(0)
	v_readlane_b32 s48, v251, 13
	s_cmpk_gt_u32 s25, 0xff
	v_readlane_b32 s49, v251, 14
	s_cbranch_scc1 .LBB0_664
	s_barrier

; #define PG8_STAGE(bufoff, gbase, voff) do { _Pragma("unroll") for (int _i = 0; _i < 2; ++_i) \
;         __builtin_amdgcn_global_load_lds((const unsigned*)((const char*)(gbase) + (voff)[_i]), (LAS unsigned*)(lds + (bufoff) + ldsw + _i * 8192), 16, 0, 0); } while (0)
; #define PG8_LDA(dst, b, h) do { _Pragma("unroll") for (int m = 0; m < 4; ++m) _Pragma("unroll") for (int k = 0; k < 2; ++k) dst[m][k] = *(const LAS h8*)(lds + PG8_SA(b, h) + aoff + m * 2048 + k * 1024); } while (0)
; #define PG8_LDB(dst, b, h) do { _Pragma("unroll") for (int n = 0; n < 2; ++n) _Pragma("unroll") for (int k = 0; k < 2; ++k) dst[n][k] = *(const LAS h8*)(lds + PG8_SB(b, h) + boff + n * 2048 + k * 1024); } while (0)
; #define PG8_WAIT_V(n) asm volatile("s_waitcnt vmcnt(" #n ")" ::: "memory")
; #define PG8_WAIT_L(n) asm volatile("s_waitcnt lgkmcnt(" #n ")" ::: "memory")
; #define PG8_BAR __builtin_amdgcn_s_barrier()
; #define PG8_SCHED __builtin_amdgcn_sched_barrier(0)
; template <class Epi>
; __device__ __forceinline__ void gemm_phase(LAS unsigned char* lds, const Gemm g, const StaticOrder& S, const Epi& E, const int tid) {
;     ...
;             const bool last = (t == nt - 2);
;             const char* a1 = cA + (size_t)(t + 1) * kstep;
;             const char* a2 = last ? nA : cA + (size_t)(t + 2) * kstep; const char* b2 = last ? nB : cB + (size_t)(t + 2) * kstep;
;             const char* a3 = a2 + kstep; const char* b3 = b2 + kstep;
;             if constexpr (Epi::HAS_MID) { if (t == (nt >> 1)) E.mid(acc, cur, wr, wc, fr, fq); }
;             PG8_LDB(B0, 0, 0); PG8_SCHED; PG8_LDA(At, 0, 0); PG8_STAGE(PG8_SA(1, 1), a1 + hstep, voffA);
;             PG8_WAIT_L(8); PG8_BAR; PG8_WAIT_L(0); PG8_MMA(0, 0, At, B0); PG8_BAR; PG8_SCHED;
;             PG8_LDB(B1, 0, 1); PG8_STAGE(PG8_SB(0, 0), b2, voffB);
;             PG8_BAR; PG8_WAIT_L(0); PG8_MMA(0, 1, At, B1); PG8_BAR;
;             PG8_LDA(At, 0, 1); PG8_STAGE(PG8_SA(0, 0), a2, voffA);
;             PG8_BAR; PG8_WAIT_L(0); PG8_MMA(1, 0, At, B0); PG8_BAR; PG8_SCHED;
;             PG8_STAGE(PG8_SB(0, 1), b2 + hstepB, voffB);
;             PG8_WAIT_V(6); PG8_BAR; PG8_MMA(1, 1, At, B1); PG8_BAR;
.LBB0_678:
	s_add_u32 s14, s12, 0xfff80080
	s_addc_u32 s15, s13, -1
	s_add_i32 s55, 0, 0x10000
	v_add_u32_e32 v88, s55, v176
	ds_read_b128 v[68:71], v88
	ds_read_b128 v[72:75], v88 offset:1024
	ds_read_b128 v[84:87], v88 offset:2048
	ds_read_b128 v[88:91], v88 offset:3072
	s_cmp_eq_u32 s54, 28
	s_cselect_b32 s19, s7, s15
	s_cselect_b32 s18, s50, s14
	s_cselect_b32 s15, s1, s53
	s_cselect_b32 s14, s51, s52
	v_lshl_add_u64 v[174:175], s[12:13], 0, v[166:167]
	s_add_i32 m0, s39, 0xc000
	ds_read_b128 v[170:173], v177
	ds_read_b128 v[190:193], v177 offset:1024
	ds_read_b128 v[194:197], v177 offset:2048
	ds_read_b128 v[198:201], v177 offset:3072
	ds_read_b128 v[202:205], v177 offset:4096
	ds_read_b128 v[206:209], v177 offset:5120
	ds_read_b128 v[210:213], v177 offset:6144
	ds_read_b128 v[214:217], v177 offset:7168
	global_load_lds_dwordx4 v[174:175], off
	v_lshl_add_u64 v[174:175], s[12:13], 0, v[168:169]
	s_add_i32 m0, s39, 0xe000
	s_nop 0
	global_load_lds_dwordx4 v[174:175], off
	s_waitcnt lgkmcnt(8)
	s_barrier
	s_waitcnt lgkmcnt(0)
	s_setprio 0
	s_waitcnt lgkmcnt(0)
	v_mfma_f32_16x16x32_bf16 v[144:147], v[68:71], v[170:173], v[144:147]
	v_mfma_f32_16x16x32_bf16 v[140:143], v[84:87], v[170:173], v[140:143]
	v_mfma_f32_16x16x32_bf16 v[128:131], v[68:71], v[194:197], v[128:131]
	v_mfma_f32_16x16x32_bf16 v[124:127], v[84:87], v[194:197], v[124:127]
	v_mfma_f32_16x16x32_bf16 v[112:115], v[68:71], v[202:205], v[112:115]
	v_mfma_f32_16x16x32_bf16 v[108:111], v[84:87], v[202:205], v[108:111]
	v_mfma_f32_16x16x32_bf16 v[96:99], v[68:71], v[210:213], v[96:99]
	v_mfma_f32_16x16x32_bf16 v[92:95], v[84:87], v[210:213], v[92:95]
	v_mfma_f32_16x16x32_bf16 v[144:147], v[72:75], v[190:193], v[144:147]
	v_mfma_f32_16x16x32_bf16 v[140:143], v[88:91], v[190:193], v[140:143]
	v_mfma_f32_16x16x32_bf16 v[128:131], v[72:75], v[198:201], v[128:131]
	v_mfma_f32_16x16x32_bf16 v[124:127], v[88:91], v[198:201], v[124:127]
	v_mfma_f32_16x16x32_bf16 v[112:115], v[72:75], v[206:209], v[112:115]
	v_mfma_f32_16x16x32_bf16 v[108:111], v[88:91], v[206:209], v[108:111]
	v_mfma_f32_16x16x32_bf16 v[96:99], v[72:75], v[214:217], v[96:99]
	v_mfma_f32_16x16x32_bf16 v[92:95], v[88:91], v[214:217], v[92:95]
	s_setprio 1
	s_barrier
	s_add_i32 s58, 0, 0x14000
	v_add_u32_e32 v174, s58, v176
	s_add_i32 s55, s55, s38
	ds_read_b128 v[218:221], v174
	ds_read_b128 v[222:225], v174 offset:1024
	ds_read_b128 v[226:229], v174 offset:2048
	ds_read_b128 v[230:233], v174 offset:3072
	v_lshl_add_u64 v[174:175], s[14:15], 0, v[2:3]
	s_mov_b32 m0, s55
	v_lshl_add_u64 v[234:235], s[14:15], 0, v[0:1]
	global_load_lds_dwordx4 v[174:175], off
	s_add_i32 m0, s55, 0x2000
	s_nop 0
	global_load_lds_dwordx4 v[234:235], off
	s_barrier
	s_waitcnt lgkmcnt(0)
	s_setprio 0
	s_waitcnt lgkmcnt(0)
	v_mfma_f32_16x16x32_bf16 v[136:139], v[218:221], v[170:173], v[136:139]
	v_mfma_f32_16x16x32_bf16 v[132:135], v[226:229], v[170:173], v[132:135]
	v_mfma_f32_16x16x32_bf16 v[120:123], v[218:221], v[194:197], v[120:123]
	v_mfma_f32_16x16x32_bf16 v[116:119], v[226:229], v[194:197], v[116:119]
	v_mfma_f32_16x16x32_bf16 v[104:107], v[218:221], v[202:205], v[104:107]
	v_mfma_f32_16x16x32_bf16 v[100:103], v[226:229], v[202:205], v[100:103]
	v_mfma_f32_16x16x32_bf16 v[80:83], v[218:221], v[210:213], v[80:83]
	v_mfma_f32_16x16x32_bf16 v[76:79], v[226:229], v[210:213], v[76:79]
	v_mfma_f32_16x16x32_bf16 v[136:139], v[222:225], v[190:193], v[136:139]
	v_mfma_f32_16x16x32_bf16 v[132:135], v[230:233], v[190:193], v[132:135]
	v_mfma_f32_16x16x32_bf16 v[120:123], v[222:225], v[198:201], v[120:123]
	v_mfma_f32_16x16x32_bf16 v[116:119], v[230:233], v[198:201], v[116:119]
	v_mfma_f32_16x16x32_bf16 v[104:107], v[222:225], v[206:209], v[104:107]
	v_mfma_f32_16x16x32_bf16 v[100:103], v[230:233], v[206:209], v[100:103]
	v_mfma_f32_16x16x32_bf16 v[80:83], v[222:225], v[214:217], v[80:83]
	v_mfma_f32_16x16x32_bf16 v[76:79], v[230:233], v[214:217], v[76:79]
	s_setprio 1
	s_mov_b32 m0, s39
	v_lshl_add_u64 v[236:237], s[18:19], 0, v[164:165]
	s_barrier
	ds_read_b128 v[170:173], v177 offset:16384
	ds_read_b128 v[190:193], v177 offset:17408
	ds_read_b128 v[194:197], v177 offset:18432
	ds_read_b128 v[198:201], v177 offset:19456
	ds_read_b128 v[202:205], v177 offset:20480
	ds_read_b128 v[206:209], v177 offset:21504
	ds_read_b128 v[210:213], v177 offset:22528
	ds_read_b128 v[214:217], v177 offset:23552
	global_load_lds_dwordx4 v[236:237], off
	v_lshl_add_u64 v[238:239], s[18:19], 0, v[162:163]
	s_mov_b32 m0, s40
	s_nop 0
	global_load_lds_dwordx4 v[238:239], off
	s_barrier
	s_waitcnt lgkmcnt(0)
	s_setprio 0
	s_waitcnt lgkmcnt(0)
	v_mfma_f32_16x16x32_bf16 v[64:67], v[68:71], v[170:173], v[64:67]
	v_mfma_f32_16x16x32_bf16 v[60:63], v[84:87], v[170:173], v[60:63]
	v_mfma_f32_16x16x32_bf16 v[48:51], v[68:71], v[194:197], v[48:51]
	v_mfma_f32_16x16x32_bf16 v[44:47], v[84:87], v[194:197], v[44:47]
	v_mfma_f32_16x16x32_bf16 v[32:35], v[68:71], v[202:205], v[32:35]
	v_mfma_f32_16x16x32_bf16 v[28:31], v[84:87], v[202:205], v[28:31]
	v_mfma_f32_16x16x32_bf16 v[16:19], v[68:71], v[210:213], v[16:19]
	v_mfma_f32_16x16x32_bf16 v[12:15], v[84:87], v[210:213], v[12:15]
	v_mfma_f32_16x16x32_bf16 v[64:67], v[72:75], v[190:193], v[64:67]
	v_mfma_f32_16x16x32_bf16 v[60:63], v[88:91], v[190:193], v[60:63]
	v_mfma_f32_16x16x32_bf16 v[48:51], v[72:75], v[198:201], v[48:51]
	v_mfma_f32_16x16x32_bf16 v[44:47], v[88:91], v[198:201], v[44:47]
	v_mfma_f32_16x16x32_bf16 v[32:35], v[72:75], v[206:209], v[32:35]
	v_mfma_f32_16x16x32_bf16 v[28:31], v[88:91], v[206:209], v[28:31]
	v_mfma_f32_16x16x32_bf16 v[16:19], v[72:75], v[214:217], v[16:19]
	v_mfma_f32_16x16x32_bf16 v[12:15], v[88:91], v[214:217], v[12:15]
	s_setprio 1
	s_barrier
; #define PG8_STAGE(bufoff, gbase, voff) do { _Pragma("unroll") for (int _i = 0; _i < 2; ++_i) \
;         __builtin_amdgcn_global_load_lds((const unsigned*)((const char*)(gbase) + (voff)[_i]), (LAS unsigned*)(lds + (bufoff) + ldsw + _i * 8192), 16, 0, 0); } while (0)
; #define PG8_LDA(dst, b, h) do { _Pragma("unroll") for (int m = 0; m < 4; ++m) _Pragma("unroll") for (int k = 0; k < 2; ++k) dst[m][k] = *(const LAS h8*)(lds + PG8_SA(b, h) + aoff + m * 2048 + k * 1024); } while (0)
; #define PG8_LDB(dst, b, h) do { _Pragma("unroll") for (int n = 0; n < 2; ++n) _Pragma("unroll") for (int k = 0; k < 2; ++k) dst[n][k] = *(const LAS h8*)(lds + PG8_SB(b, h) + boff + n * 2048 + k * 1024); } while (0)
; #define PG8_WAIT_V(n) asm volatile("s_waitcnt vmcnt(" #n ")" ::: "memory")
; #define PG8_WAIT_L(n) asm volatile("s_waitcnt lgkmcnt(" #n ")" ::: "memory")
; #define PG8_BAR __builtin_amdgcn_s_barrier()
; #define PG8_SCHED __builtin_amdgcn_sched_barrier(0)
; template <class Epi>
; __device__ __forceinline__ void gemm_phase(LAS unsigned char* lds, const Gemm g, const StaticOrder& S, const Epi& E, const int tid) {
;     ...
;             PG8_BAR; PG8_WAIT_L(0); PG8_MMA(1, 0, At, B0); PG8_BAR; PG8_SCHED;
;             PG8_STAGE(PG8_SB(0, 1), b2 + hstepB, voffB);
;             PG8_WAIT_V(6); PG8_BAR; PG8_MMA(1, 1, At, B1); PG8_BAR;
;             PG8_LDB(B0, 1, 0); PG8_SCHED; PG8_LDA(At, 1, 0); PG8_STAGE(PG8_SA(0, 1), a2 + hstep, voffA);
;             PG8_WAIT_L(8); PG8_BAR; PG8_WAIT_L(0); PG8_MMA(0, 0, At, B0); PG8_BAR; PG8_SCHED;
;             PG8_LDB(B1, 1, 1); PG8_STAGE(PG8_SB(1, 0), b3, voffB);
;             PG8_BAR; PG8_WAIT_L(0); PG8_MMA(0, 1, At, B1); PG8_BAR;
;             PG8_LDA(At, 1, 1); PG8_STAGE(PG8_SA(1, 0), a3, voffA);
;             PG8_BAR; PG8_WAIT_L(0); PG8_MMA(1, 0, At, B0); PG8_BAR; PG8_SCHED;
	s_add_u32 s56, s14, 0x80000
	s_addc_u32 s57, s15, 0
	s_add_i32 s55, s58, s38
	v_lshl_add_u64 v[68:69], s[56:57], 0, v[2:3]
	s_mov_b32 m0, s55
	s_nop 0
	global_load_lds_dwordx4 v[68:69], off
	v_lshl_add_u64 v[68:69], s[56:57], 0, v[0:1]
	s_add_i32 m0, s55, 0x2000
	s_nop 0
	global_load_lds_dwordx4 v[68:69], off
	s_waitcnt vmcnt(6)
	s_barrier
	s_setprio 0
	v_mfma_f32_16x16x32_bf16 v[56:59], v[218:221], v[170:173], v[56:59]
	v_mfma_f32_16x16x32_bf16 v[52:55], v[226:229], v[170:173], v[52:55]
	v_mfma_f32_16x16x32_bf16 v[40:43], v[218:221], v[194:197], v[40:43]
	v_mfma_f32_16x16x32_bf16 v[36:39], v[226:229], v[194:197], v[36:39]
	v_mfma_f32_16x16x32_bf16 v[24:27], v[218:221], v[202:205], v[24:27]
	v_mfma_f32_16x16x32_bf16 v[20:23], v[226:229], v[202:205], v[20:23]
	v_mfma_f32_16x16x32_bf16 v[8:11], v[218:221], v[210:213], v[8:11]
	v_mfma_f32_16x16x32_bf16 v[4:7], v[226:229], v[210:213], v[4:7]
	v_mfma_f32_16x16x32_bf16 v[56:59], v[222:225], v[190:193], v[56:59]
	v_mfma_f32_16x16x32_bf16 v[52:55], v[230:233], v[190:193], v[52:55]
	v_mfma_f32_16x16x32_bf16 v[40:43], v[222:225], v[198:201], v[40:43]
	v_mfma_f32_16x16x32_bf16 v[36:39], v[230:233], v[198:201], v[36:39]
	v_mfma_f32_16x16x32_bf16 v[24:27], v[222:225], v[206:209], v[24:27]
	v_mfma_f32_16x16x32_bf16 v[20:23], v[230:233], v[206:209], v[20:23]
	v_mfma_f32_16x16x32_bf16 v[8:11], v[222:225], v[214:217], v[8:11]
	v_mfma_f32_16x16x32_bf16 v[4:7], v[230:233], v[214:217], v[4:7]
	s_setprio 1
	s_add_i32 s55, 0, 0x18000
	v_add_u32_e32 v88, s55, v176
	s_barrier
	ds_read_b128 v[68:71], v88
	ds_read_b128 v[72:75], v88 offset:1024
	ds_read_b128 v[84:87], v88 offset:2048
	ds_read_b128 v[88:91], v88 offset:3072
	s_add_u32 s18, s18, 0x80000
	s_addc_u32 s19, s19, 0
	s_mov_b32 m0, s41
	v_lshl_add_u64 v[218:219], s[18:19], 0, v[164:165]
	ds_read_b128 v[170:173], v177 offset:32768
	ds_read_b128 v[190:193], v177 offset:33792
	ds_read_b128 v[194:197], v177 offset:34816
	ds_read_b128 v[198:201], v177 offset:35840
	ds_read_b128 v[202:205], v177 offset:36864
	ds_read_b128 v[206:209], v177 offset:37888
	ds_read_b128 v[210:213], v177 offset:38912
	ds_read_b128 v[214:217], v177 offset:39936
	global_load_lds_dwordx4 v[218:219], off
	v_lshl_add_u64 v[218:219], s[18:19], 0, v[162:163]
	s_mov_b32 m0, s42
	s_nop 0
	global_load_lds_dwordx4 v[218:219], off
	s_waitcnt lgkmcnt(8)
	s_barrier
	s_waitcnt lgkmcnt(0)
	s_setprio 0
	s_waitcnt lgkmcnt(0)
	v_mfma_f32_16x16x32_bf16 v[144:147], v[68:71], v[170:173], v[144:147]
	v_mfma_f32_16x16x32_bf16 v[140:143], v[84:87], v[170:173], v[140:143]
	v_mfma_f32_16x16x32_bf16 v[128:131], v[68:71], v[194:197], v[128:131]
	v_mfma_f32_16x16x32_bf16 v[124:127], v[84:87], v[194:197], v[124:127]
	v_mfma_f32_16x16x32_bf16 v[112:115], v[68:71], v[202:205], v[112:115]
	v_mfma_f32_16x16x32_bf16 v[108:111], v[84:87], v[202:205], v[108:111]
	v_mfma_f32_16x16x32_bf16 v[96:99], v[68:71], v[210:213], v[96:99]
	v_mfma_f32_16x16x32_bf16 v[92:95], v[84:87], v[210:213], v[92:95]
	v_mfma_f32_16x16x32_bf16 v[144:147], v[72:75], v[190:193], v[144:147]
	v_mfma_f32_16x16x32_bf16 v[140:143], v[88:91], v[190:193], v[140:143]
	v_mfma_f32_16x16x32_bf16 v[128:131], v[72:75], v[198:201], v[128:131]
	v_mfma_f32_16x16x32_bf16 v[124:127], v[88:91], v[198:201], v[124:127]
	v_mfma_f32_16x16x32_bf16 v[112:115], v[72:75], v[206:209], v[112:115]
	v_mfma_f32_16x16x32_bf16 v[108:111], v[88:91], v[206:209], v[108:111]
	v_mfma_f32_16x16x32_bf16 v[96:99], v[72:75], v[214:217], v[96:99]
	v_mfma_f32_16x16x32_bf16 v[92:95], v[88:91], v[214:217], v[92:95]
	s_setprio 1
	s_barrier
	s_add_i32 s18, 0, 0x1c000
	s_add_i32 s19, s55, s38
	v_add_u32_e32 v178, s18, v176
	v_lshl_add_u64 v[174:175], v[174:175], 0, s[30:31]
	s_mov_b32 m0, s19
	ds_read_b128 v[218:221], v178
	ds_read_b128 v[222:225], v178 offset:1024
	ds_read_b128 v[226:229], v178 offset:2048
	ds_read_b128 v[230:233], v178 offset:3072
	global_load_lds_dwordx4 v[174:175], off
	v_lshl_add_u64 v[174:175], v[234:235], 0, s[30:31]
	s_add_i32 m0, s19, 0x2000
	s_nop 0
	global_load_lds_dwordx4 v[174:175], off
	s_barrier
	s_waitcnt lgkmcnt(0)
	s_setprio 0
	s_waitcnt lgkmcnt(0)
	v_mfma_f32_16x16x32_bf16 v[136:139], v[218:221], v[170:173], v[136:139]
	v_mfma_f32_16x16x32_bf16 v[132:135], v[226:229], v[170:173], v[132:135]
	v_mfma_f32_16x16x32_bf16 v[120:123], v[218:221], v[194:197], v[120:123]
	v_mfma_f32_16x16x32_bf16 v[116:119], v[226:229], v[194:197], v[116:119]
	v_mfma_f32_16x16x32_bf16 v[104:107], v[218:221], v[202:205], v[104:107]
	v_mfma_f32_16x16x32_bf16 v[100:103], v[226:229], v[202:205], v[100:103]
	v_mfma_f32_16x16x32_bf16 v[80:83], v[218:221], v[210:213], v[80:83]
	v_mfma_f32_16x16x32_bf16 v[76:79], v[226:229], v[210:213], v[76:79]
	v_mfma_f32_16x16x32_bf16 v[136:139], v[222:225], v[190:193], v[136:139]
	v_mfma_f32_16x16x32_bf16 v[132:135], v[230:233], v[190:193], v[132:135]
	v_mfma_f32_16x16x32_bf16 v[120:123], v[222:225], v[198:201], v[120:123]
	v_mfma_f32_16x16x32_bf16 v[116:119], v[230:233], v[198:201], v[116:119]
	v_mfma_f32_16x16x32_bf16 v[104:107], v[222:225], v[206:209], v[104:107]
	v_mfma_f32_16x16x32_bf16 v[100:103], v[230:233], v[206:209], v[100:103]
	v_mfma_f32_16x16x32_bf16 v[80:83], v[222:225], v[214:217], v[80:83]
	v_mfma_f32_16x16x32_bf16 v[76:79], v[230:233], v[214:217], v[76:79]
	s_setprio 1
	s_mov_b32 m0, s43
	v_lshl_add_u64 v[174:175], v[236:237], 0, s[30:31]
	s_barrier
	ds_read_b128 v[170:173], v177 offset:49152
	ds_read_b128 v[190:193], v177 offset:50176
	ds_read_b128 v[194:197], v177 offset:51200
	ds_read_b128 v[198:201], v177 offset:52224
	ds_read_b128 v[202:205], v177 offset:53248
	ds_read_b128 v[206:209], v177 offset:54272
	ds_read_b128 v[210:213], v177 offset:55296
	ds_read_b128 v[214:217], v177 offset:56320
	global_load_lds_dwordx4 v[174:175], off
	v_lshl_add_u64 v[174:175], v[238:239], 0, s[30:31]
	s_mov_b32 m0, s46
	s_nop 0
	global_load_lds_dwordx4 v[174:175], off
	s_barrier
; #define PG8_STAGE(bufoff, gbase, voff) do { _Pragma("unroll") for (int _i = 0; _i < 2; ++_i) \
;         __builtin_amdgcn_global_load_lds((const unsigned*)((const char*)(gbase) + (voff)[_i]), (LAS unsigned*)(lds + (bufoff) + ldsw + _i * 8192), 16, 0, 0); } while (0)
; #define PG8_WAIT_V(n) asm volatile("s_waitcnt vmcnt(" #n ")" ::: "memory")
; #define PG8_WAIT_L(n) asm volatile("s_waitcnt lgkmcnt(" #n ")" ::: "memory")
; #define PG8_BAR __builtin_amdgcn_s_barrier()
; #define PG8_SCHED __builtin_amdgcn_sched_barrier(0)
; template <class Epi>
; __device__ __forceinline__ void gemm_phase(LAS unsigned char* lds, const Gemm g, const StaticOrder& S, const Epi& E, const int tid) {
;     ...
;             PG8_BAR; PG8_WAIT_L(0); PG8_MMA(1, 0, At, B0); PG8_BAR; PG8_SCHED;
;             PG8_STAGE(PG8_SB(1, 1), b3 + hstepB, voffB);
;             PG8_WAIT_V(6); PG8_BAR; PG8_MMA(1, 1, At, B1); PG8_BAR;
;     __device__ __forceinline__ void operator()(const f32x4 (&acc)[2][2][4][2], const pg8::Unit& u, int wr, int wc, int fr, int fq) const {
;         const int row0 = u.pm * 256 + wr * 64 + fr, col0 = u.pn * 256 + wc * 32 + 8 * fq;
;         const float* gp = gate + (size_t)((u.pm * 256) >> 12) * 6144 + col0;
;         f32x4 gv[2][2];
; #pragma unroll
;         for (int bj = 0; bj < 2; ++bj)
; #pragma unroll
;             for (int n = 0; n < 2; ++n) gv[bj][n] = *(const f32x4*)(gp + bj * 128 + 4 * n);
; #pragma unroll
;         for (int ai = 0; ai < 2; ++ai)
; #pragma unroll
;             for (int m = 0; m < 4; ++m) { const size_t ro = (size_t)(row0 + ai * 128 + m * 16) * DM + col0;
; #pragma unroll
;                 for (int bj = 0; bj < 2; ++bj) {
;                     f32x4 x0, x1;
;                     if (XF32) { x0 = *(const f32x4*)(xin + ro + bj * 128); x1 = *(const f32x4*)(xin + ro + bj * 128 + 4); }
;                     else { const h8 xh = *(const h8*)(H + ro + bj * 128); x0 = (f32x4){(float)xh[0], (float)xh[1], (float)xh[2], (float)xh[3]}; x1 = (f32x4){(float)xh[4], (float)xh[5], (float)xh[6], (float)xh[7]}; }
;                     const f32x4 y0 = x0 + gv[bj][0] * acc[ai][bj][m][0], y1 = x1 + gv[bj][1] * acc[ai][bj][m][1];
	s_waitcnt lgkmcnt(0)
	s_setprio 0
	s_waitcnt lgkmcnt(0)
	v_mfma_f32_16x16x32_bf16 v[64:67], v[68:71], v[170:173], v[64:67]
	v_mfma_f32_16x16x32_bf16 v[60:63], v[84:87], v[170:173], v[60:63]
	v_mfma_f32_16x16x32_bf16 v[48:51], v[68:71], v[194:197], v[48:51]
	v_mfma_f32_16x16x32_bf16 v[44:47], v[84:87], v[194:197], v[44:47]
	v_mfma_f32_16x16x32_bf16 v[32:35], v[68:71], v[202:205], v[32:35]
	v_mfma_f32_16x16x32_bf16 v[28:31], v[84:87], v[202:205], v[28:31]
	v_mfma_f32_16x16x32_bf16 v[16:19], v[68:71], v[210:213], v[16:19]
	v_mfma_f32_16x16x32_bf16 v[12:15], v[84:87], v[210:213], v[12:15]
	v_mfma_f32_16x16x32_bf16 v[64:67], v[72:75], v[190:193], v[64:67]
	v_mfma_f32_16x16x32_bf16 v[60:63], v[88:91], v[190:193], v[60:63]
	v_mfma_f32_16x16x32_bf16 v[48:51], v[72:75], v[198:201], v[48:51]
	v_mfma_f32_16x16x32_bf16 v[44:47], v[88:91], v[198:201], v[44:47]
	v_mfma_f32_16x16x32_bf16 v[32:35], v[72:75], v[206:209], v[32:35]
	v_mfma_f32_16x16x32_bf16 v[28:31], v[88:91], v[206:209], v[28:31]
	v_mfma_f32_16x16x32_bf16 v[16:19], v[72:75], v[214:217], v[16:19]
	v_mfma_f32_16x16x32_bf16 v[12:15], v[88:91], v[214:217], v[12:15]
	s_setprio 1
	s_barrier
	s_add_u32 s14, s14, 0x80080
	s_addc_u32 s15, s15, 0
	s_add_i32 s18, s18, s38
	v_lshl_add_u64 v[68:69], s[14:15], 0, v[2:3]
	s_mov_b32 m0, s18
	s_nop 0
	global_load_lds_dwordx4 v[68:69], off
	v_lshl_add_u64 v[68:69], s[14:15], 0, v[0:1]
	s_add_i32 m0, s18, 0x2000
	s_nop 0
	global_load_lds_dwordx4 v[68:69], off
	s_waitcnt vmcnt(6)
	s_barrier
	s_setprio 0
	v_mfma_f32_16x16x32_bf16 v[56:59], v[218:221], v[170:173], v[56:59]
	v_mfma_f32_16x16x32_bf16 v[52:55], v[226:229], v[170:173], v[52:55]
	v_mfma_f32_16x16x32_bf16 v[40:43], v[218:221], v[194:197], v[40:43]
	v_mfma_f32_16x16x32_bf16 v[36:39], v[226:229], v[194:197], v[36:39]
	v_mfma_f32_16x16x32_bf16 v[24:27], v[218:221], v[202:205], v[24:27]
	v_mfma_f32_16x16x32_bf16 v[20:23], v[226:229], v[202:205], v[20:23]
	v_mfma_f32_16x16x32_bf16 v[8:11], v[218:221], v[210:213], v[8:11]
	v_mfma_f32_16x16x32_bf16 v[4:7], v[226:229], v[210:213], v[4:7]
	v_mfma_f32_16x16x32_bf16 v[56:59], v[222:225], v[190:193], v[56:59]
	v_mfma_f32_16x16x32_bf16 v[52:55], v[230:233], v[190:193], v[52:55]
	v_mfma_f32_16x16x32_bf16 v[40:43], v[222:225], v[198:201], v[40:43]
	v_mfma_f32_16x16x32_bf16 v[36:39], v[230:233], v[198:201], v[36:39]
	v_mfma_f32_16x16x32_bf16 v[24:27], v[222:225], v[206:209], v[24:27]
	v_mfma_f32_16x16x32_bf16 v[20:23], v[230:233], v[206:209], v[20:23]
	v_mfma_f32_16x16x32_bf16 v[8:11], v[222:225], v[214:217], v[8:11]
	v_mfma_f32_16x16x32_bf16 v[4:7], v[230:233], v[214:217], v[4:7]
	s_setprio 1
	s_add_i32 s54, s54, 2
	s_add_u32 s12, s12, 0x100
	s_addc_u32 s13, s13, 0
	s_add_u32 s52, s52, 0x100
	s_addc_u32 s53, s53, 0
	s_cmp_gt_u32 s54, 29
	s_barrier
	s_cbranch_scc0 .LBB0_678
	s_ashr_i32 s1, s48, 4
	v_lshl_add_u32 v174, s48, 8, v179
	v_lshl_or_b32 v172, s49, 8, v157
	s_mul_hi_i32 s7, s1, 0x6000
	s_mulk_i32 s1, 0x6000
	v_ashrrev_i32_e32 v175, 31, v174
	s_add_u32 s12, s23, s1
	v_ashrrev_i32_e32 v173, 31, v172
	v_lshlrev_b64 v[170:171], 11, v[174:175]
	s_addc_u32 s13, s24, s7
	v_lshl_add_u64 v[170:171], v[170:171], 0, v[172:173]
	v_lshl_add_u64 v[72:73], v[172:173], 2, s[12:13]
	v_lshl_add_u64 v[198:199], v[170:171], 2, s[80:81]
	global_load_dwordx4 v[84:87], v[72:73], off offset:16
	global_load_dwordx4 v[88:91], v[72:73], off
	global_load_dwordx4 v[68:71], v[72:73], off offset:528
	s_nop 0
	global_load_dwordx4 v[72:75], v[72:73], off offset:512
	s_mov_b64 s[98:99], 0x0
	v_lshl_add_u64 v[248:249], v[198:199], 0, s[98:99]
	global_load_dwordx4 v[200:203], v[248:249], off offset:16
	global_load_dwordx4 v[204:207], v[248:249], off
	s_mov_b64 s[98:99], 0x0
	v_lshl_add_u64 v[248:249], v[198:199], 0, s[98:99]
	global_load_dwordx4 v[208:211], v[248:249], off offset:528
	global_load_dwordx4 v[212:215], v[248:249], off offset:512
	s_mov_b64 s[98:99], 0x20000
	v_lshl_add_u64 v[248:249], v[198:199], 0, s[98:99]
	global_load_dwordx4 v[216:219], v[248:249], off offset:16
	global_load_dwordx4 v[220:223], v[248:249], off
	s_mov_b64 s[98:99], 0x20000
	v_lshl_add_u64 v[248:249], v[198:199], 0, s[98:99]
	global_load_dwordx4 v[224:227], v[248:249], off offset:528
	global_load_dwordx4 v[228:231], v[248:249], off offset:512
	s_mov_b64 s[98:99], 0x40000
	v_lshl_add_u64 v[248:249], v[198:199], 0, s[98:99]
	global_load_dwordx4 v[232:235], v[248:249], off offset:16
	global_load_dwordx4 v[236:239], v[248:249], off
	s_mov_b64 s[98:99], 0x40000
	v_lshl_add_u64 v[248:249], v[198:199], 0, s[98:99]
	global_load_dwordx4 v[240:243], v[248:249], off offset:528
	global_load_dwordx4 v[244:247], v[248:249], off offset:512
	s_nop 0
	s_nop 1
	s_waitcnt vmcnt(10)
	v_mov_b32_e32 v190, v200
	v_mov_b32_e32 v191, v201
	v_mov_b32_e32 v192, v202
	v_mov_b32_e32 v193, v203
	s_nop 1
	v_mov_b32_e32 v194, v204
	v_mov_b32_e32 v195, v205
	v_mov_b32_e32 v196, v206
	v_mov_b32_e32 v197, v207
	s_mov_b64 s[98:99], 0x60000
	v_lshl_add_u64 v[248:249], v[198:199], 0, s[98:99]
	global_load_dwordx4 v[200:203], v[248:249], off offset:16
	global_load_dwordx4 v[204:207], v[248:249], off
	s_mov_b64 s[12:13], 0x40000
	s_and_b64 vcc, exec, s[4:5]
	s_mov_b32 s49, s0
	s_mov_b32 s48, s6
	s_mov_b64 s[14:15], s[10:11]
	s_nop 0
	v_pk_fma_f32 v[142:143], v[142:143], v[86:87], v[192:193]
	v_pk_fma_f32 v[146:147], v[146:147], v[90:91], v[196:197]
	v_pk_fma_f32 v[144:145], v[144:145], v[88:89], v[194:195]
	v_pk_fma_f32 v[190:191], v[140:141], v[84:85], v[190:191]
	v_cvt_pk_f16_f32 v143, v142, v143
	v_cvt_pk_f16_f32 v141, v146, v147
	v_cvt_pk_f16_f32 v142, v190, v191
	v_cvt_pk_f16_f32 v140, v144, v145
	v_lshl_add_u64 v[190:191], v[170:171], 1, s[16:17]
	global_store_dwordx4 v[190:191], v[140:143], off
	s_nop 1
	s_waitcnt vmcnt(10)
;     __device__ __forceinline__ void operator()(const f32x4 (&acc)[2][2][4][2], const pg8::Unit& u, int wr, int wc, int fr, int fq) const {
;     ...
;             for (int m = 0; m < 4; ++m) { const size_t ro = (size_t)(row0 + ai * 128 + m * 16) * DM + col0;
; #pragma unroll
;                 for (int bj = 0; bj < 2; ++bj) {
;                     f32x4 x0, x1;
;                     if (XF32) { x0 = *(const f32x4*)(xin + ro + bj * 128); x1 = *(const f32x4*)(xin + ro + bj * 128 + 4); }
;                     else { const h8 xh = *(const h8*)(H + ro + bj * 128); x0 = (f32x4){(float)xh[0], (float)xh[1], (float)xh[2], (float)xh[3]}; x1 = (f32x4){(float)xh[4], (float)xh[5], (float)xh[6], (float)xh[7]}; }
;                     const f32x4 y0 = x0 + gv[bj][0] * acc[ai][bj][m][0], y1 = x1 + gv[bj][1] * acc[ai][bj][m][1];
;                     h8 o; o[0] = (half_t)y0[0]; o[1] = (half_t)y0[1]; o[2] = (half_t)y0[2]; o[3] = (half_t)y0[3]; o[4] = (half_t)y1[0]; o[5] = (half_t)y1[1]; o[6] = (half_t)y1[2]; o[7] = (half_t)y1[3];
;                     *(h8*)(H + ro + bj * 128) = o; } }
	v_mov_b32_e32 v140, v208
	v_mov_b32_e32 v141, v209
	v_mov_b32_e32 v142, v210
	v_mov_b32_e32 v143, v211
	s_nop 0
	s_nop 1
	v_mov_b32_e32 v144, v212
	v_mov_b32_e32 v145, v213
	v_mov_b32_e32 v146, v214
	v_mov_b32_e32 v147, v215
	s_mov_b64 s[98:99], 0x60000
	v_lshl_add_u64 v[248:249], v[198:199], 0, s[98:99]
	global_load_dwordx4 v[208:211], v[248:249], off offset:528
	global_load_dwordx4 v[212:215], v[248:249], off offset:512
	s_nop 0
	v_pk_fma_f32 v[134:135], v[134:135], v[70:71], v[142:143]
	v_pk_fma_f32 v[138:139], v[138:139], v[74:75], v[146:147]
	v_pk_fma_f32 v[136:137], v[136:137], v[72:73], v[144:145]
	v_pk_fma_f32 v[140:141], v[132:133], v[68:69], v[140:141]
	v_cvt_pk_f16_f32 v135, v134, v135
	v_cvt_pk_f16_f32 v133, v138, v139
	v_cvt_pk_f16_f32 v134, v140, v141
	v_cvt_pk_f16_f32 v132, v136, v137
	global_store_dwordx4 v[190:191], v[132:135], off offset:256
	s_nop 1
	v_or_b32_e32 v132, 16, v174
	v_ashrrev_i32_e32 v133, 31, v132
	v_lshlrev_b64 v[132:133], 11, v[132:133]
	v_lshl_add_u64 v[140:141], v[132:133], 0, v[172:173]
	v_lshl_add_u64 v[142:143], v[140:141], 2, s[80:81]
	s_nop 1
	s_waitcnt vmcnt(10)
	v_mov_b32_e32 v132, v216
	v_mov_b32_e32 v133, v217
	v_mov_b32_e32 v134, v218
	v_mov_b32_e32 v135, v219
	s_nop 1
	v_mov_b32_e32 v136, v220
	v_mov_b32_e32 v137, v221
	v_mov_b32_e32 v138, v222
	v_mov_b32_e32 v139, v223
	s_mov_b64 s[98:99], 0x100000
	v_lshl_add_u64 v[248:249], v[198:199], 0, s[98:99]
	global_load_dwordx4 v[216:219], v[248:249], off offset:16
	global_load_dwordx4 v[220:223], v[248:249], off
	s_nop 0
	v_pk_fma_f32 v[126:127], v[126:127], v[86:87], v[134:135]
	v_pk_fma_f32 v[130:131], v[130:131], v[90:91], v[138:139]
	v_pk_fma_f32 v[128:129], v[128:129], v[88:89], v[136:137]
	v_pk_fma_f32 v[132:133], v[124:125], v[84:85], v[132:133]
	v_cvt_pk_f16_f32 v127, v126, v127
	v_cvt_pk_f16_f32 v125, v130, v131
	v_cvt_pk_f16_f32 v126, v132, v133
	v_cvt_pk_f16_f32 v124, v128, v129
	v_lshl_add_u64 v[132:133], v[140:141], 1, s[16:17]
	global_store_dwordx4 v[132:133], v[124:127], off
	s_nop 1
	s_waitcnt vmcnt(10)
	v_mov_b32_e32 v124, v224
	v_mov_b32_e32 v125, v225
	v_mov_b32_e32 v126, v226
	v_mov_b32_e32 v127, v227
	s_nop 0
	s_nop 1
	v_mov_b32_e32 v128, v228
	v_mov_b32_e32 v129, v229
	v_mov_b32_e32 v130, v230
	v_mov_b32_e32 v131, v231
	s_mov_b64 s[98:99], 0x100000
	v_lshl_add_u64 v[248:249], v[198:199], 0, s[98:99]
	global_load_dwordx4 v[224:227], v[248:249], off offset:528
	global_load_dwordx4 v[228:231], v[248:249], off offset:512
	s_nop 0
	v_pk_fma_f32 v[118:119], v[118:119], v[70:71], v[126:127]
	v_pk_fma_f32 v[122:123], v[122:123], v[74:75], v[130:131]
	v_pk_fma_f32 v[120:121], v[120:121], v[72:73], v[128:129]
	v_pk_fma_f32 v[124:125], v[116:117], v[68:69], v[124:125]
	v_cvt_pk_f16_f32 v119, v118, v119
	v_cvt_pk_f16_f32 v117, v122, v123
	v_cvt_pk_f16_f32 v118, v124, v125
	v_cvt_pk_f16_f32 v116, v120, v121
	global_store_dwordx4 v[132:133], v[116:119], off offset:256
	s_nop 1
	v_or_b32_e32 v116, 32, v174
	v_ashrrev_i32_e32 v117, 31, v116
	v_lshlrev_b64 v[116:117], 11, v[116:117]
	v_lshl_add_u64 v[124:125], v[116:117], 0, v[172:173]
	v_lshl_add_u64 v[126:127], v[124:125], 2, s[80:81]
	s_nop 1
	s_waitcnt vmcnt(10)
	v_mov_b32_e32 v116, v232
	v_mov_b32_e32 v117, v233
	v_mov_b32_e32 v118, v234
	v_mov_b32_e32 v119, v235
	s_nop 1
	v_mov_b32_e32 v120, v236
	v_mov_b32_e32 v121, v237
	v_mov_b32_e32 v122, v238
	v_mov_b32_e32 v123, v239
	s_mov_b64 s[98:99], 0x120000
	v_lshl_add_u64 v[248:249], v[198:199], 0, s[98:99]
	global_load_dwordx4 v[232:235], v[248:249], off offset:16
	global_load_dwordx4 v[236:239], v[248:249], off
	s_nop 0
	v_pk_fma_f32 v[110:111], v[110:111], v[86:87], v[118:119]
	v_pk_fma_f32 v[114:115], v[114:115], v[90:91], v[122:123]
	v_pk_fma_f32 v[112:113], v[112:113], v[88:89], v[120:121]
	v_pk_fma_f32 v[116:117], v[108:109], v[84:85], v[116:117]
	v_cvt_pk_f16_f32 v111, v110, v111
	v_cvt_pk_f16_f32 v109, v114, v115
	v_cvt_pk_f16_f32 v110, v116, v117
	v_cvt_pk_f16_f32 v108, v112, v113
	v_lshl_add_u64 v[116:117], v[124:125], 1, s[16:17]
	global_store_dwordx4 v[116:117], v[108:111], off
	s_nop 1
	s_waitcnt vmcnt(10)
	v_mov_b32_e32 v108, v240
	v_mov_b32_e32 v109, v241
	v_mov_b32_e32 v110, v242
	v_mov_b32_e32 v111, v243
	s_nop 0
	s_nop 1
	v_mov_b32_e32 v112, v244
	v_mov_b32_e32 v113, v245
	v_mov_b32_e32 v114, v246
	v_mov_b32_e32 v115, v247
	s_mov_b64 s[98:99], 0x120000
	v_lshl_add_u64 v[248:249], v[198:199], 0, s[98:99]
	global_load_dwordx4 v[240:243], v[248:249], off offset:528
	global_load_dwordx4 v[244:247], v[248:249], off offset:512
	s_nop 0
	v_pk_fma_f32 v[102:103], v[102:103], v[70:71], v[110:111]
	v_pk_fma_f32 v[106:107], v[106:107], v[74:75], v[114:115]
	v_pk_fma_f32 v[104:105], v[104:105], v[72:73], v[112:113]
	v_pk_fma_f32 v[108:109], v[100:101], v[68:69], v[108:109]
	v_cvt_pk_f16_f32 v103, v102, v103
	v_cvt_pk_f16_f32 v101, v106, v107
	v_cvt_pk_f16_f32 v102, v108, v109
	v_cvt_pk_f16_f32 v100, v104, v105
	global_store_dwordx4 v[116:117], v[100:103], off offset:256
	s_nop 1
	v_or_b32_e32 v100, 48, v174
	v_ashrrev_i32_e32 v101, 31, v100
	v_lshlrev_b64 v[100:101], 11, v[100:101]
	v_lshl_add_u64 v[108:109], v[100:101], 0, v[172:173]
	v_lshl_add_u64 v[110:111], v[108:109], 2, s[80:81]
	s_nop 1
	s_waitcnt vmcnt(10)
;     __device__ __forceinline__ void operator()(const f32x4 (&acc)[2][2][4][2], const pg8::Unit& u, int wr, int wc, int fr, int fq) const {
;     ...
;             for (int m = 0; m < 4; ++m) { const size_t ro = (size_t)(row0 + ai * 128 + m * 16) * DM + col0;
; #pragma unroll
;                 for (int bj = 0; bj < 2; ++bj) {
;                     f32x4 x0, x1;
;                     if (XF32) { x0 = *(const f32x4*)(xin + ro + bj * 128); x1 = *(const f32x4*)(xin + ro + bj * 128 + 4); }
;                     else { const h8 xh = *(const h8*)(H + ro + bj * 128); x0 = (f32x4){(float)xh[0], (float)xh[1], (float)xh[2], (float)xh[3]}; x1 = (f32x4){(float)xh[4], (float)xh[5], (float)xh[6], (float)xh[7]}; }
;                     const f32x4 y0 = x0 + gv[bj][0] * acc[ai][bj][m][0], y1 = x1 + gv[bj][1] * acc[ai][bj][m][1];
;                     h8 o; o[0] = (half_t)y0[0]; o[1] = (half_t)y0[1]; o[2] = (half_t)y0[2]; o[3] = (half_t)y0[3]; o[4] = (half_t)y1[0]; o[5] = (half_t)y1[1]; o[6] = (half_t)y1[2]; o[7] = (half_t)y1[3];
;                     *(h8*)(H + ro + bj * 128) = o; } }
	v_mov_b32_e32 v100, v200
	v_mov_b32_e32 v101, v201
	v_mov_b32_e32 v102, v202
	v_mov_b32_e32 v103, v203
	s_nop 1
	v_mov_b32_e32 v104, v204
	v_mov_b32_e32 v105, v205
	v_mov_b32_e32 v106, v206
	v_mov_b32_e32 v107, v207
	s_mov_b64 s[98:99], 0x140000
	v_lshl_add_u64 v[248:249], v[198:199], 0, s[98:99]
	global_load_dwordx4 v[200:203], v[248:249], off offset:16
	global_load_dwordx4 v[204:207], v[248:249], off
	s_nop 0
	v_pk_fma_f32 v[94:95], v[94:95], v[86:87], v[102:103]
	v_pk_fma_f32 v[98:99], v[98:99], v[90:91], v[106:107]
	v_pk_fma_f32 v[96:97], v[96:97], v[88:89], v[104:105]
	v_pk_fma_f32 v[100:101], v[92:93], v[84:85], v[100:101]
	v_cvt_pk_f16_f32 v95, v94, v95
	v_cvt_pk_f16_f32 v93, v98, v99
	v_cvt_pk_f16_f32 v94, v100, v101
	v_cvt_pk_f16_f32 v92, v96, v97
	v_lshl_add_u64 v[100:101], v[108:109], 1, s[16:17]
	global_store_dwordx4 v[100:101], v[92:95], off
	s_nop 1
	s_waitcnt vmcnt(10)
	v_mov_b32_e32 v92, v208
	v_mov_b32_e32 v93, v209
	v_mov_b32_e32 v94, v210
	v_mov_b32_e32 v95, v211
	s_nop 0
	s_nop 1
	v_mov_b32_e32 v96, v212
	v_mov_b32_e32 v97, v213
	v_mov_b32_e32 v98, v214
	v_mov_b32_e32 v99, v215
	s_mov_b64 s[98:99], 0x140000
	v_lshl_add_u64 v[248:249], v[198:199], 0, s[98:99]
	global_load_dwordx4 v[208:211], v[248:249], off offset:528
	global_load_dwordx4 v[212:215], v[248:249], off offset:512
	s_nop 0
	v_pk_fma_f32 v[78:79], v[78:79], v[70:71], v[94:95]
	v_pk_fma_f32 v[82:83], v[82:83], v[74:75], v[98:99]
	v_pk_fma_f32 v[80:81], v[80:81], v[72:73], v[96:97]
	v_pk_fma_f32 v[92:93], v[76:77], v[68:69], v[92:93]
	v_cvt_pk_f16_f32 v79, v78, v79
	v_cvt_pk_f16_f32 v77, v82, v83
	v_cvt_pk_f16_f32 v78, v92, v93
	v_cvt_pk_f16_f32 v76, v80, v81
	v_lshl_add_u64 v[92:93], v[170:171], 0, s[12:13]
	global_store_dwordx4 v[100:101], v[76:79], off offset:256
	v_lshl_add_u64 v[94:95], v[92:93], 2, s[80:81]
	s_nop 1
	s_waitcnt vmcnt(10)
	v_mov_b32_e32 v76, v216
	v_mov_b32_e32 v77, v217
	v_mov_b32_e32 v78, v218
	v_mov_b32_e32 v79, v219
	s_nop 1
	v_mov_b32_e32 v80, v220
	v_mov_b32_e32 v81, v221
	v_mov_b32_e32 v82, v222
	v_mov_b32_e32 v83, v223
	s_mov_b64 s[98:99], 0x160000
	v_lshl_add_u64 v[248:249], v[198:199], 0, s[98:99]
	global_load_dwordx4 v[216:219], v[248:249], off offset:16
	global_load_dwordx4 v[220:223], v[248:249], off
	s_mov_b64 s[12:13], 0x48000
	s_nop 0
	v_pk_fma_f32 v[62:63], v[62:63], v[86:87], v[78:79]
	v_pk_fma_f32 v[66:67], v[66:67], v[90:91], v[82:83]
	v_pk_fma_f32 v[64:65], v[64:65], v[88:89], v[80:81]
	v_pk_fma_f32 v[76:77], v[60:61], v[84:85], v[76:77]
	v_cvt_pk_f16_f32 v63, v62, v63
	v_cvt_pk_f16_f32 v61, v66, v67
	v_cvt_pk_f16_f32 v62, v76, v77
	v_cvt_pk_f16_f32 v60, v64, v65
	v_lshl_add_u64 v[76:77], v[92:93], 1, s[16:17]
	global_store_dwordx4 v[76:77], v[60:63], off
	s_nop 1
	s_waitcnt vmcnt(10)
	v_mov_b32_e32 v60, v224
	v_mov_b32_e32 v61, v225
	v_mov_b32_e32 v62, v226
	v_mov_b32_e32 v63, v227
	s_nop 0
	s_nop 1
	v_mov_b32_e32 v64, v228
	v_mov_b32_e32 v65, v229
	v_mov_b32_e32 v66, v230
	v_mov_b32_e32 v67, v231
	s_mov_b64 s[98:99], 0x160000
	v_lshl_add_u64 v[248:249], v[198:199], 0, s[98:99]
	global_load_dwordx4 v[224:227], v[248:249], off offset:528
	global_load_dwordx4 v[228:231], v[248:249], off offset:512
	s_nop 0
	v_pk_fma_f32 v[54:55], v[54:55], v[70:71], v[62:63]
	v_pk_fma_f32 v[58:59], v[58:59], v[74:75], v[66:67]
	v_pk_fma_f32 v[56:57], v[56:57], v[72:73], v[64:65]
	v_pk_fma_f32 v[60:61], v[52:53], v[68:69], v[60:61]
	v_cvt_pk_f16_f32 v55, v54, v55
	v_cvt_pk_f16_f32 v53, v58, v59
	v_cvt_pk_f16_f32 v54, v60, v61
	v_cvt_pk_f16_f32 v52, v56, v57
	v_lshl_add_u64 v[60:61], v[170:171], 0, s[12:13]
	global_store_dwordx4 v[76:77], v[52:55], off offset:256
	v_lshl_add_u64 v[62:63], v[60:61], 2, s[80:81]
	s_nop 1
	s_waitcnt vmcnt(10)
	v_mov_b32_e32 v52, v232
	v_mov_b32_e32 v53, v233
	v_mov_b32_e32 v54, v234
	v_mov_b32_e32 v55, v235
	s_nop 1
	v_mov_b32_e32 v56, v236
	v_mov_b32_e32 v57, v237
	v_mov_b32_e32 v58, v238
	v_mov_b32_e32 v59, v239
	s_mov_b64 s[12:13], 0x50000
	s_nop 0
	v_pk_fma_f32 v[46:47], v[46:47], v[86:87], v[54:55]
	v_pk_fma_f32 v[50:51], v[50:51], v[90:91], v[58:59]
	v_pk_fma_f32 v[48:49], v[48:49], v[88:89], v[56:57]
	v_pk_fma_f32 v[52:53], v[44:45], v[84:85], v[52:53]
	v_cvt_pk_f16_f32 v47, v46, v47
	v_cvt_pk_f16_f32 v45, v50, v51
	v_cvt_pk_f16_f32 v46, v52, v53
	v_cvt_pk_f16_f32 v44, v48, v49
	v_lshl_add_u64 v[52:53], v[60:61], 1, s[16:17]
	global_store_dwordx4 v[52:53], v[44:47], off
	s_nop 1
	s_waitcnt vmcnt(8)
; #define PG8_WAIT_V(n) asm volatile("s_waitcnt vmcnt(" #n ")" ::: "memory")
; #define PG8_BAR __builtin_amdgcn_s_barrier()
; template <class Epi>
; __device__ __forceinline__ void gemm_phase(LAS unsigned char* lds, const Gemm g, const StaticOrder& S, const Epi& E, const int tid) {
;     ...
;     PG8_WAIT_V(0);
;     if (wr == 0) PG8_BAR;
;     PG8_BAR;
;     __device__ __forceinline__ void operator()(const f32x4 (&acc)[2][2][4][2], const pg8::Unit& u, int wr, int wc, int fr, int fq) const {
;     ...
;             for (int m = 0; m < 4; ++m) { const size_t ro = (size_t)(row0 + ai * 128 + m * 16) * DM + col0;
; #pragma unroll
;                 for (int bj = 0; bj < 2; ++bj) {
;                     f32x4 x0, x1;
;                     if (XF32) { x0 = *(const f32x4*)(xin + ro + bj * 128); x1 = *(const f32x4*)(xin + ro + bj * 128 + 4); }
;                     else { const h8 xh = *(const h8*)(H + ro + bj * 128); x0 = (f32x4){(float)xh[0], (float)xh[1], (float)xh[2], (float)xh[3]}; x1 = (f32x4){(float)xh[4], (float)xh[5], (float)xh[6], (float)xh[7]}; }
;                     const f32x4 y0 = x0 + gv[bj][0] * acc[ai][bj][m][0], y1 = x1 + gv[bj][1] * acc[ai][bj][m][1];
;                     h8 o; o[0] = (half_t)y0[0]; o[1] = (half_t)y0[1]; o[2] = (half_t)y0[2]; o[3] = (half_t)y0[3]; o[4] = (half_t)y1[0]; o[5] = (half_t)y1[1]; o[6] = (half_t)y1[2]; o[7] = (half_t)y1[3];
;                     *(h8*)(H + ro + bj * 128) = o; } }
	v_mov_b32_e32 v44, v240
	v_mov_b32_e32 v45, v241
	v_mov_b32_e32 v46, v242
	v_mov_b32_e32 v47, v243
	s_nop 0
	s_nop 1
	v_mov_b32_e32 v48, v244
	v_mov_b32_e32 v49, v245
	v_mov_b32_e32 v50, v246
	v_mov_b32_e32 v51, v247
	s_nop 0
	v_pk_fma_f32 v[38:39], v[38:39], v[70:71], v[46:47]
	v_pk_fma_f32 v[42:43], v[42:43], v[74:75], v[50:51]
	v_pk_fma_f32 v[40:41], v[40:41], v[72:73], v[48:49]
	v_pk_fma_f32 v[44:45], v[36:37], v[68:69], v[44:45]
	v_cvt_pk_f16_f32 v39, v38, v39
	v_cvt_pk_f16_f32 v37, v42, v43
	v_cvt_pk_f16_f32 v38, v44, v45
	v_cvt_pk_f16_f32 v36, v40, v41
	v_lshl_add_u64 v[44:45], v[170:171], 0, s[12:13]
	global_store_dwordx4 v[52:53], v[36:39], off offset:256
	v_lshl_add_u64 v[46:47], v[44:45], 2, s[80:81]
	s_nop 1
	s_waitcnt vmcnt(6)
	v_mov_b32_e32 v36, v200
	v_mov_b32_e32 v37, v201
	v_mov_b32_e32 v38, v202
	v_mov_b32_e32 v39, v203
	s_nop 1
	v_mov_b32_e32 v40, v204
	v_mov_b32_e32 v41, v205
	v_mov_b32_e32 v42, v206
	v_mov_b32_e32 v43, v207
	s_mov_b64 s[12:13], 0x58000
	s_nop 0
	v_pk_fma_f32 v[30:31], v[30:31], v[86:87], v[38:39]
	v_pk_fma_f32 v[34:35], v[34:35], v[90:91], v[42:43]
	v_pk_fma_f32 v[32:33], v[32:33], v[88:89], v[40:41]
	v_pk_fma_f32 v[36:37], v[28:29], v[84:85], v[36:37]
	v_cvt_pk_f16_f32 v31, v30, v31
	v_cvt_pk_f16_f32 v29, v34, v35
	v_cvt_pk_f16_f32 v30, v36, v37
	v_cvt_pk_f16_f32 v28, v32, v33
	v_lshl_add_u64 v[36:37], v[44:45], 1, s[16:17]
	global_store_dwordx4 v[36:37], v[28:31], off
	s_nop 1
	s_waitcnt vmcnt(4)
	v_mov_b32_e32 v28, v208
	v_mov_b32_e32 v29, v209
	v_mov_b32_e32 v30, v210
	v_mov_b32_e32 v31, v211
	s_nop 0
	s_nop 1
	v_mov_b32_e32 v32, v212
	v_mov_b32_e32 v33, v213
	v_mov_b32_e32 v34, v214
	v_mov_b32_e32 v35, v215
	s_nop 0
	v_pk_fma_f32 v[22:23], v[22:23], v[70:71], v[30:31]
	v_pk_fma_f32 v[26:27], v[26:27], v[74:75], v[34:35]
	v_pk_fma_f32 v[24:25], v[24:25], v[72:73], v[32:33]
	v_pk_fma_f32 v[28:29], v[20:21], v[68:69], v[28:29]
	v_cvt_pk_f16_f32 v23, v22, v23
	v_cvt_pk_f16_f32 v21, v26, v27
	v_cvt_pk_f16_f32 v22, v28, v29
	v_cvt_pk_f16_f32 v20, v24, v25
	v_lshl_add_u64 v[28:29], v[170:171], 0, s[12:13]
	global_store_dwordx4 v[36:37], v[20:23], off offset:256
	v_lshl_add_u64 v[30:31], v[28:29], 2, s[80:81]
	s_nop 1
	s_waitcnt vmcnt(2)
	v_mov_b32_e32 v20, v216
	v_mov_b32_e32 v21, v217
	v_mov_b32_e32 v22, v218
	v_mov_b32_e32 v23, v219
	s_nop 1
	v_mov_b32_e32 v24, v220
	v_mov_b32_e32 v25, v221
	v_mov_b32_e32 v26, v222
	v_mov_b32_e32 v27, v223
	s_mov_b64 s[12:13], s[8:9]
	s_nop 0
	v_pk_fma_f32 v[14:15], v[14:15], v[86:87], v[22:23]
	v_pk_fma_f32 v[18:19], v[18:19], v[90:91], v[26:27]
	v_pk_fma_f32 v[16:17], v[16:17], v[88:89], v[24:25]
	v_pk_fma_f32 v[20:21], v[12:13], v[84:85], v[20:21]
	v_cvt_pk_f16_f32 v15, v14, v15
	v_cvt_pk_f16_f32 v13, v18, v19
	v_cvt_pk_f16_f32 v14, v20, v21
	v_cvt_pk_f16_f32 v12, v16, v17
	v_lshl_add_u64 v[20:21], v[28:29], 1, s[16:17]
	global_store_dwordx4 v[20:21], v[12:15], off
	s_nop 1
	s_waitcnt vmcnt(0)
	v_mov_b32_e32 v12, v224
	v_mov_b32_e32 v13, v225
	v_mov_b32_e32 v14, v226
	v_mov_b32_e32 v15, v227
	s_nop 0
	s_nop 1
	v_mov_b32_e32 v16, v228
	v_mov_b32_e32 v17, v229
	v_mov_b32_e32 v18, v230
	v_mov_b32_e32 v19, v231
	s_nop 0
	v_pk_fma_f32 v[6:7], v[6:7], v[70:71], v[14:15]
	v_pk_fma_f32 v[10:11], v[10:11], v[74:75], v[18:19]
	v_pk_fma_f32 v[8:9], v[8:9], v[72:73], v[16:17]
	v_pk_fma_f32 v[12:13], v[4:5], v[68:69], v[12:13]
	v_cvt_pk_f16_f32 v7, v6, v7
	v_cvt_pk_f16_f32 v5, v10, v11
	v_cvt_pk_f16_f32 v6, v12, v13
	v_cvt_pk_f16_f32 v4, v8, v9
	global_store_dwordx4 v[20:21], v[4:7], off offset:256
	s_cbranch_vccz .LBB0_671
	s_waitcnt vmcnt(0)
	v_readlane_b32 s42, v251, 7
	v_readlane_b32 s46, v251, 9
	v_readlane_b32 s48, v251, 13
	s_cmpk_gt_u32 s25, 0xff
	v_readlane_b32 s43, v251, 8
	v_readlane_b32 s47, v251, 10
	v_readlane_b32 s49, v251, 14
	s_cbranch_scc1 .LBB0_682
	s_barrier
